# P2: hand-written 4-slot-ring tile loops (PV of tile k-1 overlapped with scores of tile k) for differential items and retention pair, one shared differential implementation, rebalanced tile assignment;
# speedup vs baseline: 1.0308x; 1.0171x over previous
; #define PG8_STAGE(bufoff, gbase, voff) do { unsigned long long _gb = (unsigned long long)(gbase); asm volatile("" : "+s"(_gb)); _Pragma("unroll") for (int _i = 0; _i < 2; ++_i) \
;         __builtin_amdgcn_global_load_lds((const GAS unsigned*)((const GAS char*)_gb + (voff)[_i]), (LAS unsigned*)(lds + (bufoff) + ldsw + _i * 8192), 16, 0, 0); } while (0)
; #define PG8_LDA(dst, b, h) do { _Pragma("unroll") for (int m = 0; m < 4; ++m) _Pragma("unroll") for (int k = 0; k < 2; ++k) dst[m][k] = *(const LAS bf16x8*)(lds + PG8_SA(b, h) + aoff + m * 2048 + k * 1024); } while (0)
; #define PG8_LDB(dst, b, h) do { _Pragma("unroll") for (int n = 0; n < 2; ++n) _Pragma("unroll") for (int k = 0; k < 2; ++k) dst[n][k] = *(const LAS bf16x8*)(lds + PG8_SB(b, h) + boff + n * 2048 + k * 1024); } while (0)
; #define PG8_MMA(ai, bj, At, Bt) do { __builtin_amdgcn_s_setprio(1); _Pragma("unroll") for (int m = 0; m < 4; ++m) _Pragma("unroll") for (int n = 0; n < 2; ++n) _Pragma("unroll") for (int k = 0; k < 2; ++k) \
;         acc[ai][bj][m][n] = __builtin_amdgcn_mfma_f32_16x16x32_bf16(Bt[n][k], At[m][k], acc[ai][bj][m][n], 0, 0, 0); __builtin_amdgcn_s_setprio(0); } while (0)
; template <class Epi, bool ALIGN_EPI>
; __device__ __forceinline__ void gemm_phase(LAS unsigned char* lds, const Gemm g, const StaticOrder& S, const Epi& E, const int wid) {
;     ...
;             PG8_LDB(B0, 0, 0); PG8_LDB(B1, 0, 1); PG8_SCHED; PG8_LDA(At, 0, 0); PG8_STAGE(PG8_SA(1, 1), a1 + hstep, voffA);
;             PG8_WAIT_V(8); PG8_WAIT_L(0); PG8_BAR; PG8_MMA(0, 0, At, B0); PG8_MMA(0, 1, At, B1); PG8_BAR; PG8_SCHED;
;             PG8_LDA(At, 0, 1); PG8_STAGE(PG8_SB(0, 0), b2, voffB); PG8_STAGE(PG8_SB(0, 1), b2 + hstepB, voffB); PG8_STAGE(PG8_SA(0, 0), a2, voffA);
;             PG8_WAIT_V(8); PG8_WAIT_L(0); PG8_BAR; PG8_MMA(1, 0, At, B0); PG8_MMA(1, 1, At, B1); PG8_BAR; PG8_SCHED;
;             PG8_LDB(B0, 1, 0); PG8_LDB(B1, 1, 1); PG8_SCHED; PG8_LDA(At, 1, 0); PG8_STAGE(PG8_SA(0, 1), a2 + hstep, voffA);
;             PG8_WAIT_V(8); PG8_WAIT_L(0); PG8_BAR; PG8_MMA(0, 0, At, B0); PG8_MMA(0, 1, At, B1); PG8_BAR; PG8_SCHED;
;             PG8_LDA(At, 1, 1); PG8_STAGE(PG8_SB(1, 0), b3, voffB); PG8_STAGE(PG8_SB(1, 1), b3 + hstepB, voffB); PG8_STAGE(PG8_SA(1, 0), a3, voffA);
;             PG8_WAIT_V(8); PG8_WAIT_L(0); PG8_BAR; PG8_MMA(1, 0, At, B0); PG8_MMA(1, 1, At, B1); PG8_BAR; PG8_SCHED;
.LBB0_105:
	ds_read_b128 v[128:131], v204
	ds_read_b128 v[132:135], v204 offset:1024
	ds_read_b128 v[136:139], v204 offset:2048
	ds_read_b128 v[140:143], v204 offset:3072
	ds_read_b128 v[162:165], v205
	ds_read_b128 v[166:169], v205 offset:1024
	ds_read_b128 v[170:173], v205 offset:2048
	ds_read_b128 v[174:177], v205 offset:3072
	s_add_u32 s6, s2, 0x100
	s_addc_u32 s7, s3, 0
	s_cmp_eq_u32 s74, 28
	s_cselect_b32 s52, s70, s6
	s_cselect_b32 s53, s39, s7
	s_cselect_b32 s50, s71, s72
	s_cselect_b32 s51, s37, s73
	s_add_u32 s48, s52, 0x80
	s_addc_u32 s49, s53, 0
	s_add_u32 s2, s2, 0x80080
	s_addc_u32 s3, s3, 0
	ds_read_b128 v[178:181], v206
	ds_read_b128 v[186:189], v206 offset:1024
	ds_read_b128 v[190:193], v206 offset:2048
	ds_read_b128 v[194:197], v206 offset:3072
	ds_read_b128 v[198:201], v206 offset:4096
	ds_read_b128 v[210:213], v206 offset:5120
	ds_read_b128 v[214:217], v206 offset:6144
	ds_read_b128 v[218:221], v206 offset:7168
	s_add_i32 m0, s45, 0xc000
	v_lshl_add_u64 v[182:183], s[2:3], 0, v[144:145]
	global_load_lds_dwordx4 v[182:183], off
	v_lshl_add_u64 v[182:183], s[2:3], 0, v[148:149]
	s_add_i32 m0, s45, 0xe000
	s_nop 0
	global_load_lds_dwordx4 v[182:183], off
	s_waitcnt vmcnt(8)
	s_waitcnt lgkmcnt(0)
	s_barrier
	s_setprio 1
	v_mfma_f32_16x16x32_bf16 v[124:127], v[128:131], v[178:181], v[124:127]
	v_mfma_f32_16x16x32_bf16 v[120:123], v[136:139], v[178:181], v[120:123]
	v_mfma_f32_16x16x32_bf16 v[108:111], v[128:131], v[190:193], v[108:111]
	v_mfma_f32_16x16x32_bf16 v[104:107], v[136:139], v[190:193], v[104:107]
	v_mfma_f32_16x16x32_bf16 v[92:95], v[128:131], v[198:201], v[92:95]
	v_mfma_f32_16x16x32_bf16 v[88:91], v[136:139], v[198:201], v[88:91]
	v_mfma_f32_16x16x32_bf16 v[76:79], v[128:131], v[214:217], v[76:79]
	v_mfma_f32_16x16x32_bf16 v[72:75], v[136:139], v[214:217], v[72:75]
	v_mfma_f32_16x16x32_bf16 v[124:127], v[132:135], v[186:189], v[124:127]
	v_mfma_f32_16x16x32_bf16 v[120:123], v[140:143], v[186:189], v[120:123]
	v_mfma_f32_16x16x32_bf16 v[108:111], v[132:135], v[194:197], v[108:111]
	v_mfma_f32_16x16x32_bf16 v[104:107], v[140:143], v[194:197], v[104:107]
	v_mfma_f32_16x16x32_bf16 v[92:95], v[132:135], v[210:213], v[92:95]
	v_mfma_f32_16x16x32_bf16 v[88:91], v[140:143], v[210:213], v[88:91]
	v_mfma_f32_16x16x32_bf16 v[76:79], v[132:135], v[218:221], v[76:79]
	v_mfma_f32_16x16x32_bf16 v[72:75], v[140:143], v[218:221], v[72:75]
	v_mfma_f32_16x16x32_bf16 v[116:119], v[162:165], v[178:181], v[116:119]
	v_mfma_f32_16x16x32_bf16 v[112:115], v[170:173], v[178:181], v[112:115]
	v_mfma_f32_16x16x32_bf16 v[100:103], v[162:165], v[190:193], v[100:103]
	v_mfma_f32_16x16x32_bf16 v[96:99], v[170:173], v[190:193], v[96:99]
	v_mfma_f32_16x16x32_bf16 v[84:87], v[162:165], v[198:201], v[84:87]
	v_mfma_f32_16x16x32_bf16 v[80:83], v[170:173], v[198:201], v[80:83]
	v_mfma_f32_16x16x32_bf16 v[68:71], v[162:165], v[214:217], v[68:71]
	v_mfma_f32_16x16x32_bf16 v[64:67], v[170:173], v[214:217], v[64:67]
	v_mfma_f32_16x16x32_bf16 v[116:119], v[166:169], v[186:189], v[116:119]
	v_mfma_f32_16x16x32_bf16 v[112:115], v[174:177], v[186:189], v[112:115]
	v_mfma_f32_16x16x32_bf16 v[100:103], v[166:169], v[194:197], v[100:103]
	v_mfma_f32_16x16x32_bf16 v[96:99], v[174:177], v[194:197], v[96:99]
	v_mfma_f32_16x16x32_bf16 v[84:87], v[166:169], v[210:213], v[84:87]
	v_mfma_f32_16x16x32_bf16 v[80:83], v[174:177], v[210:213], v[80:83]
	v_mfma_f32_16x16x32_bf16 v[68:71], v[166:169], v[218:221], v[68:71]
	v_mfma_f32_16x16x32_bf16 v[64:67], v[174:177], v[218:221], v[64:67]
	s_setprio 0
	s_barrier
	s_mov_b64 s[2:3], s[50:51]
	s_add_i32 s75, s66, s33
	ds_read_b128 v[178:181], v206 offset:16384
	ds_read_b128 v[186:189], v206 offset:17408
	ds_read_b128 v[190:193], v206 offset:18432
	ds_read_b128 v[194:197], v206 offset:19456
	ds_read_b128 v[198:201], v206 offset:20480
	ds_read_b128 v[210:213], v206 offset:21504
	ds_read_b128 v[214:217], v206 offset:22528
	ds_read_b128 v[218:221], v206 offset:23552
	s_mov_b32 m0, s75
	v_lshl_add_u64 v[182:183], s[2:3], 0, v[146:147]
	global_load_lds_dwordx4 v[182:183], off
	s_add_i32 m0, s75, 0x2000
	v_lshl_add_u64 v[182:183], s[2:3], 0, v[150:151]
	s_add_u32 s2, s50, 0x20000
	s_addc_u32 s3, s51, 0
	s_add_i32 s75, s67, s33
	global_load_lds_dwordx4 v[182:183], off
	s_mov_b32 m0, s75
	v_lshl_add_u64 v[182:183], s[2:3], 0, v[146:147]
	global_load_lds_dwordx4 v[182:183], off
	v_lshl_add_u64 v[182:183], s[2:3], 0, v[150:151]
	s_add_i32 m0, s75, 0x2000
	s_mov_b64 s[2:3], s[52:53]
	global_load_lds_dwordx4 v[182:183], off
	s_mov_b32 m0, s45
	v_lshl_add_u64 v[182:183], s[2:3], 0, v[144:145]
	global_load_lds_dwordx4 v[182:183], off
	v_lshl_add_u64 v[182:183], s[2:3], 0, v[148:149]
	s_mov_b32 m0, s47
	s_nop 0
	global_load_lds_dwordx4 v[182:183], off
	s_waitcnt vmcnt(8)
	s_waitcnt lgkmcnt(0)
	s_barrier
; #define PG8_STAGE(bufoff, gbase, voff) do { unsigned long long _gb = (unsigned long long)(gbase); asm volatile("" : "+s"(_gb)); _Pragma("unroll") for (int _i = 0; _i < 2; ++_i) \
;         __builtin_amdgcn_global_load_lds((const GAS unsigned*)((const GAS char*)_gb + (voff)[_i]), (LAS unsigned*)(lds + (bufoff) + ldsw + _i * 8192), 16, 0, 0); } while (0)
; #define PG8_LDA(dst, b, h) do { _Pragma("unroll") for (int m = 0; m < 4; ++m) _Pragma("unroll") for (int k = 0; k < 2; ++k) dst[m][k] = *(const LAS bf16x8*)(lds + PG8_SA(b, h) + aoff + m * 2048 + k * 1024); } while (0)
; #define PG8_LDB(dst, b, h) do { _Pragma("unroll") for (int n = 0; n < 2; ++n) _Pragma("unroll") for (int k = 0; k < 2; ++k) dst[n][k] = *(const LAS bf16x8*)(lds + PG8_SB(b, h) + boff + n * 2048 + k * 1024); } while (0)
; #define PG8_MMA(ai, bj, At, Bt) do { __builtin_amdgcn_s_setprio(1); _Pragma("unroll") for (int m = 0; m < 4; ++m) _Pragma("unroll") for (int n = 0; n < 2; ++n) _Pragma("unroll") for (int k = 0; k < 2; ++k) \
;         acc[ai][bj][m][n] = __builtin_amdgcn_mfma_f32_16x16x32_bf16(Bt[n][k], At[m][k], acc[ai][bj][m][n], 0, 0, 0); __builtin_amdgcn_s_setprio(0); } while (0)
; template <class Epi, bool ALIGN_EPI>
; __device__ __forceinline__ void gemm_phase(LAS unsigned char* lds, const Gemm g, const StaticOrder& S, const Epi& E, const int wid) {
;     ...
;             PG8_LDB(B0, 0, 0); PG8_LDB(B1, 0, 1); PG8_SCHED; PG8_LDA(At, 0, 0); PG8_STAGE(PG8_SA(1, 1), a1 + hstep, voffA);
;             PG8_WAIT_V(8); PG8_WAIT_L(0); PG8_BAR; PG8_MMA(0, 0, At, B0); PG8_MMA(0, 1, At, B1); PG8_BAR; PG8_SCHED;
;             PG8_LDA(At, 0, 1); PG8_STAGE(PG8_SB(0, 0), b2, voffB); PG8_STAGE(PG8_SB(0, 1), b2 + hstepB, voffB); PG8_STAGE(PG8_SA(0, 0), a2, voffA);
;             PG8_WAIT_V(8); PG8_WAIT_L(0); PG8_BAR; PG8_MMA(1, 0, At, B0); PG8_MMA(1, 1, At, B1); PG8_BAR; PG8_SCHED;
;             PG8_LDB(B0, 1, 0); PG8_LDB(B1, 1, 1); PG8_SCHED; PG8_LDA(At, 1, 0); PG8_STAGE(PG8_SA(0, 1), a2 + hstep, voffA);
;             PG8_WAIT_V(8); PG8_WAIT_L(0); PG8_BAR; PG8_MMA(0, 0, At, B0); PG8_MMA(0, 1, At, B1); PG8_BAR; PG8_SCHED;
;             PG8_LDA(At, 1, 1); PG8_STAGE(PG8_SB(1, 0), b3, voffB); PG8_STAGE(PG8_SB(1, 1), b3 + hstepB, voffB); PG8_STAGE(PG8_SA(1, 0), a3, voffA);
;             PG8_WAIT_V(8); PG8_WAIT_L(0); PG8_BAR; PG8_MMA(1, 0, At, B0); PG8_MMA(1, 1, At, B1); PG8_BAR; PG8_SCHED;
	s_setprio 1
	v_mfma_f32_16x16x32_bf16 v[60:63], v[128:131], v[178:181], v[60:63]
	v_mfma_f32_16x16x32_bf16 v[56:59], v[136:139], v[178:181], v[56:59]
	v_mfma_f32_16x16x32_bf16 v[44:47], v[128:131], v[190:193], v[44:47]
	v_mfma_f32_16x16x32_bf16 v[40:43], v[136:139], v[190:193], v[40:43]
	v_mfma_f32_16x16x32_bf16 v[28:31], v[128:131], v[198:201], v[28:31]
	v_mfma_f32_16x16x32_bf16 v[24:27], v[136:139], v[198:201], v[24:27]
	v_mfma_f32_16x16x32_bf16 v[12:15], v[128:131], v[214:217], v[12:15]
	v_mfma_f32_16x16x32_bf16 v[8:11], v[136:139], v[214:217], v[8:11]
	v_mfma_f32_16x16x32_bf16 v[60:63], v[132:135], v[186:189], v[60:63]
	v_mfma_f32_16x16x32_bf16 v[56:59], v[140:143], v[186:189], v[56:59]
	v_mfma_f32_16x16x32_bf16 v[44:47], v[132:135], v[194:197], v[44:47]
	v_mfma_f32_16x16x32_bf16 v[40:43], v[140:143], v[194:197], v[40:43]
	v_mfma_f32_16x16x32_bf16 v[28:31], v[132:135], v[210:213], v[28:31]
	v_mfma_f32_16x16x32_bf16 v[24:27], v[140:143], v[210:213], v[24:27]
	v_mfma_f32_16x16x32_bf16 v[12:15], v[132:135], v[218:221], v[12:15]
	v_mfma_f32_16x16x32_bf16 v[8:11], v[140:143], v[218:221], v[8:11]
	v_mfma_f32_16x16x32_bf16 v[52:55], v[162:165], v[178:181], v[52:55]
	v_mfma_f32_16x16x32_bf16 v[48:51], v[170:173], v[178:181], v[48:51]
	v_mfma_f32_16x16x32_bf16 v[36:39], v[162:165], v[190:193], v[36:39]
	v_mfma_f32_16x16x32_bf16 v[32:35], v[170:173], v[190:193], v[32:35]
	v_mfma_f32_16x16x32_bf16 v[20:23], v[162:165], v[198:201], v[20:23]
	v_mfma_f32_16x16x32_bf16 v[16:19], v[170:173], v[198:201], v[16:19]
	v_mfma_f32_16x16x32_bf16 v[4:7], v[162:165], v[214:217], v[4:7]
	v_mfma_f32_16x16x32_bf16 v[0:3], v[170:173], v[214:217], v[0:3]
	v_mfma_f32_16x16x32_bf16 v[52:55], v[166:169], v[186:189], v[52:55]
	v_mfma_f32_16x16x32_bf16 v[48:51], v[174:177], v[186:189], v[48:51]
	v_mfma_f32_16x16x32_bf16 v[36:39], v[166:169], v[194:197], v[36:39]
	v_mfma_f32_16x16x32_bf16 v[32:35], v[174:177], v[194:197], v[32:35]
	v_mfma_f32_16x16x32_bf16 v[20:23], v[166:169], v[210:213], v[20:23]
	v_mfma_f32_16x16x32_bf16 v[16:19], v[174:177], v[210:213], v[16:19]
	v_mfma_f32_16x16x32_bf16 v[4:7], v[166:169], v[218:221], v[4:7]
	v_mfma_f32_16x16x32_bf16 v[0:3], v[174:177], v[218:221], v[0:3]
	s_setprio 0
	s_barrier
	s_add_i32 s75, 0, 0x18000
	s_add_i32 s76, 0, 0x1c000
	v_add_u32_e32 v140, s75, v203
	v_add_u32_e32 v152, s76, v203
	ds_read_b128 v[128:131], v140
	ds_read_b128 v[132:135], v140 offset:1024
	ds_read_b128 v[136:139], v140 offset:2048
	ds_read_b128 v[140:143], v140 offset:3072
	ds_read_b128 v[162:165], v152
	ds_read_b128 v[166:169], v152 offset:1024
	ds_read_b128 v[170:173], v152 offset:2048
	ds_read_b128 v[174:177], v152 offset:3072
	s_add_u32 s2, s52, 0x80000
	s_addc_u32 s3, s53, 0
	s_mov_b32 m0, s57
	ds_read_b128 v[178:181], v206 offset:32768
	ds_read_b128 v[186:189], v206 offset:33792
	ds_read_b128 v[190:193], v206 offset:34816
	ds_read_b128 v[194:197], v206 offset:35840
	ds_read_b128 v[198:201], v206 offset:36864
	ds_read_b128 v[210:213], v206 offset:37888
	ds_read_b128 v[214:217], v206 offset:38912
	ds_read_b128 v[218:221], v206 offset:39936
	s_nop 0
	v_lshl_add_u64 v[182:183], s[2:3], 0, v[144:145]
	global_load_lds_dwordx4 v[182:183], off
	v_lshl_add_u64 v[182:183], s[2:3], 0, v[148:149]
	s_mov_b32 m0, s58
	s_nop 0
	global_load_lds_dwordx4 v[182:183], off
	s_waitcnt vmcnt(8)
	s_waitcnt lgkmcnt(0)
	s_barrier
	s_setprio 1
	v_mfma_f32_16x16x32_bf16 v[124:127], v[128:131], v[178:181], v[124:127]
	v_mfma_f32_16x16x32_bf16 v[120:123], v[136:139], v[178:181], v[120:123]
	v_mfma_f32_16x16x32_bf16 v[108:111], v[128:131], v[190:193], v[108:111]
	v_mfma_f32_16x16x32_bf16 v[104:107], v[136:139], v[190:193], v[104:107]
	v_mfma_f32_16x16x32_bf16 v[92:95], v[128:131], v[198:201], v[92:95]
	v_mfma_f32_16x16x32_bf16 v[88:91], v[136:139], v[198:201], v[88:91]
	v_mfma_f32_16x16x32_bf16 v[76:79], v[128:131], v[214:217], v[76:79]
	v_mfma_f32_16x16x32_bf16 v[72:75], v[136:139], v[214:217], v[72:75]
	v_mfma_f32_16x16x32_bf16 v[124:127], v[132:135], v[186:189], v[124:127]
	v_mfma_f32_16x16x32_bf16 v[120:123], v[140:143], v[186:189], v[120:123]
	v_mfma_f32_16x16x32_bf16 v[108:111], v[132:135], v[194:197], v[108:111]
	v_mfma_f32_16x16x32_bf16 v[104:107], v[140:143], v[194:197], v[104:107]
	v_mfma_f32_16x16x32_bf16 v[92:95], v[132:135], v[210:213], v[92:95]
	v_mfma_f32_16x16x32_bf16 v[88:91], v[140:143], v[210:213], v[88:91]
	v_mfma_f32_16x16x32_bf16 v[76:79], v[132:135], v[218:221], v[76:79]
	v_mfma_f32_16x16x32_bf16 v[72:75], v[140:143], v[218:221], v[72:75]
	v_mfma_f32_16x16x32_bf16 v[116:119], v[162:165], v[178:181], v[116:119]
	v_mfma_f32_16x16x32_bf16 v[112:115], v[170:173], v[178:181], v[112:115]
	v_mfma_f32_16x16x32_bf16 v[100:103], v[162:165], v[190:193], v[100:103]
	v_mfma_f32_16x16x32_bf16 v[96:99], v[170:173], v[190:193], v[96:99]
	v_mfma_f32_16x16x32_bf16 v[84:87], v[162:165], v[198:201], v[84:87]
	v_mfma_f32_16x16x32_bf16 v[80:83], v[170:173], v[198:201], v[80:83]
	v_mfma_f32_16x16x32_bf16 v[68:71], v[162:165], v[214:217], v[68:71]
	v_mfma_f32_16x16x32_bf16 v[64:67], v[170:173], v[214:217], v[64:67]
	v_mfma_f32_16x16x32_bf16 v[116:119], v[166:169], v[186:189], v[116:119]
	v_mfma_f32_16x16x32_bf16 v[112:115], v[174:177], v[186:189], v[112:115]
	v_mfma_f32_16x16x32_bf16 v[100:103], v[166:169], v[194:197], v[100:103]
	v_mfma_f32_16x16x32_bf16 v[96:99], v[174:177], v[194:197], v[96:99]
	v_mfma_f32_16x16x32_bf16 v[84:87], v[166:169], v[210:213], v[84:87]
	v_mfma_f32_16x16x32_bf16 v[80:83], v[174:177], v[210:213], v[80:83]
	v_mfma_f32_16x16x32_bf16 v[68:71], v[166:169], v[218:221], v[68:71]
	v_mfma_f32_16x16x32_bf16 v[64:67], v[174:177], v[218:221], v[64:67]
	s_setprio 0
	s_barrier
; #define PG8_STAGE(bufoff, gbase, voff) do { unsigned long long _gb = (unsigned long long)(gbase); asm volatile("" : "+s"(_gb)); _Pragma("unroll") for (int _i = 0; _i < 2; ++_i) \
;         __builtin_amdgcn_global_load_lds((const GAS unsigned*)((const GAS char*)_gb + (voff)[_i]), (LAS unsigned*)(lds + (bufoff) + ldsw + _i * 8192), 16, 0, 0); } while (0)
; #define PG8_LDA(dst, b, h) do { _Pragma("unroll") for (int m = 0; m < 4; ++m) _Pragma("unroll") for (int k = 0; k < 2; ++k) dst[m][k] = *(const LAS bf16x8*)(lds + PG8_SA(b, h) + aoff + m * 2048 + k * 1024); } while (0)
; #define PG8_LDB(dst, b, h) do { _Pragma("unroll") for (int n = 0; n < 2; ++n) _Pragma("unroll") for (int k = 0; k < 2; ++k) dst[n][k] = *(const LAS bf16x8*)(lds + PG8_SB(b, h) + boff + n * 2048 + k * 1024); } while (0)
; #define PG8_MMA(ai, bj, At, Bt) do { __builtin_amdgcn_s_setprio(1); _Pragma("unroll") for (int m = 0; m < 4; ++m) _Pragma("unroll") for (int n = 0; n < 2; ++n) _Pragma("unroll") for (int k = 0; k < 2; ++k) \
;         acc[ai][bj][m][n] = __builtin_amdgcn_mfma_f32_16x16x32_bf16(Bt[n][k], At[m][k], acc[ai][bj][m][n], 0, 0, 0); __builtin_amdgcn_s_setprio(0); } while (0)
; template <class Epi, bool ALIGN_EPI>
; __device__ __forceinline__ void gemm_phase(LAS unsigned char* lds, const Gemm g, const StaticOrder& S, const Epi& E, const int wid) {
;     ...
;             PG8_LDB(B0, 0, 0); PG8_LDB(B1, 0, 1); PG8_SCHED; PG8_LDA(At, 0, 0); PG8_STAGE(PG8_SA(1, 1), a1 + hstep, voffA);
;             PG8_WAIT_V(8); PG8_WAIT_L(0); PG8_BAR; PG8_MMA(0, 0, At, B0); PG8_MMA(0, 1, At, B1); PG8_BAR; PG8_SCHED;
;             PG8_LDA(At, 0, 1); PG8_STAGE(PG8_SB(0, 0), b2, voffB); PG8_STAGE(PG8_SB(0, 1), b2 + hstepB, voffB); PG8_STAGE(PG8_SA(0, 0), a2, voffA);
;             PG8_WAIT_V(8); PG8_WAIT_L(0); PG8_BAR; PG8_MMA(1, 0, At, B0); PG8_MMA(1, 1, At, B1); PG8_BAR; PG8_SCHED;
;             PG8_LDB(B0, 1, 0); PG8_LDB(B1, 1, 1); PG8_SCHED; PG8_LDA(At, 1, 0); PG8_STAGE(PG8_SA(0, 1), a2 + hstep, voffA);
;             PG8_WAIT_V(8); PG8_WAIT_L(0); PG8_BAR; PG8_MMA(0, 0, At, B0); PG8_MMA(0, 1, At, B1); PG8_BAR; PG8_SCHED;
;             PG8_LDA(At, 1, 1); PG8_STAGE(PG8_SB(1, 0), b3, voffB); PG8_STAGE(PG8_SB(1, 1), b3 + hstepB, voffB); PG8_STAGE(PG8_SA(1, 0), a3, voffA);
;             PG8_WAIT_V(8); PG8_WAIT_L(0); PG8_BAR; PG8_MMA(1, 0, At, B0); PG8_MMA(1, 1, At, B1); PG8_BAR; PG8_SCHED;
	s_add_u32 s2, s50, 0x80
	s_addc_u32 s3, s51, 0
	s_add_i32 s52, s75, s33
	ds_read_b128 v[178:181], v206 offset:49152
	ds_read_b128 v[186:189], v206 offset:50176
	ds_read_b128 v[190:193], v206 offset:51200
	ds_read_b128 v[194:197], v206 offset:52224
	ds_read_b128 v[198:201], v206 offset:53248
	ds_read_b128 v[210:213], v206 offset:54272
	ds_read_b128 v[214:217], v206 offset:55296
	ds_read_b128 v[218:221], v206 offset:56320
	s_mov_b32 m0, s52
	v_lshl_add_u64 v[182:183], s[2:3], 0, v[146:147]
	global_load_lds_dwordx4 v[182:183], off
	s_add_i32 m0, s52, 0x2000
	v_lshl_add_u64 v[182:183], s[2:3], 0, v[150:151]
	s_add_u32 s2, s50, 0x20080
	s_addc_u32 s3, s51, 0
	s_add_i32 s50, s76, s33
	global_load_lds_dwordx4 v[182:183], off
	s_mov_b32 m0, s50
	v_lshl_add_u64 v[182:183], s[2:3], 0, v[146:147]
	global_load_lds_dwordx4 v[182:183], off
	v_lshl_add_u64 v[182:183], s[2:3], 0, v[150:151]
	s_add_i32 m0, s50, 0x2000
	s_nop 0
	global_load_lds_dwordx4 v[182:183], off
	s_mov_b32 m0, s63
	v_lshl_add_u64 v[182:183], s[48:49], 0, v[144:145]
	global_load_lds_dwordx4 v[182:183], off
	v_lshl_add_u64 v[182:183], s[48:49], 0, v[148:149]
	s_mov_b32 m0, s64
	s_nop 0
	global_load_lds_dwordx4 v[182:183], off
	s_waitcnt vmcnt(8)
	s_waitcnt lgkmcnt(0)
	s_barrier
	s_setprio 1
	v_mfma_f32_16x16x32_bf16 v[60:63], v[128:131], v[178:181], v[60:63]
	v_mfma_f32_16x16x32_bf16 v[56:59], v[136:139], v[178:181], v[56:59]
	v_mfma_f32_16x16x32_bf16 v[44:47], v[128:131], v[190:193], v[44:47]
	v_mfma_f32_16x16x32_bf16 v[40:43], v[136:139], v[190:193], v[40:43]
	v_mfma_f32_16x16x32_bf16 v[28:31], v[128:131], v[198:201], v[28:31]
	v_mfma_f32_16x16x32_bf16 v[24:27], v[136:139], v[198:201], v[24:27]
	v_mfma_f32_16x16x32_bf16 v[12:15], v[128:131], v[214:217], v[12:15]
	v_mfma_f32_16x16x32_bf16 v[8:11], v[136:139], v[214:217], v[8:11]
	v_mfma_f32_16x16x32_bf16 v[60:63], v[132:135], v[186:189], v[60:63]
	v_mfma_f32_16x16x32_bf16 v[56:59], v[140:143], v[186:189], v[56:59]
	v_mfma_f32_16x16x32_bf16 v[44:47], v[132:135], v[194:197], v[44:47]
	v_mfma_f32_16x16x32_bf16 v[40:43], v[140:143], v[194:197], v[40:43]
	v_mfma_f32_16x16x32_bf16 v[28:31], v[132:135], v[210:213], v[28:31]
	v_mfma_f32_16x16x32_bf16 v[24:27], v[140:143], v[210:213], v[24:27]
	v_mfma_f32_16x16x32_bf16 v[12:15], v[132:135], v[218:221], v[12:15]
	v_mfma_f32_16x16x32_bf16 v[8:11], v[140:143], v[218:221], v[8:11]
	v_mfma_f32_16x16x32_bf16 v[52:55], v[162:165], v[178:181], v[52:55]
	v_mfma_f32_16x16x32_bf16 v[48:51], v[170:173], v[178:181], v[48:51]
	v_mfma_f32_16x16x32_bf16 v[36:39], v[162:165], v[190:193], v[36:39]
	v_mfma_f32_16x16x32_bf16 v[32:35], v[170:173], v[190:193], v[32:35]
	v_mfma_f32_16x16x32_bf16 v[20:23], v[162:165], v[198:201], v[20:23]
	v_mfma_f32_16x16x32_bf16 v[16:19], v[170:173], v[198:201], v[16:19]
	v_mfma_f32_16x16x32_bf16 v[4:7], v[162:165], v[214:217], v[4:7]
	v_mfma_f32_16x16x32_bf16 v[0:3], v[170:173], v[214:217], v[0:3]
	v_mfma_f32_16x16x32_bf16 v[52:55], v[166:169], v[186:189], v[52:55]
	v_mfma_f32_16x16x32_bf16 v[48:51], v[174:177], v[186:189], v[48:51]
	v_mfma_f32_16x16x32_bf16 v[36:39], v[166:169], v[194:197], v[36:39]
	v_mfma_f32_16x16x32_bf16 v[32:35], v[174:177], v[194:197], v[32:35]
	v_mfma_f32_16x16x32_bf16 v[20:23], v[166:169], v[210:213], v[20:23]
	v_mfma_f32_16x16x32_bf16 v[16:19], v[174:177], v[210:213], v[16:19]
	v_mfma_f32_16x16x32_bf16 v[4:7], v[166:169], v[218:221], v[4:7]
	v_mfma_f32_16x16x32_bf16 v[0:3], v[174:177], v[218:221], v[0:3]
	s_setprio 0
	s_barrier
	s_add_i32 s74, s74, 2
	s_add_u32 s72, s72, 0x100
	s_addc_u32 s73, s73, 0
	s_cmp_gt_u32 s74, 29
	s_mov_b64 s[2:3], s[6:7]
	s_cbranch_scc0 .LBB0_105
	s_and_b64 vcc, exec, s[84:85]
	s_cbranch_vccz .LBB0_108
	s_barrier

; #define PG8_STAGE(bufoff, gbase, voff) do { unsigned long long _gb = (unsigned long long)(gbase); asm volatile("" : "+s"(_gb)); _Pragma("unroll") for (int _i = 0; _i < 2; ++_i) \
;         __builtin_amdgcn_global_load_lds((const GAS unsigned*)((const GAS char*)_gb + (voff)[_i]), (LAS unsigned*)(lds + (bufoff) + ldsw + _i * 8192), 16, 0, 0); } while (0)
; #define PG8_LDA(dst, b, h) do { _Pragma("unroll") for (int m = 0; m < 4; ++m) _Pragma("unroll") for (int k = 0; k < 2; ++k) dst[m][k] = *(const LAS bf16x8*)(lds + PG8_SA(b, h) + aoff + m * 2048 + k * 1024); } while (0)
; #define PG8_LDB(dst, b, h) do { _Pragma("unroll") for (int n = 0; n < 2; ++n) _Pragma("unroll") for (int k = 0; k < 2; ++k) dst[n][k] = *(const LAS bf16x8*)(lds + PG8_SB(b, h) + boff + n * 2048 + k * 1024); } while (0)
; #define PG8_MMA(ai, bj, At, Bt) do { __builtin_amdgcn_s_setprio(1); _Pragma("unroll") for (int m = 0; m < 4; ++m) _Pragma("unroll") for (int n = 0; n < 2; ++n) _Pragma("unroll") for (int k = 0; k < 2; ++k) \
;         acc[ai][bj][m][n] = __builtin_amdgcn_mfma_f32_16x16x32_bf16(Bt[n][k], At[m][k], acc[ai][bj][m][n], 0, 0, 0); __builtin_amdgcn_s_setprio(0); } while (0)
; template <class Epi, bool ALIGN_EPI>
; __device__ __forceinline__ void gemm_phase(LAS unsigned char* lds, const Gemm g, const StaticOrder& S, const Epi& E, const int wid) {
;     ...
;             PG8_LDB(B0, 0, 0); PG8_LDB(B1, 0, 1); PG8_SCHED; PG8_LDA(At, 0, 0); PG8_STAGE(PG8_SA(1, 1), a1 + hstep, voffA);
;             PG8_WAIT_V(8); PG8_WAIT_L(0); PG8_BAR; PG8_MMA(0, 0, At, B0); PG8_MMA(0, 1, At, B1); PG8_BAR; PG8_SCHED;
;             PG8_LDA(At, 0, 1); PG8_STAGE(PG8_SB(0, 0), b2, voffB); PG8_STAGE(PG8_SB(0, 1), b2 + hstepB, voffB); PG8_STAGE(PG8_SA(0, 0), a2, voffA);
;             PG8_WAIT_V(8); PG8_WAIT_L(0); PG8_BAR; PG8_MMA(1, 0, At, B0); PG8_MMA(1, 1, At, B1); PG8_BAR; PG8_SCHED;
;             PG8_LDB(B0, 1, 0); PG8_LDB(B1, 1, 1); PG8_SCHED; PG8_LDA(At, 1, 0); PG8_STAGE(PG8_SA(0, 1), a2 + hstep, voffA);
;             PG8_WAIT_V(8); PG8_WAIT_L(0); PG8_BAR; PG8_MMA(0, 0, At, B0); PG8_MMA(0, 1, At, B1); PG8_BAR; PG8_SCHED;
;             PG8_LDA(At, 1, 1); PG8_STAGE(PG8_SB(1, 0), b3, voffB); PG8_STAGE(PG8_SB(1, 1), b3 + hstepB, voffB); PG8_STAGE(PG8_SA(1, 0), a3, voffA);
;             PG8_WAIT_V(8); PG8_WAIT_L(0); PG8_BAR; PG8_MMA(1, 0, At, B0); PG8_MMA(1, 1, At, B1); PG8_BAR; PG8_SCHED;
.LBB0_488:
	s_ashr_i32 s19, s18, 31
	s_lshl_b64 s[22:23], s[18:19], 17
	s_add_u32 s22, s42, s22
	s_addc_u32 s23, s43, s23
	s_and_b64 s[26:27], s[4:5], exec
	ds_read_b128 v[0:3], v141
	ds_read_b128 v[4:7], v141 offset:1024
	ds_read_b128 v[8:11], v141 offset:2048
	ds_read_b128 v[12:15], v141 offset:3072
	ds_read_b128 v[16:19], v142
	ds_read_b128 v[20:23], v142 offset:1024
	ds_read_b128 v[24:27], v142 offset:2048
	ds_read_b128 v[28:31], v142 offset:3072
	s_cselect_b32 s37, s23, s29
	s_cselect_b32 s36, s22, s28
	s_ashr_i32 s17, s16, 31
	s_lshl_b64 s[26:27], s[16:17], 17
	s_add_u32 s26, s24, s26
	s_addc_u32 s27, s25, s27
	s_and_b64 s[30:31], s[4:5], exec
	s_cselect_b32 s31, s27, s35
	s_cselect_b32 s30, s26, s34
	s_add_u32 s40, s28, 0x100
	s_addc_u32 s41, s29, 0
	s_add_u32 s56, s34, 0x100
	s_addc_u32 s57, s35, 0
	s_add_u32 s38, s28, 0x180
	s_addc_u32 s39, s29, 0
	s_add_u32 s58, s28, 0x10080
	s_addc_u32 s59, s29, 0
	s_add_i32 s62, s44, 0xc000
	ds_read_b128 v[32:35], v143
	ds_read_b128 v[36:39], v143 offset:1024
	ds_read_b128 v[40:43], v143 offset:2048
	ds_read_b128 v[44:47], v143 offset:3072
	ds_read_b128 v[48:51], v143 offset:4096
	ds_read_b128 v[52:55], v143 offset:5120
	ds_read_b128 v[56:59], v143 offset:6144
	ds_read_b128 v[60:63], v143 offset:7168
	s_mov_b32 m0, s62
	v_lshl_add_u64 v[64:65], s[58:59], 0, v[134:135]
	s_add_i32 s17, s44, 0xe000
	global_load_lds_dwordx4 v[64:65], off
	v_lshl_add_u64 v[64:65], s[58:59], 0, v[130:131]
	s_mov_b32 m0, s17
	s_nop 0
	global_load_lds_dwordx4 v[64:65], off
	s_waitcnt vmcnt(8)
	s_waitcnt lgkmcnt(0)
	s_barrier
	s_setprio 1
	v_mfma_f32_16x16x32_bf16 v[64:67], v[0:3], v[32:35], 0
	v_mfma_f32_16x16x32_bf16 v[68:71], v[8:11], v[32:35], 0
	v_mfma_f32_16x16x32_bf16 v[72:75], v[0:3], v[40:43], 0
	v_mfma_f32_16x16x32_bf16 v[76:79], v[8:11], v[40:43], 0
	v_mfma_f32_16x16x32_bf16 v[80:83], v[0:3], v[48:51], 0
	v_mfma_f32_16x16x32_bf16 v[84:87], v[8:11], v[48:51], 0
	v_mfma_f32_16x16x32_bf16 v[88:91], v[0:3], v[56:59], 0
	v_mfma_f32_16x16x32_bf16 v[92:95], v[8:11], v[56:59], 0
	v_mfma_f32_16x16x32_bf16 v[64:67], v[4:7], v[36:39], v[64:67]
	v_mfma_f32_16x16x32_bf16 v[68:71], v[12:15], v[36:39], v[68:71]
	v_mfma_f32_16x16x32_bf16 v[72:75], v[4:7], v[44:47], v[72:75]
	v_mfma_f32_16x16x32_bf16 v[76:79], v[12:15], v[44:47], v[76:79]
	v_mfma_f32_16x16x32_bf16 v[80:83], v[4:7], v[52:55], v[80:83]
	v_mfma_f32_16x16x32_bf16 v[84:87], v[12:15], v[52:55], v[84:87]
	v_mfma_f32_16x16x32_bf16 v[88:91], v[4:7], v[60:63], v[88:91]
	v_mfma_f32_16x16x32_bf16 v[92:95], v[12:15], v[60:63], v[92:95]
	v_mfma_f32_16x16x32_bf16 v[96:99], v[16:19], v[32:35], 0
	v_mfma_f32_16x16x32_bf16 v[32:35], v[24:27], v[32:35], 0
	v_mfma_f32_16x16x32_bf16 v[96:99], v[20:23], v[36:39], v[96:99]
	v_mfma_f32_16x16x32_bf16 v[32:35], v[28:31], v[36:39], v[32:35]
	v_mfma_f32_16x16x32_bf16 v[36:39], v[16:19], v[40:43], 0
	v_mfma_f32_16x16x32_bf16 v[40:43], v[24:27], v[40:43], 0
	v_mfma_f32_16x16x32_bf16 v[36:39], v[20:23], v[44:47], v[36:39]
	v_mfma_f32_16x16x32_bf16 v[40:43], v[28:31], v[44:47], v[40:43]
	v_mfma_f32_16x16x32_bf16 v[44:47], v[16:19], v[48:51], 0
	v_mfma_f32_16x16x32_bf16 v[48:51], v[24:27], v[48:51], 0
	v_mfma_f32_16x16x32_bf16 v[44:47], v[20:23], v[52:55], v[44:47]
	v_mfma_f32_16x16x32_bf16 v[48:51], v[28:31], v[52:55], v[48:51]
	v_mfma_f32_16x16x32_bf16 v[52:55], v[16:19], v[56:59], 0
	v_mfma_f32_16x16x32_bf16 v[56:59], v[24:27], v[56:59], 0
	v_mfma_f32_16x16x32_bf16 v[52:55], v[20:23], v[60:63], v[52:55]
	v_mfma_f32_16x16x32_bf16 v[56:59], v[28:31], v[60:63], v[56:59]
	s_setprio 0
	s_barrier
	s_add_i32 s59, s52, s33
	s_add_i32 s19, s59, 0x2000
	ds_read_b128 v[60:63], v143 offset:16384
	ds_read_b128 v[100:103], v143 offset:17408
	ds_read_b128 v[104:107], v143 offset:18432
	ds_read_b128 v[108:111], v143 offset:19456
	ds_read_b128 v[112:115], v143 offset:20480
	ds_read_b128 v[116:119], v143 offset:21504
	ds_read_b128 v[120:123], v143 offset:22528
	ds_read_b128 v[124:127], v143 offset:23552
	s_mov_b32 m0, s59
	v_lshl_add_u64 v[144:145], s[56:57], 0, v[132:133]
	s_add_u32 s64, s34, 0x4100
	global_load_lds_dwordx4 v[144:145], off
	v_lshl_add_u64 v[144:145], s[56:57], 0, v[128:129]
	s_mov_b32 m0, s19
	s_addc_u32 s65, s35, 0
	s_add_i32 s56, s53, s33
	global_load_lds_dwordx4 v[144:145], off
	s_mov_b32 m0, s56
	v_lshl_add_u64 v[144:145], s[64:65], 0, v[132:133]
	s_add_i32 s57, s56, 0x2000
	global_load_lds_dwordx4 v[144:145], off
	v_lshl_add_u64 v[144:145], s[64:65], 0, v[128:129]
	s_mov_b32 m0, s57
	s_nop 0
	global_load_lds_dwordx4 v[144:145], off
	s_mov_b32 m0, s44
	v_lshl_add_u64 v[144:145], s[40:41], 0, v[134:135]
	global_load_lds_dwordx4 v[144:145], off
	v_lshl_add_u64 v[144:145], s[40:41], 0, v[130:131]
	s_mov_b32 m0, s45
	s_nop 0
	global_load_lds_dwordx4 v[144:145], off
	s_waitcnt vmcnt(8)
	s_waitcnt lgkmcnt(0)
	s_barrier
; #define PG8_STAGE(bufoff, gbase, voff) do { unsigned long long _gb = (unsigned long long)(gbase); asm volatile("" : "+s"(_gb)); _Pragma("unroll") for (int _i = 0; _i < 2; ++_i) \
;         __builtin_amdgcn_global_load_lds((const GAS unsigned*)((const GAS char*)_gb + (voff)[_i]), (LAS unsigned*)(lds + (bufoff) + ldsw + _i * 8192), 16, 0, 0); } while (0)
; #define PG8_LDA(dst, b, h) do { _Pragma("unroll") for (int m = 0; m < 4; ++m) _Pragma("unroll") for (int k = 0; k < 2; ++k) dst[m][k] = *(const LAS bf16x8*)(lds + PG8_SA(b, h) + aoff + m * 2048 + k * 1024); } while (0)
; #define PG8_LDB(dst, b, h) do { _Pragma("unroll") for (int n = 0; n < 2; ++n) _Pragma("unroll") for (int k = 0; k < 2; ++k) dst[n][k] = *(const LAS bf16x8*)(lds + PG8_SB(b, h) + boff + n * 2048 + k * 1024); } while (0)
; #define PG8_MMA(ai, bj, At, Bt) do { __builtin_amdgcn_s_setprio(1); _Pragma("unroll") for (int m = 0; m < 4; ++m) _Pragma("unroll") for (int n = 0; n < 2; ++n) _Pragma("unroll") for (int k = 0; k < 2; ++k) \
;         acc[ai][bj][m][n] = __builtin_amdgcn_mfma_f32_16x16x32_bf16(Bt[n][k], At[m][k], acc[ai][bj][m][n], 0, 0, 0); __builtin_amdgcn_s_setprio(0); } while (0)
; template <class Epi, bool ALIGN_EPI>
; __device__ __forceinline__ void gemm_phase(LAS unsigned char* lds, const Gemm g, const StaticOrder& S, const Epi& E, const int wid) {
;     ...
;             PG8_LDB(B0, 0, 0); PG8_LDB(B1, 0, 1); PG8_SCHED; PG8_LDA(At, 0, 0); PG8_STAGE(PG8_SA(1, 1), a1 + hstep, voffA);
;             PG8_WAIT_V(8); PG8_WAIT_L(0); PG8_BAR; PG8_MMA(0, 0, At, B0); PG8_MMA(0, 1, At, B1); PG8_BAR; PG8_SCHED;
;             PG8_LDA(At, 0, 1); PG8_STAGE(PG8_SB(0, 0), b2, voffB); PG8_STAGE(PG8_SB(0, 1), b2 + hstepB, voffB); PG8_STAGE(PG8_SA(0, 0), a2, voffA);
;             PG8_WAIT_V(8); PG8_WAIT_L(0); PG8_BAR; PG8_MMA(1, 0, At, B0); PG8_MMA(1, 1, At, B1); PG8_BAR; PG8_SCHED;
;             PG8_LDB(B0, 1, 0); PG8_LDB(B1, 1, 1); PG8_SCHED; PG8_LDA(At, 1, 0); PG8_STAGE(PG8_SA(0, 1), a2 + hstep, voffA);
;             PG8_WAIT_V(8); PG8_WAIT_L(0); PG8_BAR; PG8_MMA(0, 0, At, B0); PG8_MMA(0, 1, At, B1); PG8_BAR; PG8_SCHED;
;             PG8_LDA(At, 1, 1); PG8_STAGE(PG8_SB(1, 0), b3, voffB); PG8_STAGE(PG8_SB(1, 1), b3 + hstepB, voffB); PG8_STAGE(PG8_SA(1, 0), a3, voffA);
;             PG8_WAIT_V(8); PG8_WAIT_L(0); PG8_BAR; PG8_MMA(1, 0, At, B0); PG8_MMA(1, 1, At, B1); PG8_BAR; PG8_SCHED;
	s_setprio 1
	v_mfma_f32_16x16x32_bf16 v[144:147], v[0:3], v[60:63], 0
	v_mfma_f32_16x16x32_bf16 v[152:155], v[0:3], v[104:107], 0
	v_mfma_f32_16x16x32_bf16 v[160:163], v[0:3], v[112:115], 0
	v_mfma_f32_16x16x32_bf16 v[0:3], v[0:3], v[120:123], 0
	v_mfma_f32_16x16x32_bf16 v[144:147], v[4:7], v[100:103], v[144:147]
	v_mfma_f32_16x16x32_bf16 v[152:155], v[4:7], v[108:111], v[152:155]
	v_mfma_f32_16x16x32_bf16 v[160:163], v[4:7], v[116:119], v[160:163]
	v_mfma_f32_16x16x32_bf16 v[0:3], v[4:7], v[124:127], v[0:3]
	v_mfma_f32_16x16x32_bf16 v[4:7], v[8:11], v[120:123], 0
	v_mfma_f32_16x16x32_bf16 v[148:151], v[8:11], v[60:63], 0
	v_mfma_f32_16x16x32_bf16 v[156:159], v[8:11], v[104:107], 0
	v_mfma_f32_16x16x32_bf16 v[164:167], v[8:11], v[112:115], 0
	v_mfma_f32_16x16x32_bf16 v[4:7], v[12:15], v[124:127], v[4:7]
	v_mfma_f32_16x16x32_bf16 v[148:151], v[12:15], v[100:103], v[148:151]
	v_mfma_f32_16x16x32_bf16 v[156:159], v[12:15], v[108:111], v[156:159]
	v_mfma_f32_16x16x32_bf16 v[164:167], v[12:15], v[116:119], v[164:167]
	v_mfma_f32_16x16x32_bf16 v[8:11], v[16:19], v[60:63], 0
	v_mfma_f32_16x16x32_bf16 v[12:15], v[24:27], v[60:63], 0
	v_mfma_f32_16x16x32_bf16 v[8:11], v[20:23], v[100:103], v[8:11]
	v_mfma_f32_16x16x32_bf16 v[12:15], v[28:31], v[100:103], v[12:15]
	v_mfma_f32_16x16x32_bf16 v[60:63], v[16:19], v[104:107], 0
	v_mfma_f32_16x16x32_bf16 v[100:103], v[24:27], v[104:107], 0
	v_mfma_f32_16x16x32_bf16 v[104:107], v[16:19], v[112:115], 0
	v_mfma_f32_16x16x32_bf16 v[16:19], v[16:19], v[120:123], 0
	v_mfma_f32_16x16x32_bf16 v[60:63], v[20:23], v[108:111], v[60:63]
	v_mfma_f32_16x16x32_bf16 v[100:103], v[28:31], v[108:111], v[100:103]
	v_mfma_f32_16x16x32_bf16 v[104:107], v[20:23], v[116:119], v[104:107]
	v_mfma_f32_16x16x32_bf16 v[108:111], v[24:27], v[112:115], 0
	v_mfma_f32_16x16x32_bf16 v[16:19], v[20:23], v[124:127], v[16:19]
	v_mfma_f32_16x16x32_bf16 v[20:23], v[24:27], v[120:123], 0
	v_mfma_f32_16x16x32_bf16 v[108:111], v[28:31], v[116:119], v[108:111]
	v_mfma_f32_16x16x32_bf16 v[20:23], v[28:31], v[124:127], v[20:23]
	s_setprio 0
	s_barrier
	s_add_i32 s63, 0, 0x18000
	s_add_i32 s58, 0, 0x1c000
	v_add_u32_e32 v184, s63, v140
	v_add_u32_e32 v236, s58, v140
	ds_read_b128 v[24:27], v184
	ds_read_b128 v[28:31], v184 offset:1024
	ds_read_b128 v[112:115], v184 offset:2048
	ds_read_b128 v[116:119], v184 offset:3072
	ds_read_b128 v[120:123], v236
	ds_read_b128 v[124:127], v236 offset:1024
	ds_read_b128 v[168:171], v236 offset:2048
	ds_read_b128 v[172:175], v236 offset:3072
	s_add_u32 s40, s28, 0x10100
	s_addc_u32 s41, s29, 0
	s_mov_b32 m0, s46
	ds_read_b128 v[176:179], v143 offset:32768
	ds_read_b128 v[180:183], v143 offset:33792
	ds_read_b128 v[186:189], v143 offset:34816
	ds_read_b128 v[190:193], v143 offset:35840
	ds_read_b128 v[194:197], v143 offset:36864
	ds_read_b128 v[198:201], v143 offset:37888
	ds_read_b128 v[204:207], v143 offset:38912
	ds_read_b128 v[208:211], v143 offset:39936
	s_nop 0
	v_lshl_add_u64 v[202:203], s[40:41], 0, v[134:135]
	global_load_lds_dwordx4 v[202:203], off
	v_lshl_add_u64 v[202:203], s[40:41], 0, v[130:131]
	s_mov_b32 m0, s47
	s_nop 0
	global_load_lds_dwordx4 v[202:203], off
	s_waitcnt vmcnt(8)
	s_waitcnt lgkmcnt(0)
	s_barrier
	s_setprio 1
	v_mfma_f32_16x16x32_bf16 v[64:67], v[24:27], v[176:179], v[64:67]
	v_mfma_f32_16x16x32_bf16 v[68:71], v[112:115], v[176:179], v[68:71]
	v_mfma_f32_16x16x32_bf16 v[72:75], v[24:27], v[186:189], v[72:75]
	v_mfma_f32_16x16x32_bf16 v[76:79], v[112:115], v[186:189], v[76:79]
	v_mfma_f32_16x16x32_bf16 v[80:83], v[24:27], v[194:197], v[80:83]
	v_mfma_f32_16x16x32_bf16 v[84:87], v[112:115], v[194:197], v[84:87]
	v_mfma_f32_16x16x32_bf16 v[88:91], v[24:27], v[204:207], v[88:91]
	v_mfma_f32_16x16x32_bf16 v[92:95], v[112:115], v[204:207], v[92:95]
	v_mfma_f32_16x16x32_bf16 v[64:67], v[28:31], v[180:183], v[64:67]
	v_mfma_f32_16x16x32_bf16 v[68:71], v[116:119], v[180:183], v[68:71]
	v_mfma_f32_16x16x32_bf16 v[72:75], v[28:31], v[190:193], v[72:75]
	v_mfma_f32_16x16x32_bf16 v[76:79], v[116:119], v[190:193], v[76:79]
	v_mfma_f32_16x16x32_bf16 v[80:83], v[28:31], v[198:201], v[80:83]
	v_mfma_f32_16x16x32_bf16 v[84:87], v[116:119], v[198:201], v[84:87]
	v_mfma_f32_16x16x32_bf16 v[88:91], v[28:31], v[208:211], v[88:91]
	v_mfma_f32_16x16x32_bf16 v[92:95], v[116:119], v[208:211], v[92:95]
	v_mfma_f32_16x16x32_bf16 v[96:99], v[120:123], v[176:179], v[96:99]
	v_mfma_f32_16x16x32_bf16 v[32:35], v[168:171], v[176:179], v[32:35]
	v_mfma_f32_16x16x32_bf16 v[36:39], v[120:123], v[186:189], v[36:39]
	v_mfma_f32_16x16x32_bf16 v[40:43], v[168:171], v[186:189], v[40:43]
	v_mfma_f32_16x16x32_bf16 v[44:47], v[120:123], v[194:197], v[44:47]
	v_mfma_f32_16x16x32_bf16 v[48:51], v[168:171], v[194:197], v[48:51]
	v_mfma_f32_16x16x32_bf16 v[52:55], v[120:123], v[204:207], v[52:55]
	v_mfma_f32_16x16x32_bf16 v[56:59], v[168:171], v[204:207], v[56:59]
	v_mfma_f32_16x16x32_bf16 v[96:99], v[124:127], v[180:183], v[96:99]
	v_mfma_f32_16x16x32_bf16 v[32:35], v[172:175], v[180:183], v[32:35]
	v_mfma_f32_16x16x32_bf16 v[36:39], v[124:127], v[190:193], v[36:39]
	v_mfma_f32_16x16x32_bf16 v[40:43], v[172:175], v[190:193], v[40:43]
	v_mfma_f32_16x16x32_bf16 v[44:47], v[124:127], v[198:201], v[44:47]
	v_mfma_f32_16x16x32_bf16 v[48:51], v[172:175], v[198:201], v[48:51]
	v_mfma_f32_16x16x32_bf16 v[52:55], v[124:127], v[208:211], v[52:55]
	v_mfma_f32_16x16x32_bf16 v[56:59], v[172:175], v[208:211], v[56:59]
	s_setprio 0
	s_barrier
; #define PG8_STAGE(bufoff, gbase, voff) do { unsigned long long _gb = (unsigned long long)(gbase); asm volatile("" : "+s"(_gb)); _Pragma("unroll") for (int _i = 0; _i < 2; ++_i) \
;         __builtin_amdgcn_global_load_lds((const GAS unsigned*)((const GAS char*)_gb + (voff)[_i]), (LAS unsigned*)(lds + (bufoff) + ldsw + _i * 8192), 16, 0, 0); } while (0)
; #define PG8_LDA(dst, b, h) do { _Pragma("unroll") for (int m = 0; m < 4; ++m) _Pragma("unroll") for (int k = 0; k < 2; ++k) dst[m][k] = *(const LAS bf16x8*)(lds + PG8_SA(b, h) + aoff + m * 2048 + k * 1024); } while (0)
; #define PG8_LDB(dst, b, h) do { _Pragma("unroll") for (int n = 0; n < 2; ++n) _Pragma("unroll") for (int k = 0; k < 2; ++k) dst[n][k] = *(const LAS bf16x8*)(lds + PG8_SB(b, h) + boff + n * 2048 + k * 1024); } while (0)
; #define PG8_MMA(ai, bj, At, Bt) do { __builtin_amdgcn_s_setprio(1); _Pragma("unroll") for (int m = 0; m < 4; ++m) _Pragma("unroll") for (int n = 0; n < 2; ++n) _Pragma("unroll") for (int k = 0; k < 2; ++k) \
;         acc[ai][bj][m][n] = __builtin_amdgcn_mfma_f32_16x16x32_bf16(Bt[n][k], At[m][k], acc[ai][bj][m][n], 0, 0, 0); __builtin_amdgcn_s_setprio(0); } while (0)
; template <class Epi, bool ALIGN_EPI>
; __device__ __forceinline__ void gemm_phase(LAS unsigned char* lds, const Gemm g, const StaticOrder& S, const Epi& E, const int wid) {
;     ...
;             PG8_LDB(B0, 0, 0); PG8_LDB(B1, 0, 1); PG8_SCHED; PG8_LDA(At, 0, 0); PG8_STAGE(PG8_SA(1, 1), a1 + hstep, voffA);
;             PG8_WAIT_V(8); PG8_WAIT_L(0); PG8_BAR; PG8_MMA(0, 0, At, B0); PG8_MMA(0, 1, At, B1); PG8_BAR; PG8_SCHED;
;             PG8_LDA(At, 0, 1); PG8_STAGE(PG8_SB(0, 0), b2, voffB); PG8_STAGE(PG8_SB(0, 1), b2 + hstepB, voffB); PG8_STAGE(PG8_SA(0, 0), a2, voffA);
;             PG8_WAIT_V(8); PG8_WAIT_L(0); PG8_BAR; PG8_MMA(1, 0, At, B0); PG8_MMA(1, 1, At, B1); PG8_BAR; PG8_SCHED;
;             PG8_LDB(B0, 1, 0); PG8_LDB(B1, 1, 1); PG8_SCHED; PG8_LDA(At, 1, 0); PG8_STAGE(PG8_SA(0, 1), a2 + hstep, voffA);
;             PG8_WAIT_V(8); PG8_WAIT_L(0); PG8_BAR; PG8_MMA(0, 0, At, B0); PG8_MMA(0, 1, At, B1); PG8_BAR; PG8_SCHED;
;             PG8_LDA(At, 1, 1); PG8_STAGE(PG8_SB(1, 0), b3, voffB); PG8_STAGE(PG8_SB(1, 1), b3 + hstepB, voffB); PG8_STAGE(PG8_SA(1, 0), a3, voffA);
;             PG8_WAIT_V(8); PG8_WAIT_L(0); PG8_BAR; PG8_MMA(1, 0, At, B0); PG8_MMA(1, 1, At, B1); PG8_BAR; PG8_SCHED;
	s_add_u32 s40, s34, 0x180
	s_addc_u32 s41, s35, 0
	s_add_i32 s63, s63, s33
	ds_read_b128 v[176:179], v143 offset:49152
	ds_read_b128 v[180:183], v143 offset:50176
	ds_read_b128 v[186:189], v143 offset:51200
	ds_read_b128 v[190:193], v143 offset:52224
	ds_read_b128 v[194:197], v143 offset:53248
	ds_read_b128 v[198:201], v143 offset:54272
	ds_read_b128 v[204:207], v143 offset:55296
	ds_read_b128 v[208:211], v143 offset:56320
	s_mov_b32 m0, s63
	v_lshl_add_u64 v[202:203], s[40:41], 0, v[132:133]
	global_load_lds_dwordx4 v[202:203], off
	v_lshl_add_u64 v[202:203], s[40:41], 0, v[128:129]
	s_add_i32 s40, s63, 0x2000
	s_add_u32 s34, s34, 0x4180
	s_mov_b32 m0, s40
	s_addc_u32 s35, s35, 0
	s_add_i32 s41, s58, s33
	global_load_lds_dwordx4 v[202:203], off
	s_mov_b32 m0, s41
	v_lshl_add_u64 v[202:203], s[34:35], 0, v[132:133]
	s_add_i32 s58, s41, 0x2000
	global_load_lds_dwordx4 v[202:203], off
	v_lshl_add_u64 v[202:203], s[34:35], 0, v[128:129]
	s_mov_b32 m0, s58
	s_nop 0
	global_load_lds_dwordx4 v[202:203], off
	s_mov_b32 m0, s50
	v_lshl_add_u64 v[202:203], s[38:39], 0, v[134:135]
	global_load_lds_dwordx4 v[202:203], off
	v_lshl_add_u64 v[202:203], s[38:39], 0, v[130:131]
	s_mov_b32 m0, s51
	s_nop 0
	global_load_lds_dwordx4 v[202:203], off
	s_waitcnt vmcnt(8)
	s_waitcnt lgkmcnt(0)
	s_barrier
	s_setprio 1
	v_mfma_f32_16x16x32_bf16 v[0:3], v[24:27], v[204:207], v[0:3]
	v_mfma_f32_16x16x32_bf16 v[4:7], v[112:115], v[204:207], v[4:7]
	v_mfma_f32_16x16x32_bf16 v[144:147], v[24:27], v[176:179], v[144:147]
	v_mfma_f32_16x16x32_bf16 v[148:151], v[112:115], v[176:179], v[148:151]
	v_mfma_f32_16x16x32_bf16 v[152:155], v[24:27], v[186:189], v[152:155]
	v_mfma_f32_16x16x32_bf16 v[156:159], v[112:115], v[186:189], v[156:159]
	v_mfma_f32_16x16x32_bf16 v[160:163], v[24:27], v[194:197], v[160:163]
	v_mfma_f32_16x16x32_bf16 v[164:167], v[112:115], v[194:197], v[164:167]
	v_mfma_f32_16x16x32_bf16 v[0:3], v[28:31], v[208:211], v[0:3]
	v_mfma_f32_16x16x32_bf16 v[4:7], v[116:119], v[208:211], v[4:7]
	v_mfma_f32_16x16x32_bf16 v[144:147], v[28:31], v[180:183], v[144:147]
	v_mfma_f32_16x16x32_bf16 v[148:151], v[116:119], v[180:183], v[148:151]
	v_mfma_f32_16x16x32_bf16 v[152:155], v[28:31], v[190:193], v[152:155]
	v_mfma_f32_16x16x32_bf16 v[156:159], v[116:119], v[190:193], v[156:159]
	v_mfma_f32_16x16x32_bf16 v[160:163], v[28:31], v[198:201], v[160:163]
	v_mfma_f32_16x16x32_bf16 v[164:167], v[116:119], v[198:201], v[164:167]
	v_mfma_f32_16x16x32_bf16 v[8:11], v[120:123], v[176:179], v[8:11]
	v_mfma_f32_16x16x32_bf16 v[12:15], v[168:171], v[176:179], v[12:15]
	v_mfma_f32_16x16x32_bf16 v[24:27], v[120:123], v[186:189], v[60:63]
	v_mfma_f32_16x16x32_bf16 v[28:31], v[168:171], v[186:189], v[100:103]
	v_mfma_f32_16x16x32_bf16 v[60:63], v[120:123], v[194:197], v[104:107]
	v_mfma_f32_16x16x32_bf16 v[100:103], v[168:171], v[194:197], v[108:111]
	v_mfma_f32_16x16x32_bf16 v[16:19], v[120:123], v[204:207], v[16:19]
	v_mfma_f32_16x16x32_bf16 v[20:23], v[168:171], v[204:207], v[20:23]
	v_mfma_f32_16x16x32_bf16 v[8:11], v[124:127], v[180:183], v[8:11]
	v_mfma_f32_16x16x32_bf16 v[12:15], v[172:175], v[180:183], v[12:15]
	v_mfma_f32_16x16x32_bf16 v[24:27], v[124:127], v[190:193], v[24:27]
	v_mfma_f32_16x16x32_bf16 v[28:31], v[172:175], v[190:193], v[28:31]
	v_mfma_f32_16x16x32_bf16 v[60:63], v[124:127], v[198:201], v[60:63]
	v_mfma_f32_16x16x32_bf16 v[100:103], v[172:175], v[198:201], v[100:103]
	v_mfma_f32_16x16x32_bf16 v[16:19], v[124:127], v[208:211], v[16:19]
	v_mfma_f32_16x16x32_bf16 v[20:23], v[172:175], v[208:211], v[20:23]
	s_setprio 0
	s_barrier
	ds_read_b128 v[104:107], v141
	ds_read_b128 v[108:111], v141 offset:1024
	ds_read_b128 v[112:115], v141 offset:2048
	ds_read_b128 v[116:119], v141 offset:3072
	ds_read_b128 v[120:123], v142
	ds_read_b128 v[124:127], v142 offset:1024
	ds_read_b128 v[168:171], v142 offset:2048
	ds_read_b128 v[172:175], v142 offset:3072
	s_add_u32 s34, s36, 0x80
	s_addc_u32 s35, s37, 0
	s_add_u32 s28, s28, 0x10180
	s_addc_u32 s29, s29, 0
	s_mov_b32 m0, s62
	ds_read_b128 v[176:179], v143
	ds_read_b128 v[180:183], v143 offset:1024
	ds_read_b128 v[186:189], v143 offset:2048
	ds_read_b128 v[190:193], v143 offset:3072
	ds_read_b128 v[194:197], v143 offset:4096
	ds_read_b128 v[198:201], v143 offset:5120
	ds_read_b128 v[204:207], v143 offset:6144
	ds_read_b128 v[208:211], v143 offset:7168
	s_nop 0
	v_lshl_add_u64 v[202:203], s[28:29], 0, v[134:135]
	global_load_lds_dwordx4 v[202:203], off
	v_lshl_add_u64 v[202:203], s[28:29], 0, v[130:131]
	s_mov_b32 m0, s17
	s_nop 0
	global_load_lds_dwordx4 v[202:203], off
	s_waitcnt vmcnt(8)
	s_waitcnt lgkmcnt(0)
	s_barrier
; #define PG8_STAGE(bufoff, gbase, voff) do { unsigned long long _gb = (unsigned long long)(gbase); asm volatile("" : "+s"(_gb)); _Pragma("unroll") for (int _i = 0; _i < 2; ++_i) \
;         __builtin_amdgcn_global_load_lds((const GAS unsigned*)((const GAS char*)_gb + (voff)[_i]), (LAS unsigned*)(lds + (bufoff) + ldsw + _i * 8192), 16, 0, 0); } while (0)
; #define PG8_LDA(dst, b, h) do { _Pragma("unroll") for (int m = 0; m < 4; ++m) _Pragma("unroll") for (int k = 0; k < 2; ++k) dst[m][k] = *(const LAS bf16x8*)(lds + PG8_SA(b, h) + aoff + m * 2048 + k * 1024); } while (0)
; #define PG8_LDB(dst, b, h) do { _Pragma("unroll") for (int n = 0; n < 2; ++n) _Pragma("unroll") for (int k = 0; k < 2; ++k) dst[n][k] = *(const LAS bf16x8*)(lds + PG8_SB(b, h) + boff + n * 2048 + k * 1024); } while (0)
; #define PG8_MMA(ai, bj, At, Bt) do { __builtin_amdgcn_s_setprio(1); _Pragma("unroll") for (int m = 0; m < 4; ++m) _Pragma("unroll") for (int n = 0; n < 2; ++n) _Pragma("unroll") for (int k = 0; k < 2; ++k) \
;         acc[ai][bj][m][n] = __builtin_amdgcn_mfma_f32_16x16x32_bf16(Bt[n][k], At[m][k], acc[ai][bj][m][n], 0, 0, 0); __builtin_amdgcn_s_setprio(0); } while (0)
; template <class Epi, bool ALIGN_EPI>
; __device__ __forceinline__ void gemm_phase(LAS unsigned char* lds, const Gemm g, const StaticOrder& S, const Epi& E, const int wid) {
;     ...
;             PG8_LDB(B0, 0, 0); PG8_LDB(B1, 0, 1); PG8_SCHED; PG8_LDA(At, 0, 0); PG8_STAGE(PG8_SA(1, 1), a1 + hstep, voffA);
;             PG8_WAIT_V(8); PG8_WAIT_L(0); PG8_BAR; PG8_MMA(0, 0, At, B0); PG8_MMA(0, 1, At, B1); PG8_BAR; PG8_SCHED;
;             PG8_LDA(At, 0, 1); PG8_STAGE(PG8_SB(0, 0), b2, voffB); PG8_STAGE(PG8_SB(0, 1), b2 + hstepB, voffB); PG8_STAGE(PG8_SA(0, 0), a2, voffA);
;             PG8_WAIT_V(8); PG8_WAIT_L(0); PG8_BAR; PG8_MMA(1, 0, At, B0); PG8_MMA(1, 1, At, B1); PG8_BAR; PG8_SCHED;
;             PG8_LDB(B0, 1, 0); PG8_LDB(B1, 1, 1); PG8_SCHED; PG8_LDA(At, 1, 0); PG8_STAGE(PG8_SA(0, 1), a2 + hstep, voffA);
;             PG8_WAIT_V(8); PG8_WAIT_L(0); PG8_BAR; PG8_MMA(0, 0, At, B0); PG8_MMA(0, 1, At, B1); PG8_BAR; PG8_SCHED;
;             PG8_LDA(At, 1, 1); PG8_STAGE(PG8_SB(1, 0), b3, voffB); PG8_STAGE(PG8_SB(1, 1), b3 + hstepB, voffB); PG8_STAGE(PG8_SA(1, 0), a3, voffA);
;             PG8_WAIT_V(8); PG8_WAIT_L(0); PG8_BAR; PG8_MMA(1, 0, At, B0); PG8_MMA(1, 1, At, B1); PG8_BAR; PG8_SCHED;
	s_setprio 1
	v_mfma_f32_16x16x32_bf16 v[80:83], v[104:107], v[194:197], v[80:83]
	v_mfma_f32_16x16x32_bf16 v[212:215], v[108:111], v[198:201], v[80:83]
	v_mfma_f32_16x16x32_bf16 v[80:83], v[112:115], v[194:197], v[84:87]
	v_mfma_f32_16x16x32_bf16 v[216:219], v[116:119], v[198:201], v[80:83]
	v_mfma_f32_16x16x32_bf16 v[80:83], v[104:107], v[204:207], v[88:91]
	v_mfma_f32_16x16x32_bf16 v[64:67], v[104:107], v[176:179], v[64:67]
	v_mfma_f32_16x16x32_bf16 v[68:71], v[112:115], v[176:179], v[68:71]
	v_mfma_f32_16x16x32_bf16 v[72:75], v[104:107], v[186:189], v[72:75]
	v_mfma_f32_16x16x32_bf16 v[76:79], v[112:115], v[186:189], v[76:79]
	v_mfma_f32_16x16x32_bf16 v[88:91], v[108:111], v[208:211], v[80:83]
	v_mfma_f32_16x16x32_bf16 v[80:83], v[112:115], v[204:207], v[92:95]
	v_mfma_f32_16x16x32_bf16 v[64:67], v[108:111], v[180:183], v[64:67]
	v_mfma_f32_16x16x32_bf16 v[68:71], v[116:119], v[180:183], v[68:71]
	v_mfma_f32_16x16x32_bf16 v[72:75], v[108:111], v[190:193], v[72:75]
	v_mfma_f32_16x16x32_bf16 v[76:79], v[116:119], v[190:193], v[76:79]
	v_mfma_f32_16x16x32_bf16 v[92:95], v[116:119], v[208:211], v[80:83]
	v_mfma_f32_16x16x32_bf16 v[48:51], v[168:171], v[194:197], v[48:51]
	v_mfma_f32_16x16x32_bf16 v[80:83], v[120:123], v[176:179], v[96:99]
	v_mfma_f32_16x16x32_bf16 v[32:35], v[168:171], v[176:179], v[32:35]
	v_mfma_f32_16x16x32_bf16 v[36:39], v[120:123], v[186:189], v[36:39]
	v_mfma_f32_16x16x32_bf16 v[40:43], v[168:171], v[186:189], v[40:43]
	v_mfma_f32_16x16x32_bf16 v[44:47], v[120:123], v[194:197], v[44:47]
	v_mfma_f32_16x16x32_bf16 v[176:179], v[172:175], v[198:201], v[48:51]
	v_mfma_f32_16x16x32_bf16 v[48:51], v[120:123], v[204:207], v[52:55]
	v_mfma_f32_16x16x32_bf16 v[96:99], v[124:127], v[180:183], v[80:83]
	v_mfma_f32_16x16x32_bf16 v[32:35], v[172:175], v[180:183], v[32:35]
	v_mfma_f32_16x16x32_bf16 v[36:39], v[124:127], v[190:193], v[36:39]
	v_mfma_f32_16x16x32_bf16 v[40:43], v[172:175], v[190:193], v[40:43]
	v_mfma_f32_16x16x32_bf16 v[44:47], v[124:127], v[198:201], v[44:47]
	v_mfma_f32_16x16x32_bf16 v[180:183], v[124:127], v[208:211], v[48:51]
	v_mfma_f32_16x16x32_bf16 v[48:51], v[168:171], v[204:207], v[56:59]
	v_mfma_f32_16x16x32_bf16 v[186:189], v[172:175], v[208:211], v[48:51]
	s_setprio 0
	s_barrier
	s_mov_b64 s[28:29], s[30:31]
	s_mov_b32 m0, s59
	s_nop 2
	ds_read_b128 v[48:51], v143 offset:16384
	ds_read_b128 v[52:55], v143 offset:17408
	ds_read_b128 v[56:59], v143 offset:18432
	ds_read_b128 v[80:83], v143 offset:19456
	ds_read_b128 v[84:87], v143 offset:20480
	ds_read_b128 v[190:193], v143 offset:21504
	ds_read_b128 v[194:197], v143 offset:22528
	ds_read_b128 v[198:201], v143 offset:23552
	s_nop 0
	v_lshl_add_u64 v[202:203], s[28:29], 0, v[132:133]
	global_load_lds_dwordx4 v[202:203], off
	v_lshl_add_u64 v[202:203], s[28:29], 0, v[128:129]
	s_add_u32 s28, s30, 0x4000
	s_mov_b32 m0, s19
	s_addc_u32 s29, s31, 0
	global_load_lds_dwordx4 v[202:203], off
	s_mov_b32 m0, s56
	v_lshl_add_u64 v[202:203], s[28:29], 0, v[132:133]
	global_load_lds_dwordx4 v[202:203], off
	v_lshl_add_u64 v[202:203], s[28:29], 0, v[128:129]
	s_mov_b32 m0, s57
	s_mov_b64 s[28:29], s[36:37]
	global_load_lds_dwordx4 v[202:203], off
	s_mov_b32 m0, s44
	v_lshl_add_u64 v[202:203], s[28:29], 0, v[134:135]
	global_load_lds_dwordx4 v[202:203], off
	v_lshl_add_u64 v[202:203], s[28:29], 0, v[130:131]
	s_mov_b32 m0, s45
	s_nop 0
	global_load_lds_dwordx4 v[202:203], off
	s_waitcnt vmcnt(8)
	s_waitcnt lgkmcnt(0)
	s_barrier
	s_setprio 1
	v_mfma_f32_16x16x32_bf16 v[0:3], v[104:107], v[194:197], v[0:3]
	v_mfma_f32_16x16x32_bf16 v[4:7], v[112:115], v[194:197], v[4:7]
	v_mfma_f32_16x16x32_bf16 v[144:147], v[104:107], v[48:51], v[144:147]
	v_mfma_f32_16x16x32_bf16 v[148:151], v[112:115], v[48:51], v[148:151]
	v_mfma_f32_16x16x32_bf16 v[152:155], v[104:107], v[56:59], v[152:155]
	v_mfma_f32_16x16x32_bf16 v[156:159], v[112:115], v[56:59], v[156:159]
	v_mfma_f32_16x16x32_bf16 v[160:163], v[104:107], v[84:87], v[160:163]
	v_mfma_f32_16x16x32_bf16 v[164:167], v[112:115], v[84:87], v[164:167]
	v_mfma_f32_16x16x32_bf16 v[0:3], v[108:111], v[198:201], v[0:3]
	v_mfma_f32_16x16x32_bf16 v[4:7], v[116:119], v[198:201], v[4:7]
	v_mfma_f32_16x16x32_bf16 v[144:147], v[108:111], v[52:55], v[144:147]
	v_mfma_f32_16x16x32_bf16 v[148:151], v[116:119], v[52:55], v[148:151]
	v_mfma_f32_16x16x32_bf16 v[152:155], v[108:111], v[80:83], v[152:155]
	v_mfma_f32_16x16x32_bf16 v[156:159], v[116:119], v[80:83], v[156:159]
	v_mfma_f32_16x16x32_bf16 v[160:163], v[108:111], v[190:193], v[160:163]
	v_mfma_f32_16x16x32_bf16 v[164:167], v[116:119], v[190:193], v[164:167]
	v_mfma_f32_16x16x32_bf16 v[24:27], v[120:123], v[56:59], v[24:27]
	v_mfma_f32_16x16x32_bf16 v[204:207], v[124:127], v[80:83], v[24:27]
	v_mfma_f32_16x16x32_bf16 v[24:27], v[168:171], v[56:59], v[28:31]
	v_mfma_f32_16x16x32_bf16 v[8:11], v[120:123], v[48:51], v[8:11]
	v_mfma_f32_16x16x32_bf16 v[12:15], v[168:171], v[48:51], v[12:15]
	v_mfma_f32_16x16x32_bf16 v[208:211], v[172:175], v[80:83], v[24:27]
	v_mfma_f32_16x16x32_bf16 v[24:27], v[120:123], v[84:87], v[60:63]
	v_mfma_f32_16x16x32_bf16 v[16:19], v[120:123], v[194:197], v[16:19]
	v_mfma_f32_16x16x32_bf16 v[8:11], v[124:127], v[52:55], v[8:11]
	v_mfma_f32_16x16x32_bf16 v[12:15], v[172:175], v[52:55], v[12:15]
	v_mfma_f32_16x16x32_bf16 v[220:223], v[124:127], v[190:193], v[24:27]
	v_mfma_f32_16x16x32_bf16 v[24:27], v[168:171], v[84:87], v[100:103]
	v_mfma_f32_16x16x32_bf16 v[224:227], v[124:127], v[198:201], v[16:19]
	v_mfma_f32_16x16x32_bf16 v[16:19], v[168:171], v[194:197], v[20:23]
	v_mfma_f32_16x16x32_bf16 v[190:193], v[172:175], v[190:193], v[24:27]
	v_mfma_f32_16x16x32_bf16 v[168:171], v[172:175], v[198:201], v[16:19]
	s_setprio 0
	s_barrier
; #define PG8_STAGE(bufoff, gbase, voff) do { unsigned long long _gb = (unsigned long long)(gbase); asm volatile("" : "+s"(_gb)); _Pragma("unroll") for (int _i = 0; _i < 2; ++_i) \
;         __builtin_amdgcn_global_load_lds((const GAS unsigned*)((const GAS char*)_gb + (voff)[_i]), (LAS unsigned*)(lds + (bufoff) + ldsw + _i * 8192), 16, 0, 0); } while (0)
; #define PG8_LDA(dst, b, h) do { _Pragma("unroll") for (int m = 0; m < 4; ++m) _Pragma("unroll") for (int k = 0; k < 2; ++k) dst[m][k] = *(const LAS bf16x8*)(lds + PG8_SA(b, h) + aoff + m * 2048 + k * 1024); } while (0)
; #define PG8_LDB(dst, b, h) do { _Pragma("unroll") for (int n = 0; n < 2; ++n) _Pragma("unroll") for (int k = 0; k < 2; ++k) dst[n][k] = *(const LAS bf16x8*)(lds + PG8_SB(b, h) + boff + n * 2048 + k * 1024); } while (0)
; #define PG8_WAIT_V(n) asm volatile("s_waitcnt vmcnt(" #n ")" ::: "memory")
; #define PG8_WAIT_L(n) asm volatile("s_waitcnt lgkmcnt(" #n ")" ::: "memory")
; #define PG8_BAR __builtin_amdgcn_s_barrier()
; #define PG8_SCHED __builtin_amdgcn_sched_barrier(0)
; template <class Epi, bool ALIGN_EPI>
; __device__ __forceinline__ void gemm_phase(LAS unsigned char* lds, const Gemm g, const StaticOrder& S, const Epi& E, const int wid) {
;     ...
;             PG8_LDB(B0, 0, 0); PG8_LDB(B1, 0, 1); PG8_SCHED; PG8_LDA(At, 0, 0); PG8_STAGE(PG8_SA(1, 1), a1 + hstep, voffA);
;             PG8_WAIT_V(8); PG8_WAIT_L(0); PG8_BAR; PG8_MMA(0, 0, At, B0); PG8_MMA(0, 1, At, B1); PG8_BAR; PG8_SCHED;
;             PG8_LDA(At, 0, 1); PG8_STAGE(PG8_SB(0, 0), b2, voffB); PG8_STAGE(PG8_SB(0, 1), b2 + hstepB, voffB); PG8_STAGE(PG8_SA(0, 0), a2, voffA);
;             PG8_WAIT_V(8); PG8_WAIT_L(0); PG8_BAR; PG8_MMA(1, 0, At, B0); PG8_MMA(1, 1, At, B1); PG8_BAR; PG8_SCHED;
;             PG8_LDB(B0, 1, 0); PG8_LDB(B1, 1, 1); PG8_SCHED; PG8_LDA(At, 1, 0); PG8_STAGE(PG8_SA(0, 1), a2 + hstep, voffA);
;             PG8_WAIT_V(8); PG8_WAIT_L(0); PG8_BAR; PG8_MMA(0, 0, At, B0); PG8_MMA(0, 1, At, B1); PG8_BAR; PG8_SCHED;
;             PG8_LDA(At, 1, 1); PG8_STAGE(PG8_SB(1, 0), b3, voffB); PG8_STAGE(PG8_SB(1, 1), b3 + hstepB, voffB); PG8_STAGE(PG8_SA(1, 0), a3, voffA);
;             PG8_WAIT_V(8); PG8_WAIT_L(0); PG8_BAR; PG8_MMA(1, 0, At, B0); PG8_MMA(1, 1, At, B1); PG8_BAR; PG8_SCHED;
;         }
;         if constexpr (ALIGN_EPI) { if (wr == 0) PG8_BAR; }
	ds_read_b128 v[104:107], v184
	ds_read_b128 v[108:111], v184 offset:1024
	ds_read_b128 v[172:175], v184 offset:2048
	ds_read_b128 v[194:197], v184 offset:3072
	ds_read_b128 v[198:201], v236
	ds_read_b128 v[228:231], v236 offset:1024
	ds_read_b128 v[232:235], v236 offset:2048
	ds_read_b128 v[236:239], v236 offset:3072
	s_add_u32 s28, s36, 0x10000
	s_addc_u32 s29, s37, 0
	s_mov_b32 m0, s46
	ds_read_b128 v[24:27], v143 offset:32768
	ds_read_b128 v[28:31], v143 offset:33792
	ds_read_b128 v[56:59], v143 offset:34816
	ds_read_b128 v[60:63], v143 offset:35840
	ds_read_b128 v[100:103], v143 offset:36864
	ds_read_b128 v[240:243], v143 offset:37888
	ds_read_b128 v[244:247], v143 offset:38912
	ds_read_b128 v[248:251], v143 offset:39936
	s_nop 0
	v_lshl_add_u64 v[16:17], s[28:29], 0, v[134:135]
	global_load_lds_dwordx4 v[16:17], off
	v_lshl_add_u64 v[16:17], s[28:29], 0, v[130:131]
	s_mov_b32 m0, s47
	s_nop 0
	global_load_lds_dwordx4 v[16:17], off
	s_waitcnt vmcnt(8)
	s_waitcnt lgkmcnt(0)
	s_barrier
	s_setprio 1
	v_mfma_f32_16x16x32_bf16 v[16:19], v[104:107], v[24:27], v[64:67]
	v_mfma_f32_16x16x32_bf16 v[112:115], v[108:111], v[28:31], v[16:19]
	v_mfma_f32_16x16x32_bf16 v[16:19], v[172:175], v[24:27], v[68:71]
	v_mfma_f32_16x16x32_bf16 v[116:119], v[194:197], v[28:31], v[16:19]
	v_mfma_f32_16x16x32_bf16 v[16:19], v[104:107], v[56:59], v[72:75]
	v_mfma_f32_16x16x32_bf16 v[80:83], v[108:111], v[60:63], v[16:19]
	v_mfma_f32_16x16x32_bf16 v[16:19], v[172:175], v[56:59], v[76:79]
	v_mfma_f32_16x16x32_bf16 v[84:87], v[194:197], v[60:63], v[16:19]
	v_mfma_f32_16x16x32_bf16 v[16:19], v[104:107], v[100:103], v[212:215]
	v_mfma_f32_16x16x32_bf16 v[48:51], v[108:111], v[240:243], v[16:19]
	v_mfma_f32_16x16x32_bf16 v[16:19], v[172:175], v[100:103], v[216:219]
	v_mfma_f32_16x16x32_bf16 v[52:55], v[194:197], v[240:243], v[16:19]
	v_mfma_f32_16x16x32_bf16 v[16:19], v[104:107], v[244:247], v[88:91]
	v_mfma_f32_16x16x32_bf16 v[20:23], v[172:175], v[244:247], v[92:95]
	v_mfma_f32_16x16x32_bf16 v[16:19], v[108:111], v[248:251], v[16:19]
	v_mfma_f32_16x16x32_bf16 v[20:23], v[194:197], v[248:251], v[20:23]
	v_mfma_f32_16x16x32_bf16 v[64:67], v[198:201], v[24:27], v[96:99]
	v_mfma_f32_16x16x32_bf16 v[24:27], v[232:235], v[24:27], v[32:35]
	v_mfma_f32_16x16x32_bf16 v[124:127], v[236:239], v[28:31], v[24:27]
	v_mfma_f32_16x16x32_bf16 v[24:27], v[198:201], v[56:59], v[36:39]
	v_mfma_f32_16x16x32_bf16 v[88:91], v[228:231], v[60:63], v[24:27]
	v_mfma_f32_16x16x32_bf16 v[24:27], v[232:235], v[56:59], v[40:43]
	v_mfma_f32_16x16x32_bf16 v[92:95], v[236:239], v[60:63], v[24:27]
	v_mfma_f32_16x16x32_bf16 v[24:27], v[198:201], v[100:103], v[44:47]
	v_mfma_f32_16x16x32_bf16 v[56:59], v[228:231], v[240:243], v[24:27]
	v_mfma_f32_16x16x32_bf16 v[24:27], v[232:235], v[100:103], v[176:179]
	v_mfma_f32_16x16x32_bf16 v[120:123], v[228:231], v[28:31], v[64:67]
	v_mfma_f32_16x16x32_bf16 v[60:63], v[236:239], v[240:243], v[24:27]
	v_mfma_f32_16x16x32_bf16 v[24:27], v[198:201], v[244:247], v[180:183]
	v_mfma_f32_16x16x32_bf16 v[28:31], v[232:235], v[244:247], v[186:189]
	v_mfma_f32_16x16x32_bf16 v[24:27], v[228:231], v[248:251], v[24:27]
	v_mfma_f32_16x16x32_bf16 v[28:31], v[236:239], v[248:251], v[28:31]
	s_setprio 0
	s_barrier
	s_add_u32 s28, s30, 0x80
	s_addc_u32 s29, s31, 0
	s_mov_b32 m0, s63
	ds_read_b128 v[40:43], v143 offset:49152
	ds_read_b128 v[44:47], v143 offset:50176
	ds_read_b128 v[76:79], v143 offset:51200
	ds_read_b128 v[176:179], v143 offset:52224
	ds_read_b128 v[180:183], v143 offset:53248
	ds_read_b128 v[186:189], v143 offset:54272
	ds_read_b128 v[212:215], v143 offset:55296
	ds_read_b128 v[216:219], v143 offset:56320
	s_nop 0
	v_lshl_add_u64 v[32:33], s[28:29], 0, v[132:133]
	global_load_lds_dwordx4 v[32:33], off
	v_lshl_add_u64 v[32:33], s[28:29], 0, v[128:129]
	s_add_u32 s28, s30, 0x4080
	s_mov_b32 m0, s40
	s_addc_u32 s29, s31, 0
	global_load_lds_dwordx4 v[32:33], off
	s_mov_b32 m0, s41
	v_lshl_add_u64 v[32:33], s[28:29], 0, v[132:133]
	global_load_lds_dwordx4 v[32:33], off
	v_lshl_add_u64 v[32:33], s[28:29], 0, v[128:129]
	s_mov_b32 m0, s58
	s_nop 0
	global_load_lds_dwordx4 v[32:33], off
	s_mov_b32 m0, s50
	v_lshl_add_u64 v[32:33], s[34:35], 0, v[134:135]
	global_load_lds_dwordx4 v[32:33], off
	v_lshl_add_u64 v[32:33], s[34:35], 0, v[130:131]
	s_mov_b32 m0, s51
	s_nop 0
	global_load_lds_dwordx4 v[32:33], off
	s_waitcnt vmcnt(8)
	s_waitcnt lgkmcnt(0)
	s_barrier
	s_setprio 1
	v_mfma_f32_16x16x32_bf16 v[32:35], v[104:107], v[40:43], v[144:147]
	v_mfma_f32_16x16x32_bf16 v[96:99], v[108:111], v[44:47], v[32:35]
	v_mfma_f32_16x16x32_bf16 v[32:35], v[172:175], v[40:43], v[148:151]
	v_mfma_f32_16x16x32_bf16 v[100:103], v[194:197], v[44:47], v[32:35]
	v_mfma_f32_16x16x32_bf16 v[32:35], v[104:107], v[76:79], v[152:155]
	v_mfma_f32_16x16x32_bf16 v[64:67], v[108:111], v[176:179], v[32:35]
	v_mfma_f32_16x16x32_bf16 v[32:35], v[172:175], v[76:79], v[156:159]
	v_mfma_f32_16x16x32_bf16 v[68:71], v[194:197], v[176:179], v[32:35]
	v_mfma_f32_16x16x32_bf16 v[32:35], v[104:107], v[180:183], v[160:163]
	v_mfma_f32_16x16x32_bf16 v[36:39], v[172:175], v[180:183], v[164:167]
	v_mfma_f32_16x16x32_bf16 v[0:3], v[104:107], v[212:215], v[0:3]
	v_mfma_f32_16x16x32_bf16 v[4:7], v[172:175], v[212:215], v[4:7]
	v_mfma_f32_16x16x32_bf16 v[32:35], v[108:111], v[186:189], v[32:35]
	v_mfma_f32_16x16x32_bf16 v[36:39], v[194:197], v[186:189], v[36:39]
	v_mfma_f32_16x16x32_bf16 v[0:3], v[108:111], v[216:219], v[0:3]
	v_mfma_f32_16x16x32_bf16 v[4:7], v[194:197], v[216:219], v[4:7]
	v_mfma_f32_16x16x32_bf16 v[8:11], v[198:201], v[40:43], v[8:11]
	v_mfma_f32_16x16x32_bf16 v[104:107], v[228:231], v[44:47], v[8:11]
	v_mfma_f32_16x16x32_bf16 v[8:11], v[232:235], v[40:43], v[12:15]
	v_mfma_f32_16x16x32_bf16 v[108:111], v[236:239], v[44:47], v[8:11]
	v_mfma_f32_16x16x32_bf16 v[8:11], v[198:201], v[76:79], v[204:207]
	v_mfma_f32_16x16x32_bf16 v[72:75], v[228:231], v[176:179], v[8:11]
	v_mfma_f32_16x16x32_bf16 v[8:11], v[232:235], v[76:79], v[208:211]
	v_mfma_f32_16x16x32_bf16 v[76:79], v[236:239], v[176:179], v[8:11]
	v_mfma_f32_16x16x32_bf16 v[8:11], v[198:201], v[180:183], v[220:223]
	v_mfma_f32_16x16x32_bf16 v[40:43], v[228:231], v[186:189], v[8:11]
	v_mfma_f32_16x16x32_bf16 v[8:11], v[232:235], v[180:183], v[190:193]
	v_mfma_f32_16x16x32_bf16 v[44:47], v[236:239], v[186:189], v[8:11]
	v_mfma_f32_16x16x32_bf16 v[8:11], v[198:201], v[212:215], v[224:227]
	v_mfma_f32_16x16x32_bf16 v[12:15], v[232:235], v[212:215], v[168:171]
	v_mfma_f32_16x16x32_bf16 v[8:11], v[228:231], v[216:219], v[8:11]
	v_mfma_f32_16x16x32_bf16 v[12:15], v[236:239], v[216:219], v[12:15]
	s_setprio 0
	s_barrier
	s_andn2_b64 vcc, exec, s[84:85]
	s_cbranch_vccnz .LBB0_490
	s_barrier

; __device__ __forceinline__ int lane_id() { return (int)__builtin_amdgcn_mbcnt_hi(~0u, __builtin_amdgcn_mbcnt_lo(~0u, 0u)); }
; __global__ void __launch_bounds__(NWAVES * 64, 2) fwd(Args args) {
;     ...
;         unsigned char* wsp = ws; asm volatile("" : "+s"(wsp)); const unsigned char* tbl = wsp + WS_PTRS;
;         const float* ret_gn = ld_uptr(tbl, 4); const float* diff_qn = ld_uptr(tbl, 5); const float* diff_kn = ld_uptr(tbl, 6); const float* lq1 = ld_uptr(tbl, 7); const float* lk1 = ld_uptr(tbl, 8);
;         const float* lq2 = ld_uptr(tbl, 9); const float* lk2 = ld_uptr(tbl, 10); const float* subln = ld_uptr(tbl, 11);
;         bf16_t* Z = (bf16_t*)(wsp + WS_Z); bf16_t* MIX = (bf16_t*)(wsp + WS_MIX);
;         int lane2 = lane_id(); asm volatile("" : "+v"(lane2));
;         const float d1 = wave_sum(lq1[lane2] * lk1[lane2]), d2 = wave_sum(lq2[lane2] * lk2[lane2]);
;         float lam; { float lv = __expf(d1) - __expf(d2) + 0.2f; asm volatile("" : "+v"(lv)); lam = __uint_as_float(__builtin_amdgcn_readfirstlane(__float_as_uint(lv))); }
;         const float mq = wave_max(fabsf(diff_qn[lane2])), mk = wave_max(fabsf(diff_kn[lane2]));
;         float shift; { float sv = 11.541560327111707f * mq * mk; asm volatile("" : "+v"(sv)); shift = __uint_as_float(__builtin_amdgcn_readfirstlane(__float_as_uint(sv))); }
;         for (int pi = vcu; pi < 256; pi += G) {
.LBB0_561:
	s_cmp_lt_i32 s82, 3
	s_cselect_b64 s[2:3], -1, 0
	v_writelane_b32 v254, s2, 2
	s_and_b64 s[0:1], s[2:3], s[0:1]
	s_andn2_b64 vcc, exec, s[0:1]
	v_writelane_b32 v254, s3, 3
	s_cbranch_vccnz .LBB0_654
	v_writelane_b32 v254, s96, 4
	v_mov_b32_e32 v181, 0
	v_mbcnt_lo_u32_b32 v13, -1, 0
	v_writelane_b32 v254, s97, 5
	v_writelane_b32 v254, s94, 6
	v_writelane_b32 v254, s93, 7
	v_writelane_b32 v254, s92, 8
	v_writelane_b32 v254, s90, 9
	v_mbcnt_hi_u32_b32 v183, -1, v13
	v_mov_b32_e32 v12, 0x20000
	v_writelane_b32 v254, s91, 10
	v_writelane_b32 v254, s87, 11
	v_writelane_b32 v254, s88, 12
	v_mov_b32_e32 v16, v183
	s_mov_b32 s27, 0
	v_writelane_b32 v254, s89, 13
	v_writelane_b32 v254, s86, 14
	v_writelane_b32 v254, s84, 15
	s_nop 1
	v_writelane_b32 v254, s85, 16
	v_writelane_b32 v254, s79, 17
	v_writelane_b32 v254, s77, 18
	v_writelane_b32 v254, s80, 19
	s_mov_b64 s[0:1], s[80:81]
	s_add_u32 s2, s0, 0x20020
	s_addc_u32 s3, s1, 0
	global_load_dwordx4 v[0:3], v181, s[2:3] offset:16
	global_load_dwordx4 v[4:7], v181, s[2:3] offset:32
	global_load_dwordx4 v[8:11], v181, s[2:3] offset:48
	v_writelane_b32 v254, s81, 20
	global_load_dwordx4 v[12:15], v12, s[0:1] offset:32
	v_writelane_b32 v254, s82, 21
	v_ashrrev_i32_e32 v17, 31, v16
	v_lshlrev_b64 v[16:17], 2, v[16:17]
	v_writelane_b32 v254, s83, 22
	s_cmpk_gt_i32 s95, 0xff
	s_waitcnt vmcnt(0)
	v_readfirstlane_b32 s3, v3
	v_readfirstlane_b32 s2, v2
	v_readfirstlane_b32 s5, v5
	v_readfirstlane_b32 s4, v4
	v_readfirstlane_b32 s7, v7
	v_readfirstlane_b32 s6, v6
	v_readfirstlane_b32 s9, v9
	v_readfirstlane_b32 s8, v8
	v_lshl_add_u64 v[2:3], s[2:3], 0, v[16:17]
	v_lshl_add_u64 v[4:5], s[4:5], 0, v[16:17]
	v_lshl_add_u64 v[6:7], s[6:7], 0, v[16:17]
	v_lshl_add_u64 v[8:9], s[8:9], 0, v[16:17]
	flat_load_dword v18, v[2:3]
	flat_load_dword v19, v[4:5]
	flat_load_dword v20, v[6:7]
	flat_load_dword v21, v[8:9]
	v_and_b32_e32 v2, 64, v183
	v_xor_b32_e32 v3, 1, v183
	v_add_u32_e32 v2, 64, v2
	v_cmp_lt_i32_e32 vcc, v3, v2
	v_xor_b32_e32 v4, 2, v183
	v_xor_b32_e32 v5, 4, v183
	v_cndmask_b32_e32 v3, v183, v3, vcc
	v_lshlrev_b32_e32 v9, 2, v3
	v_cmp_lt_i32_e32 vcc, v4, v2
	v_xor_b32_e32 v6, 8, v183
	v_xor_b32_e32 v7, 16, v183
	v_cndmask_b32_e32 v4, v183, v4, vcc
	v_lshlrev_b32_e32 v4, 2, v4
	v_cmp_lt_i32_e32 vcc, v5, v2
	v_xor_b32_e32 v8, 32, v183
	v_readfirstlane_b32 s5, v1
	v_cndmask_b32_e32 v5, v183, v5, vcc
	v_lshlrev_b32_e32 v5, 2, v5
	v_cmp_lt_i32_e32 vcc, v6, v2
	v_readfirstlane_b32 s3, v15
	v_readfirstlane_b32 s2, v14
	v_cndmask_b32_e32 v6, v183, v6, vcc
	v_lshlrev_b32_e32 v6, 2, v6
	v_cmp_lt_i32_e32 vcc, v7, v2
	v_readfirstlane_b32 s4, v0
	v_readfirstlane_b32 s85, v11
	v_cndmask_b32_e32 v7, v183, v7, vcc
	v_lshlrev_b32_e32 v7, 2, v7
	v_cmp_lt_i32_e32 vcc, v8, v2
	v_readfirstlane_b32 s84, v10
	s_waitcnt vmcnt(0) lgkmcnt(0)
	v_mul_f32_e32 v3, v18, v19
	ds_bpermute_b32 v3, v9, v3
	v_mul_f32_e32 v22, v20, v21
	ds_bpermute_b32 v22, v9, v22
	v_cndmask_b32_e32 v2, v183, v8, vcc
	v_lshlrev_b32_e32 v8, 2, v2
	s_waitcnt lgkmcnt(1)
	v_fmac_f32_e32 v3, v18, v19
	ds_bpermute_b32 v18, v4, v3
	s_waitcnt lgkmcnt(1)
	v_fmac_f32_e32 v22, v20, v21
	ds_bpermute_b32 v19, v4, v22
	s_waitcnt lgkmcnt(1)
	v_add_f32_e32 v3, v3, v18
	s_waitcnt lgkmcnt(0)
	v_add_f32_e32 v18, v22, v19
	ds_bpermute_b32 v19, v5, v3
	ds_bpermute_b32 v20, v5, v18
	s_waitcnt lgkmcnt(1)
	v_add_f32_e32 v3, v3, v19
	s_waitcnt lgkmcnt(0)
	v_add_f32_e32 v18, v18, v20
	ds_bpermute_b32 v19, v6, v3
	ds_bpermute_b32 v20, v6, v18
	s_waitcnt lgkmcnt(1)
	v_add_f32_e32 v3, v3, v19
	s_waitcnt lgkmcnt(0)
	v_add_f32_e32 v18, v18, v20
	ds_bpermute_b32 v19, v7, v3
	ds_bpermute_b32 v20, v7, v18
	s_waitcnt lgkmcnt(1)
	v_add_f32_e32 v2, v3, v19
	s_waitcnt lgkmcnt(0)
	v_add_f32_e32 v3, v18, v20
	ds_bpermute_b32 v18, v8, v2
	ds_bpermute_b32 v19, v8, v3
	s_waitcnt lgkmcnt(1)
	v_add_f32_e32 v1, v2, v18
	s_waitcnt lgkmcnt(0)
	v_add_f32_e32 v2, v3, v19
	v_mul_f32_e32 v1, 0x3fb8aa3b, v1
	v_mul_f32_e32 v2, 0x3fb8aa3b, v2
	v_exp_f32_e32 v14, v1
	v_exp_f32_e32 v15, v2
	v_lshl_add_u64 v[0:1], s[2:3], 0, v[16:17]
	v_lshl_add_u64 v[2:3], s[4:5], 0, v[16:17]
	v_readfirstlane_b32 s2, v13
	v_sub_f32_e32 v14, v14, v15
	v_add_f32_e32 v14, 0x3e4ccccd, v14
	flat_load_dword v15, v[0:1]
	flat_load_dword v16, v[2:3]
	v_writelane_b32 v254, s2, 23
	v_readfirstlane_b32 s2, v12
	v_readfirstlane_b32 s28, v14
	s_waitcnt vmcnt(0) lgkmcnt(0)
	v_and_b32_e32 v0, 0x7fffffff, v15
	v_and_b32_e32 v1, 0x7fffffff, v16
	ds_bpermute_b32 v0, v9, v0
	ds_bpermute_b32 v1, v9, v1
	v_max_f32_e64 v2, |v15|, |v15|
	v_max_f32_e64 v3, |v16|, |v16|
	v_writelane_b32 v254, s2, 24
	s_waitcnt lgkmcnt(1)
	v_max_f32_e32 v0, v0, v0
	s_waitcnt lgkmcnt(0)
	v_max_f32_e32 v1, v1, v1
	v_max_f32_e32 v0, v2, v0
	v_max_f32_e32 v1, v3, v1
	ds_bpermute_b32 v2, v4, v0
	ds_bpermute_b32 v3, v4, v1
	s_waitcnt lgkmcnt(1)
	v_max_f32_e32 v2, v2, v2
	s_waitcnt lgkmcnt(0)
	v_max_f32_e32 v3, v3, v3
	v_max_f32_e32 v0, v0, v2
	v_max_f32_e32 v1, v1, v3
	ds_bpermute_b32 v2, v5, v0
	ds_bpermute_b32 v3, v5, v1
	s_waitcnt lgkmcnt(1)
	v_max_f32_e32 v2, v2, v2
	s_waitcnt lgkmcnt(0)
	v_max_f32_e32 v3, v3, v3
	v_max_f32_e32 v0, v0, v2
	v_max_f32_e32 v1, v1, v3
	ds_bpermute_b32 v2, v6, v0
	ds_bpermute_b32 v3, v6, v1
	s_waitcnt lgkmcnt(1)
	v_max_f32_e32 v2, v2, v2
	s_waitcnt lgkmcnt(0)
	v_max_f32_e32 v3, v3, v3
	v_max_f32_e32 v0, v0, v2
	v_max_f32_e32 v1, v1, v3
	ds_bpermute_b32 v2, v7, v0
	ds_bpermute_b32 v3, v7, v1
	s_waitcnt lgkmcnt(1)
	v_max_f32_e32 v2, v2, v2
	s_waitcnt lgkmcnt(0)
	v_max_f32_e32 v3, v3, v3
	v_max_f32_e32 v0, v0, v2
	v_max_f32_e32 v1, v1, v3
	ds_bpermute_b32 v2, v8, v0
	ds_bpermute_b32 v3, v8, v1
	s_waitcnt lgkmcnt(1)
	v_max_f32_e32 v2, v2, v2
	s_waitcnt lgkmcnt(0)
	v_max_f32_e32 v3, v3, v3
	v_max_f32_e32 v0, v0, v2
	v_max_f32_e32 v1, v1, v3
	v_mul_f32_e32 v0, 0x4138aa3b, v0
	v_mul_f32_e32 v0, v0, v1
	s_nop 0
	v_readfirstlane_b32 s2, v0
	s_cbranch_scc1 .LBB0_653
; #define LAS __attribute__((address_space(3)))
; __device__ __forceinline__ int lane_id() { return (int)__builtin_amdgcn_mbcnt_hi(~0u, __builtin_amdgcn_mbcnt_lo(~0u, 0u)); }
; template <bool DIFF>
; __device__ __forceinline__ void attn_item(LAS unsigned char* lds, const bf16_t* Z, bf16_t* MIX, int b, int h, int t, float lam, float shift, const float* gain, int tid, int wid, int lane) {
;     constexpr int NC = DIFF ? 2 : 1;
;     lane = lane_id(); asm volatile("" : "+v"(lane)); tid = wid * 64 + lane;
;     const int q16 = lane & 15, quad = lane >> 4;
;     const int row0 = b * SEQ + 128 * t + 16 * wid;
;     const int cq = 2 * t + (wid >> 2), nkt = 2 * t + 2;
;     const int qcol = DIFF ? (3072 + 128 * h) : (64 * h);
;     const int kcol = DIFF ? (4096 + 128 * h) : (512 + 64 * h);
;     const int vcol = DIFF ? (5120 + 128 * h) : (1024 + 128 * h);
;     const int gcol = DIFF ? (6144 + 128 * h) : (2048 + 128 * h);
;     const float lg = lg2gamma(h);
;     bf16x8 qf[NC][2];
;     { const bf16_t* qrow = Z + (size_t)(row0 + q16) * DIN + qcol;
; #pragma unroll
;       for (int c = 0; c < NC; ++c)
; #pragma unroll
;           for (int ds = 0; ds < 2; ++ds) qf[c][ds] = __builtin_nontemporal_load((const bf16x8*)(qrow + 64 * c + 32 * ds + 8 * quad)); }
; __global__ void __launch_bounds__(NWAVES * 64, 2) fwd(Args args) {
;     ...
;         for (int pi = vcu; pi < 256; pi += G) {
;             const int bh = pi >> 3, tp = pi & 7, b = bh >> 3, h = bh & 7;
;             attn_item<true>(lds, Z, MIX, b, h, 15 - tp, lam, shift, subln, 0, wid, 0);
	s_add_u32 s30, s0, 0x5300000
	s_addc_u32 s31, s1, 0
	s_add_u32 s88, s0, 0x2f00000
	s_addc_u32 s89, s1, 0
	s_lshl_b32 s29, s60, 4
	s_lshl_b32 s34, s60, 3
	s_lshl_b32 s35, s60, 2
	s_add_i32 s90, s33, 0
	v_sub_f32_e64 v0, 0, s2
	s_add_u32 s2, s0, 0x54c2800
	v_writelane_b32 v254, s2, 25
	s_addc_u32 s2, s1, 0
	v_writelane_b32 v254, s2, 26
	s_lshl_b32 s2, s95, 5
	s_lshl_b32 s3, s78, 5
	v_writelane_b32 v254, s3, 27
	s_add_u32 s3, s0, 0x54c0800
	v_writelane_b32 v254, s3, 28
	s_addc_u32 s3, s1, 0
	v_writelane_b32 v254, s3, 29
	s_add_u32 s0, s0, 0x54c0400
	v_writelane_b32 v254, s0, 30
	s_addc_u32 s0, s1, 0
	v_writelane_b32 v254, s0, 31
	v_writelane_b32 v254, s78, 32
	v_writelane_b32 v254, s66, 33
	v_writelane_b32 v254, s84, 34
	s_add_i32 s17, s90, 0x2000
	s_add_i32 s38, s90, 0x6000
	v_writelane_b32 v254, s85, 35
	v_writelane_b32 v254, s28, 36
	v_writelane_b32 v254, s30, 37
	s_add_i32 s39, s90, 0x8000
	s_add_i32 s18, s90, 0xa000
	v_writelane_b32 v254, s31, 38
	v_writelane_b32 v254, s88, 39
	s_add_i32 s40, s90, 0xc000
	s_add_i32 s41, s90, 0xe000
	v_writelane_b32 v254, s89, 40
	v_writelane_b32 v254, s29, 41
	v_writelane_b32 v254, s34, 42
	v_writelane_b32 v254, s35, 43
	v_writelane_b32 v254, s17, 44
	v_writelane_b32 v254, s38, 45
	v_writelane_b32 v254, s39, 46
	v_writelane_b32 v254, s18, 47
	v_writelane_b32 v254, s40, 48
	s_add_i32 s43, s90, 0x4000
	v_writelane_b32 v254, s41, 49
	v_mov_b32_e32 v1, v0
	v_mov_b32_e32 v2, v0
	v_mov_b32_e32 v3, v0
	s_movk_i32 s36, 0x3800
	s_mov_b64 s[14:15], 0x1800
	s_movk_i32 s16, 0x1000
	s_movk_i32 s37, 0x1c00
	s_mov_b64 s[96:97], 0x80
	s_movk_i32 s67, 0xe0
	s_movk_i32 s73, 0x60
	s_movk_i32 s74, 0x80
	s_movk_i32 s75, 0xa0
	s_movk_i32 s79, 0xc0
	s_mov_b64 s[92:93], 0x3000
	s_mov_b32 s42, 0x800000
	v_mov_b32_e32 v186, 0xe0
	s_mov_b32 s44, s95
	s_mov_b32 s101, 0
	s_mov_b32 s98, 0
	s_mov_b32 s99, 0x89abcdef
	v_writelane_b32 v254, s43, 50
	s_branch .LBB0_565
.Lp2_item_done:
	v_readlane_b32 s17, v254, 44
	v_readlane_b32 s38, v254, 45
	v_readlane_b32 s39, v254, 46
	v_readlane_b32 s18, v254, 47
	v_readlane_b32 s40, v254, 48
	v_readlane_b32 s41, v254, 49
	v_readlane_b32 s43, v254, 50
	v_readlane_b32 s28, v254, 36
	v_readlane_b32 s30, v254, 37
	v_readlane_b32 s31, v254, 38
	v_readlane_b32 s88, v254, 39
	v_readlane_b32 s89, v254, 40
	v_readlane_b32 s29, v254, 41
	v_readlane_b32 s34, v254, 42
	v_readlane_b32 s35, v254, 43
	v_readlane_b32 s66, v254, 33
	v_readlane_b32 s84, v254, 34
	v_readlane_b32 s85, v254, 35
	v_readlane_b32 s78, v254, 32
	s_mov_b32 s27, 0
	s_movk_i32 s36, 0x3800
	s_mov_b64 s[14:15], 0x1800
	s_movk_i32 s16, 0x1000
	s_movk_i32 s37, 0x1c00
	s_mov_b64 s[96:97], 0x80
	s_movk_i32 s67, 0xe0
	s_movk_i32 s73, 0x60
	s_movk_i32 s74, 0x80
	s_movk_i32 s75, 0xa0
	s_movk_i32 s79, 0xc0
	s_mov_b64 s[92:93], 0x3000
	s_mov_b32 s42, 0x800000
	v_readlane_b32 s2, v254, 51
	v_readlane_b32 s0, v254, 27
	s_mov_b32 s98, 0
	s_mov_b32 s99, 0x89abcdef
	s_add_i32 s95, s95, s78
	s_add_i32 s2, s2, s0
	s_add_i32 s44, s44, s78
	s_cmpk_gt_i32 s95, 0xff
	s_cbranch_scc1 .LBB0_653
.LBB0_565:
	v_writelane_b32 v254, s2, 51
	s_and_b32 s0, s2, 0xfffff800
	s_mul_hi_i32 s6, s0, 0x3800
	s_mul_i32 s7, s0, 0x3800
	v_readlane_b32 s0, v254, 25
	s_add_u32 s0, s0, s7
	v_readlane_b32 s1, v254, 26
	s_addc_u32 s1, s1, s6
	s_bfe_u32 s9, s95, 0x30003
	s_lshl_b32 s26, s9, 8
	s_add_u32 s76, s0, s26
	s_addc_u32 s77, s1, 0
	s_and_b32 s10, s95, 7
	s_lshl_b32 s0, s10, 2
	s_lshr_b32 s0, s99, s0
	s_and_b32 s0, s0, 15
	s_lshl_b32 s1, s95, 5
	s_and_b32 s11, s1, 0xfffff800
	s_lshl_b32 s8, s0, 7
	v_mov_b32_e32 v8, v183
	s_or_b32 s1, s8, s11
	s_add_i32 s45, s1, s29
	v_and_b32_e32 v9, 15, v8
	v_or_b32_e32 v124, s45, v9
	v_mov_b64_e32 v[4:5], s[30:31]
	v_ashrrev_i32_e32 v10, 4, v8
	s_lshl_b32 s70, s0, 1
	v_mad_i64_i32 v[4:5], s[0:1], v124, s36, v[4:5]
	s_add_i32 s83, s70, s66
	s_lshl_b32 s80, s9, 7
	v_lshl_add_u64 v[126:127], v[4:5], 0, s[26:27]
	v_lshlrev_b32_e32 v4, 3, v10
	s_mul_i32 s1, s11, 0x3800
	v_ashrrev_i32_e32 v5, 31, v4
	s_mul_hi_i32 s0, s11, 0x3800
	s_add_u32 s12, s30, s1
	v_lshl_add_u64 v[4:5], v[4:5], 1, v[126:127]
	s_addc_u32 s13, s31, s0
	v_lshl_add_u64 v[6:7], v[4:5], 0, s[14:15]
	v_add_co_u32_e32 v4, vcc, s16, v4
	s_add_u32 s71, s12, s26
	s_nop 0
	v_addc_co_u32_e32 v5, vcc, 0, v5, vcc
	global_load_dwordx4 v[76:79], v[6:7], off offset:64 nt
	global_load_dwordx4 v[72:75], v[6:7], off offset:128 nt
	global_load_dwordx4 v[80:83], v[4:5], off offset:2048 nt
	global_load_dwordx4 v[68:71], v[6:7], off offset:192 nt
	s_addc_u32 s94, s13, 0
	v_ashrrev_i32_e32 v4, 3, v8
	s_add_u32 s0, s71, 0x2000
	v_add_u32_e32 v5, s34, v4
	v_xor_b32_e32 v4, v4, v8
	s_addc_u32 s1, s94, 0
	v_mul_lo_u32 v5, v5, s37
	v_lshlrev_b32_e32 v4, 3, v4
	s_add_u32 s2, s71, 0x2800
	v_and_or_b32 v4, v4, 56, v5
	v_writelane_b32 v254, s0, 52
	s_addc_u32 s3, s94, 0
	v_lshlrev_b32_e32 v180, 1, v4
	v_add_u32_e32 v4, s35, v10
	v_writelane_b32 v254, s1, 53
	v_lshlrev_b32_e32 v5, 1, v4
	v_writelane_b32 v254, s2, 54
	v_xor_b32_e32 v5, v5, v8
	v_and_b32_e32 v6, 1, v8
	s_waitcnt lgkmcnt(0)
	s_barrier
; #define ATT_WAITBAR_ONE() do { if (DIFF) asm volatile("s_waitcnt vmcnt(4) lgkmcnt(0)\n\ts_barrier" ::: "memory"); else asm volatile("s_waitcnt vmcnt(3) lgkmcnt(0)\n\ts_barrier" ::: "memory"); } while (0)
; template <bool DIFF>
; __device__ __forceinline__ void attn_item(LAS unsigned char* lds, const bf16_t* Z, bf16_t* MIX, int b, int h, int t, float lam, float shift, const float* gain, int tid, int wid, int lane) {
;     ...
;     const char* kbase = (const char*)(Z + (size_t)(b * SEQ) * DIN + kcol);
;     const char* vbase = (const char*)(Z + (size_t)(b * SEQ) * DIN + vcol);
;     const unsigned krow = (unsigned)(8 * wid + (lane >> 3));
;     const unsigned kso = (krow * DIN + 8u * ((unsigned)(lane & 7) ^ (krow & 7u))) * 2u;
;     const unsigned vrow = (unsigned)(4 * wid + (lane >> 4));
;     const unsigned vso = (vrow * DIN + 8u * (2u * ((((unsigned)lane & 15u) >> 1) ^ (vrow & 7u)) + ((unsigned)lane & 1u))) * 2u;
;     constexpr int ATT_RING = 32768;
;     ...
;     asm volatile("s_waitcnt lgkmcnt(0)\n\ts_barrier" ::: "memory");
;     ATT_DMA(0, 0); ATT_DMA(1, 1);
;     ATT_WAITBAR_ONE();
;     const unsigned kfo = (unsigned)(q16 * 128), ksw = (unsigned)(q16 & 7);
;     const unsigned vrr = (unsigned)(4 * quad + (q16 >> 2)), vx32 = (vrr & 7u) * 32u, vb0 = 16384u + vrr * 256u + 8u * (unsigned)(q16 & 3);
;     const float iq = (float)(128 * t + 16 * wid + q16);
;     int bcur = 0;
;     for (int kt = 0; kt < nkt; ++kt) {
;         const int bnx = (bcur == 2) ? 0 : bcur + 1, bn2 = (bnx == 2) ? 0 : bnx + 1;
;         const bool more2 = (kt + 2 < nkt);
;         if (more2) ATT_DMA(kt + 2, bn2);
	v_writelane_b32 v254, s3, 55
	s_add_u32 s4, s2, 0x70000
	s_mov_b32 m0, s90
	v_and_or_b32 v6, v5, 14, v6
	v_mul_lo_u32 v7, v4, s36
	s_addc_u32 s5, s3, 0
	v_lshl_add_u64 v[4:5], s[0:1], 0, v[180:181]
	global_load_lds_dwordx4 v180, s[0:1]
	v_lshl_add_u64 v[4:5], v[4:5], 0, s[96:97]
	s_mov_b32 m0, s17
	v_lshl_or_b32 v132, v6, 4, v7
	global_load_lds_dwordx4 v[4:5], off
	s_mov_b32 m0, s43
	s_add_u32 s0, s71, 0xe2000
	global_load_lds_dwordx4 v132, s[2:3]
	s_mov_b32 m0, s38
	s_addc_u32 s1, s94, 0
	global_load_lds_dwordx4 v132, s[4:5]
	v_writelane_b32 v254, s0, 56
	s_add_u32 s4, s71, 0xe2800
	s_addc_u32 s5, s94, 0
	v_writelane_b32 v254, s1, 57
	v_writelane_b32 v254, s4, 58
	s_mov_b32 m0, s39
	v_lshl_add_u64 v[4:5], s[0:1], 0, v[180:181]
	v_writelane_b32 v254, s5, 59
	s_add_u32 s14, s4, 0x70000
	s_addc_u32 s15, s5, 0
	global_load_lds_dwordx4 v180, s[0:1]
	v_lshl_add_u64 v[4:5], v[4:5], 0, s[96:97]
	s_mov_b32 m0, s18
	v_lshlrev_b32_e32 v128, 2, v10
	global_load_lds_dwordx4 v[4:5], off
	s_mov_b32 m0, s40
	v_bfe_u32 v4, v8, 2, 2
	global_load_lds_dwordx4 v132, s[4:5]
	s_mov_b32 m0, s41
	v_lshlrev_b32_e32 v6, 3, v8
	global_load_lds_dwordx4 v132, s[14:15]
	v_or_b32_e32 v4, v128, v4
	v_and_b32_e32 v6, 24, v6
	v_lshlrev_b32_e32 v5, 5, v4
	v_lshl_or_b32 v4, v4, 8, v6
	v_add_u32_e32 v143, 0x4000, v4
	v_bitop3_b32 v4, v10, v8, 7 bitop3:0x78
	v_lshlrev_b32_e32 v145, 4, v4
	v_add_u32_e32 v4, 4, v10
	s_waitcnt vmcnt(4) lgkmcnt(0)
	s_barrier
	v_bitop3_b32 v4, v4, v8, 7 bitop3:0x78
	v_mov_b32_e32 v6, v181
	v_mov_b32_e32 v7, v181
	v_lshlrev_b32_e32 v144, 7, v9
	v_and_b32_e32 v142, 0xe0, v5
	v_lshlrev_b32_e32 v146, 4, v4
	v_bitop3_b32 v141, v5, 32, v186 bitop3:0x6c
	v_bitop3_b32 v140, v5, 64, v186 bitop3:0x6c
	v_bitop3_b32 v139, v5, s73, v186 bitop3:0x6c
	v_bitop3_b32 v138, v5, s74, v186 bitop3:0x6c
	v_bitop3_b32 v137, v5, s75, v186 bitop3:0x6c
	v_bitop3_b32 v136, v5, s79, v186 bitop3:0x6c
	v_bitop3_b32 v129, v5, s67, v5 bitop3:0xc
	v_mov_b32_e32 v4, v181
	v_mov_b32_e32 v5, v181
	v_mov_b64_e32 v[14:15], v[6:7]
	v_mov_b64_e32 v[22:23], v[6:7]
	v_mov_b64_e32 v[30:31], v[6:7]
	v_mov_b64_e32 v[38:39], v[6:7]
	v_mov_b64_e32 v[46:47], v[6:7]
	v_mov_b64_e32 v[54:55], v[6:7]
	v_mov_b64_e32 v[58:59], v[6:7]
	v_mov_b64_e32 v[10:11], v[6:7]
	v_mov_b64_e32 v[18:19], v[6:7]
	v_mov_b64_e32 v[26:27], v[6:7]
	v_mov_b64_e32 v[34:35], v[6:7]
	v_mov_b64_e32 v[42:43], v[6:7]
	v_mov_b64_e32 v[50:51], v[6:7]
	v_mov_b64_e32 v[62:63], v[6:7]
	v_mov_b64_e32 v[66:67], v[6:7]
	v_ashrrev_i32_e32 v125, 31, v124
	s_mov_b32 s17, 0
	v_mov_b32_e32 v133, v181
	v_mov_b32_e32 v130, v181
	v_mov_b32_e32 v131, v181
	s_mov_b64 s[4:5], s[76:77]
	v_mov_b64_e32 v[12:13], v[4:5]
	v_mov_b64_e32 v[20:21], v[4:5]
	v_mov_b64_e32 v[28:29], v[4:5]
	v_mov_b64_e32 v[36:37], v[4:5]
	v_mov_b64_e32 v[44:45], v[4:5]
	v_mov_b64_e32 v[52:53], v[4:5]
	v_mov_b64_e32 v[56:57], v[4:5]
	v_mov_b64_e32 v[8:9], v[4:5]
	v_mov_b64_e32 v[16:17], v[4:5]
	v_mov_b64_e32 v[24:25], v[4:5]
	v_mov_b64_e32 v[32:33], v[4:5]
	v_mov_b64_e32 v[40:41], v[4:5]
	v_mov_b64_e32 v[48:49], v[4:5]
	v_mov_b64_e32 v[60:61], v[4:5]
	s_mov_b32 s15, 0
	v_mov_b64_e32 v[64:65], v[4:5]
	s_mov_b64 s[4:5], s[76:77]
	s_mov_b32 s15, 0
	s_and_b32 s0, s15, 3
	s_lshl_b32 s0, s0, 15
	s_add_i32 s1, s15, 3
	s_and_b32 s1, s1, 3
	s_lshl_b32 s1, s1, 15
	s_add_i32 s16, s15, 2
	s_and_b32 s16, s16, 3
	s_lshl_b32 s16, s16, 15
	s_add_i32 s16, s16, s90
	v_add_u32_e32 v119, s0, v144
	v_add_u32_e32 v116, v119, v145
	v_add_u32_e32 v117, v119, v146
	ds_read_b128 v[84:87], v116
	ds_read_b128 v[88:91], v116 offset:2048
	ds_read_b128 v[92:95], v117
	ds_read_b128 v[96:99], v117 offset:2048
	ds_read_b128 v[100:103], v116 offset:4096
	ds_read_b128 v[104:107], v116 offset:6144
	ds_read_b128 v[108:111], v117 offset:4096
	ds_read_b128 v[112:115], v117 offset:6144
	s_cmp_ge_u32 s15, s70
	s_cbranch_scc1 .Ldx_nd0
	s_add_u32 s18, s4, 0xfffff800
	s_addc_u32 s19, s5, -1
	s_add_u32 s22, s18, 0x80
	s_addc_u32 s23, s19, 0
	s_add_u32 s24, s4, 0x70000
	s_addc_u32 s25, s5, 0
	s_mov_b32 m0, s16
	s_nop 0
	global_load_lds_dwordx4 v180, s[18:19]
	s_add_i32 m0, s16, 0x2000
	s_nop 0
	global_load_lds_dwordx4 v180, s[22:23]
	s_add_i32 m0, s16, 0x4000
	s_nop 0
	global_load_lds_dwordx4 v132, s[4:5]
	s_add_i32 m0, s16, 0x6000
	s_nop 0
	global_load_lds_dwordx4 v132, s[24:25]
	s_add_u32 s4, s4, 0xe0000
	s_addc_u32 s5, s5, 0
; #define ATT_KREAD(dst, c) do { _Pragma("unroll") for (int kb = 0; kb < 4; ++kb) _Pragma("unroll") for (int ds = 0; ds < 2; ++ds) \
;                 dst[kb * 2 + ds] = *(const LAS bf16x8*)(bp + (c) * 8192 + kb * 2048 + kfo + (((unsigned)(4 * ds + quad) ^ ksw) * 16)); } while (0)
; #define ATT_SMMA(sv, kf, c) do { _Pragma("unroll") for (int kb = 0; kb < 4; ++kb) { sv[kb] = (f32x4){sinit, sinit, sinit, sinit}; _Pragma("unroll") for (int ds = 0; ds < 2; ++ds) \
;                 sv[kb] = __builtin_amdgcn_mfma_f32_16x16x32_bf16(kf[kb * 2 + ds], qf[c][ds], sv[kb], 0, 0, 0); } } while (0)
; #define ATT_SB __builtin_amdgcn_sched_barrier(0)
; template <bool DIFF>
; __device__ __forceinline__ void attn_item(LAS unsigned char* lds, const bf16_t* Z, bf16_t* MIX, int b, int h, int t, float lam, float shift, const float* gain, int tid, int wid, int lane) {
;     ...
;             ATT_KREAD(kfA, 0); ATT_SB;
;             if (DIFF) { ATT_KREAD(kfB, NC - 1); ATT_SMMA(s0, kfA, 0); ATT_SB;
;                         ATT_VISSUE(vAl, vAh, 0); ATT_SMMA(s1, kfB, NC - 1); ATT_SOFT(s0, 0); ATT_SB;
.Ldx_nd0:
	s_waitcnt lgkmcnt(0)
	v_mfma_f32_16x16x32_bf16 v[188:191], v[84:87], v[80:83], v[0:3]
	v_mfma_f32_16x16x32_bf16 v[192:195], v[88:91], v[80:83], v[0:3]
	v_mfma_f32_16x16x32_bf16 v[196:199], v[100:103], v[80:83], v[0:3]
	v_mfma_f32_16x16x32_bf16 v[200:203], v[104:107], v[80:83], v[0:3]
	v_mfma_f32_16x16x32_bf16 v[188:191], v[92:95], v[76:79], v[188:191]
	v_mfma_f32_16x16x32_bf16 v[192:195], v[96:99], v[76:79], v[192:195]
	v_mfma_f32_16x16x32_bf16 v[196:199], v[108:111], v[76:79], v[196:199]
	v_mfma_f32_16x16x32_bf16 v[200:203], v[112:115], v[76:79], v[200:203]
	ds_read_b128 v[84:87], v116 offset:8192
	ds_read_b128 v[88:91], v116 offset:10240
	ds_read_b128 v[92:95], v117 offset:8192
	ds_read_b128 v[96:99], v117 offset:10240
	ds_read_b128 v[100:103], v116 offset:12288
	ds_read_b128 v[104:107], v116 offset:14336
	ds_read_b128 v[108:111], v117 offset:12288
	ds_read_b128 v[112:115], v117 offset:14336
	s_waitcnt lgkmcnt(0)
	v_mfma_f32_16x16x32_bf16 v[204:207], v[84:87], v[72:75], v[0:3]
	v_exp_f32_e32 v188, v188
	v_exp_f32_e32 v189, v189
	v_mfma_f32_16x16x32_bf16 v[208:211], v[88:91], v[72:75], v[0:3]
	v_exp_f32_e32 v190, v190
	v_exp_f32_e32 v191, v191
	v_mfma_f32_16x16x32_bf16 v[212:215], v[100:103], v[72:75], v[0:3]
	v_exp_f32_e32 v192, v192
	v_exp_f32_e32 v193, v193
	v_mfma_f32_16x16x32_bf16 v[216:219], v[104:107], v[72:75], v[0:3]
	v_exp_f32_e32 v194, v194
	v_exp_f32_e32 v195, v195
	v_mfma_f32_16x16x32_bf16 v[204:207], v[92:95], v[68:71], v[204:207]
	v_exp_f32_e32 v196, v196
	v_exp_f32_e32 v197, v197
	v_mfma_f32_16x16x32_bf16 v[208:211], v[96:99], v[68:71], v[208:211]
	v_exp_f32_e32 v198, v198
	v_exp_f32_e32 v199, v199
	v_mfma_f32_16x16x32_bf16 v[212:215], v[108:111], v[68:71], v[212:215]
	v_exp_f32_e32 v200, v200
	v_exp_f32_e32 v201, v201
	v_mfma_f32_16x16x32_bf16 v[216:219], v[112:115], v[68:71], v[216:219]
	v_exp_f32_e32 v202, v202
	v_exp_f32_e32 v203, v203
	v_add_u32_e32 v118, s0, v143
	v_add_u32_e32 v120, v118, v142
	v_add_u32_e32 v121, v118, v141
	v_add_u32_e32 v122, v118, v140
	v_add_u32_e32 v123, v118, v139
	ds_read_b64_tr_b16 v[148:149], v120
	ds_read_b64_tr_b16 v[150:151], v120 offset:4096
	ds_read_b64_tr_b16 v[152:153], v120 offset:8192
	ds_read_b64_tr_b16 v[154:155], v120 offset:12288
	ds_read_b64_tr_b16 v[156:157], v121
	ds_read_b64_tr_b16 v[158:159], v121 offset:4096
	ds_read_b64_tr_b16 v[160:161], v121 offset:8192
	ds_read_b64_tr_b16 v[162:163], v121 offset:12288
	ds_read_b64_tr_b16 v[164:165], v122
	ds_read_b64_tr_b16 v[166:167], v122 offset:4096
	ds_read_b64_tr_b16 v[168:169], v122 offset:8192
	ds_read_b64_tr_b16 v[170:171], v122 offset:12288
	ds_read_b64_tr_b16 v[172:173], v123
	ds_read_b64_tr_b16 v[174:175], v123 offset:4096
	ds_read_b64_tr_b16 v[176:177], v123 offset:8192
	ds_read_b64_tr_b16 v[178:179], v123 offset:12288
	v_exp_f32_e32 v204, v204
	v_add_f32_e32 v131, v131, v188
	v_exp_f32_e32 v205, v205
	v_add_f32_e32 v131, v131, v189
	v_exp_f32_e32 v206, v206
	v_add_f32_e32 v131, v131, v190
	v_exp_f32_e32 v207, v207
	v_add_f32_e32 v131, v131, v191
	v_exp_f32_e32 v208, v208
	v_add_f32_e32 v131, v131, v192
	v_exp_f32_e32 v209, v209
	v_add_f32_e32 v131, v131, v193
	v_exp_f32_e32 v210, v210
	v_add_f32_e32 v131, v131, v194
	v_exp_f32_e32 v211, v211
	v_add_f32_e32 v131, v131, v195
	v_exp_f32_e32 v212, v212
	v_add_f32_e32 v131, v131, v196
	v_exp_f32_e32 v213, v213
	v_add_f32_e32 v131, v131, v197
	v_exp_f32_e32 v214, v214
	v_add_f32_e32 v131, v131, v198
	v_exp_f32_e32 v215, v215
	v_add_f32_e32 v131, v131, v199
	v_exp_f32_e32 v216, v216
	v_add_f32_e32 v131, v131, v200
	v_exp_f32_e32 v217, v217
	v_add_f32_e32 v131, v131, v201
	v_exp_f32_e32 v218, v218
	v_add_f32_e32 v131, v131, v202
	v_exp_f32_e32 v219, v219
	v_add_f32_e32 v131, v131, v203
	v_cvt_pk_bf16_f32 v220, v188, v189
	v_cvt_pk_bf16_f32 v221, v190, v191
	v_cvt_pk_bf16_f32 v222, v192, v193
	v_cvt_pk_bf16_f32 v223, v194, v195
	v_cvt_pk_bf16_f32 v224, v196, v197
	v_cvt_pk_bf16_f32 v225, v198, v199
	v_cvt_pk_bf16_f32 v226, v200, v201
	v_cvt_pk_bf16_f32 v227, v202, v203
	v_add_f32_e32 v130, v130, v204
	v_add_f32_e32 v130, v130, v205
	v_add_f32_e32 v130, v130, v206
	v_add_f32_e32 v130, v130, v207
	v_add_f32_e32 v130, v130, v208
	v_add_f32_e32 v130, v130, v209
	v_add_f32_e32 v130, v130, v210
	v_add_f32_e32 v130, v130, v211
	v_add_f32_e32 v130, v130, v212
	v_add_f32_e32 v130, v130, v213
	v_add_f32_e32 v130, v130, v214
	v_add_f32_e32 v130, v130, v215
	v_add_f32_e32 v130, v130, v216
	v_add_f32_e32 v130, v130, v217
	v_add_f32_e32 v130, v130, v218
	v_add_f32_e32 v130, v130, v219
	v_cvt_pk_bf16_f32 v228, v204, v205
	v_cvt_pk_bf16_f32 v229, v206, v207
	v_cvt_pk_bf16_f32 v230, v208, v209
	v_cvt_pk_bf16_f32 v231, v210, v211
	v_cvt_pk_bf16_f32 v232, v212, v213
	v_cvt_pk_bf16_f32 v233, v214, v215
	v_cvt_pk_bf16_f32 v234, v216, v217
	v_cvt_pk_bf16_f32 v235, v218, v219
	s_cmp_eq_u32 s70, 0
	s_cbranch_scc1 .Ldx_w00
	s_waitcnt vmcnt(4)
	s_branch .Ldx_b0

; #define LAS __attribute__((address_space(3)))
; #define ATT_KREAD(dst, c) do { _Pragma("unroll") for (int kb = 0; kb < 4; ++kb) _Pragma("unroll") for (int ds = 0; ds < 2; ++ds) \
;                 dst[kb * 2 + ds] = *(const LAS bf16x8*)(bp + (c) * 8192 + kb * 2048 + kfo + (((unsigned)(4 * ds + quad) ^ ksw) * 16)); } while (0)
; #define ATT_SMMA(sv, kf, c) do { _Pragma("unroll") for (int kb = 0; kb < 4; ++kb) { sv[kb] = (f32x4){sinit, sinit, sinit, sinit}; _Pragma("unroll") for (int ds = 0; ds < 2; ++ds) \
;                 sv[kb] = __builtin_amdgcn_mfma_f32_16x16x32_bf16(kf[kb * 2 + ds], qf[c][ds], sv[kb], 0, 0, 0); } } while (0)
; #define ATT_PV(c, lo_, hi_, eb0) do { _Pragma("unroll") for (int e = 0; e < 4; ++e) _Pragma("unroll") for (int ks = 0; ks < 2; ++ks) \
;                 O[c][(eb0) + e] = __builtin_amdgcn_mfma_f32_16x16x32_bf16(__builtin_shufflevector(lo_[e * 2 + ks], hi_[e * 2 + ks], 0, 1, 2, 3, 4, 5, 6, 7), P[c][ks], O[c][(eb0) + e], 0, 0, 0); } while (0)
; #define ATT_SB __builtin_amdgcn_sched_barrier(0)
; template <bool DIFF>
; __device__ __forceinline__ void attn_item(LAS unsigned char* lds, const bf16_t* Z, bf16_t* MIX, int b, int h, int t, float lam, float shift, const float* gain, int tid, int wid, int lane) {
;     ...
;     for (int kt = 0; kt < nkt; ++kt) {
;         const int bnx = (bcur == 2) ? 0 : bcur + 1, bn2 = (bnx == 2) ? 0 : bnx + 1;
;         const bool more2 = (kt + 2 < nkt);
;         if (more2) ATT_DMA(kt + 2, bn2);
;         if (kt <= cq) {
;             LAS unsigned char* bp = lds + bcur * ATT_RING;
;             const float msk = 0.f;
;             const float sinit = DIFF ? (msk - shift) : 0.f;
;             bf16x8 kfA[8], kfB[8]; s16x4 vAl[8], vAh[8], vBl[8], vBh[8];
;             f32x4 s0[4], s1[4];
;             bf16x8 P[NC][2];
;             const unsigned bpa = (unsigned)(size_t)bp;
;     ...
;             ATT_KREAD(kfA, 0); ATT_SB;
;             if (DIFF) { ATT_KREAD(kfB, NC - 1); ATT_SMMA(s0, kfA, 0); ATT_SB;
;                         ATT_VISSUE(vAl, vAh, 0); ATT_SMMA(s1, kfB, NC - 1); ATT_SOFT(s0, 0); ATT_SB;
;                         ATT_SOFT(s1, NC - 1); ATT_PVW(0, vAl, vAh, 0); ATT_SB;
;                         ATT_VISSUE(vBl, vBh, 4); ATT_PV(NC - 1, vAl, vAh, 0); ATT_SB;
;                         ATT_PVW(0, vBl, vBh, 4); ATT_PV(NC - 1, vBl, vBh, 4); ATT_SB; }
.Ldx_b0:
	s_barrier
	s_mov_b32 s15, 1
.Ldx_loop:
	s_and_b32 s0, s15, 3
	s_lshl_b32 s0, s0, 15
	s_add_i32 s1, s15, 3
	s_and_b32 s1, s1, 3
	s_lshl_b32 s1, s1, 15
	s_add_i32 s16, s15, 2
	s_and_b32 s16, s16, 3
	s_lshl_b32 s16, s16, 15
	s_add_i32 s16, s16, s90
	s_cmp_gt_u32 s15, s83
	s_cbranch_scc1 .Ldx_pvo
	s_waitcnt lgkmcnt(0)
	v_add_u32_e32 v119, s0, v144
	v_add_u32_e32 v116, v119, v145
	v_add_u32_e32 v117, v119, v146
	ds_read_b128 v[84:87], v116
	ds_read_b128 v[88:91], v116 offset:2048
	ds_read_b128 v[92:95], v117
	ds_read_b128 v[96:99], v117 offset:2048
	ds_read_b128 v[100:103], v116 offset:4096
	ds_read_b128 v[104:107], v116 offset:6144
	ds_read_b128 v[108:111], v117 offset:4096
	ds_read_b128 v[112:115], v117 offset:6144
	v_add_u32_e32 v118, s1, v143
	v_add_u32_e32 v120, v118, v138
	v_add_u32_e32 v121, v118, v137
	v_add_u32_e32 v122, v118, v136
	v_add_u32_e32 v123, v118, v129
	v_mfma_f32_16x16x32_bf16 v[64:67], v[148:151], v[220:223], v[64:67]
	v_mfma_f32_16x16x32_bf16 v[60:63], v[156:159], v[220:223], v[60:63]
	v_mfma_f32_16x16x32_bf16 v[56:59], v[148:151], v[228:231], v[56:59]
	v_mfma_f32_16x16x32_bf16 v[52:55], v[156:159], v[228:231], v[52:55]
	v_mfma_f32_16x16x32_bf16 v[64:67], v[152:155], v[224:227], v[64:67]
	v_mfma_f32_16x16x32_bf16 v[60:63], v[160:163], v[224:227], v[60:63]
	v_mfma_f32_16x16x32_bf16 v[56:59], v[152:155], v[232:235], v[56:59]
	v_mfma_f32_16x16x32_bf16 v[52:55], v[160:163], v[232:235], v[52:55]
	ds_read_b64_tr_b16 v[148:149], v120
	ds_read_b64_tr_b16 v[150:151], v120 offset:4096
	ds_read_b64_tr_b16 v[152:153], v120 offset:8192
	ds_read_b64_tr_b16 v[154:155], v120 offset:12288
	ds_read_b64_tr_b16 v[156:157], v121
	ds_read_b64_tr_b16 v[158:159], v121 offset:4096
	ds_read_b64_tr_b16 v[160:161], v121 offset:8192
	ds_read_b64_tr_b16 v[162:163], v121 offset:12288
	v_mfma_f32_16x16x32_bf16 v[48:51], v[164:167], v[220:223], v[48:51]
	v_mfma_f32_16x16x32_bf16 v[40:43], v[172:175], v[220:223], v[40:43]
	v_mfma_f32_16x16x32_bf16 v[44:47], v[164:167], v[228:231], v[44:47]
	v_mfma_f32_16x16x32_bf16 v[36:39], v[172:175], v[228:231], v[36:39]
	v_mfma_f32_16x16x32_bf16 v[48:51], v[168:171], v[224:227], v[48:51]
	v_mfma_f32_16x16x32_bf16 v[40:43], v[176:179], v[224:227], v[40:43]
	v_mfma_f32_16x16x32_bf16 v[44:47], v[168:171], v[232:235], v[44:47]
	v_mfma_f32_16x16x32_bf16 v[36:39], v[176:179], v[232:235], v[36:39]
	ds_read_b64_tr_b16 v[164:165], v122
	ds_read_b64_tr_b16 v[166:167], v122 offset:4096
	ds_read_b64_tr_b16 v[168:169], v122 offset:8192
	ds_read_b64_tr_b16 v[170:171], v122 offset:12288
	ds_read_b64_tr_b16 v[172:173], v123
	ds_read_b64_tr_b16 v[174:175], v123 offset:4096
	ds_read_b64_tr_b16 v[176:177], v123 offset:8192
	ds_read_b64_tr_b16 v[178:179], v123 offset:12288
	s_cmp_ge_u32 s15, s70
	s_cbranch_scc1 .Ldx_nd
	s_add_u32 s18, s4, 0xfffff800
	s_addc_u32 s19, s5, -1
	s_add_u32 s22, s18, 0x80
	s_addc_u32 s23, s19, 0
	s_add_u32 s24, s4, 0x70000
	s_addc_u32 s25, s5, 0
	s_mov_b32 m0, s16
	s_nop 0
	global_load_lds_dwordx4 v180, s[18:19]
	s_add_i32 m0, s16, 0x2000
	s_nop 0
	global_load_lds_dwordx4 v180, s[22:23]
	s_add_i32 m0, s16, 0x4000
	s_nop 0
	global_load_lds_dwordx4 v132, s[4:5]
	s_add_i32 m0, s16, 0x6000
	s_nop 0
	global_load_lds_dwordx4 v132, s[24:25]
	s_add_u32 s4, s4, 0xe0000
	s_addc_u32 s5, s5, 0
.Ldx_nd:
	s_waitcnt lgkmcnt(15)
	v_mfma_f32_16x16x32_bf16 v[188:191], v[84:87], v[80:83], v[0:3]
	v_mfma_f32_16x16x32_bf16 v[192:195], v[88:91], v[80:83], v[0:3]
	v_mfma_f32_16x16x32_bf16 v[196:199], v[100:103], v[80:83], v[0:3]
	v_mfma_f32_16x16x32_bf16 v[200:203], v[104:107], v[80:83], v[0:3]
	v_mfma_f32_16x16x32_bf16 v[188:191], v[92:95], v[76:79], v[188:191]
	v_mfma_f32_16x16x32_bf16 v[192:195], v[96:99], v[76:79], v[192:195]
	v_mfma_f32_16x16x32_bf16 v[196:199], v[108:111], v[76:79], v[196:199]
	v_mfma_f32_16x16x32_bf16 v[200:203], v[112:115], v[76:79], v[200:203]
	ds_read_b128 v[84:87], v116 offset:8192
	ds_read_b128 v[88:91], v116 offset:10240
	ds_read_b128 v[92:95], v117 offset:8192
	ds_read_b128 v[96:99], v117 offset:10240
	ds_read_b128 v[100:103], v116 offset:12288
	ds_read_b128 v[104:107], v116 offset:14336
	ds_read_b128 v[108:111], v117 offset:12288
	ds_read_b128 v[112:115], v117 offset:14336
	s_waitcnt lgkmcnt(15)
	v_mfma_f32_16x16x32_bf16 v[32:35], v[148:151], v[220:223], v[32:35]
	v_exp_f32_e32 v188, v188
	v_mfma_f32_16x16x32_bf16 v[24:27], v[156:159], v[220:223], v[24:27]
	v_exp_f32_e32 v189, v189
	v_mfma_f32_16x16x32_bf16 v[28:31], v[148:151], v[228:231], v[28:31]
	v_exp_f32_e32 v190, v190
	v_mfma_f32_16x16x32_bf16 v[20:23], v[156:159], v[228:231], v[20:23]
	v_exp_f32_e32 v191, v191
	v_mfma_f32_16x16x32_bf16 v[32:35], v[152:155], v[224:227], v[32:35]
	v_exp_f32_e32 v192, v192
	v_mfma_f32_16x16x32_bf16 v[24:27], v[160:163], v[224:227], v[24:27]
	v_exp_f32_e32 v193, v193
	v_mfma_f32_16x16x32_bf16 v[28:31], v[152:155], v[232:235], v[28:31]
	v_exp_f32_e32 v194, v194
	v_mfma_f32_16x16x32_bf16 v[20:23], v[160:163], v[232:235], v[20:23]
	v_exp_f32_e32 v195, v195
	s_waitcnt lgkmcnt(8)
	v_mfma_f32_16x16x32_bf16 v[16:19], v[164:167], v[220:223], v[16:19]
	v_exp_f32_e32 v196, v196
	v_mfma_f32_16x16x32_bf16 v[8:11], v[172:175], v[220:223], v[8:11]
	v_exp_f32_e32 v197, v197
	v_mfma_f32_16x16x32_bf16 v[12:15], v[164:167], v[228:231], v[12:15]
	v_exp_f32_e32 v198, v198
	v_mfma_f32_16x16x32_bf16 v[4:7], v[172:175], v[228:231], v[4:7]
	v_exp_f32_e32 v199, v199
	v_mfma_f32_16x16x32_bf16 v[16:19], v[168:171], v[224:227], v[16:19]
	v_exp_f32_e32 v200, v200
	v_mfma_f32_16x16x32_bf16 v[8:11], v[176:179], v[224:227], v[8:11]
	v_exp_f32_e32 v201, v201
	v_mfma_f32_16x16x32_bf16 v[12:15], v[168:171], v[232:235], v[12:15]
	v_exp_f32_e32 v202, v202
	v_mfma_f32_16x16x32_bf16 v[4:7], v[176:179], v[232:235], v[4:7]
	v_exp_f32_e32 v203, v203
	s_waitcnt lgkmcnt(0)
; #define ATT_WAITBAR_ALL() asm volatile("s_waitcnt vmcnt(0) lgkmcnt(0)\n\ts_barrier" ::: "memory")
; #define ATT_WAITBAR_ONE() do { if (DIFF) asm volatile("s_waitcnt vmcnt(4) lgkmcnt(0)\n\ts_barrier" ::: "memory"); else asm volatile("s_waitcnt vmcnt(3) lgkmcnt(0)\n\ts_barrier" ::: "memory"); } while (0)
; #define ATT_KREAD(dst, c) do { _Pragma("unroll") for (int kb = 0; kb < 4; ++kb) _Pragma("unroll") for (int ds = 0; ds < 2; ++ds) \
;                 dst[kb * 2 + ds] = *(const LAS bf16x8*)(bp + (c) * 8192 + kb * 2048 + kfo + (((unsigned)(4 * ds + quad) ^ ksw) * 16)); } while (0)
; #define ATT_VWAIT15(lo_, hi_) asm volatile("s_waitcnt lgkmcnt(15)" : "+v"(lo_[0]), "+v"(lo_[1]), "+v"(lo_[2]), "+v"(lo_[3]), "+v"(lo_[4]), "+v"(lo_[5]), "+v"(lo_[6]), "+v"(lo_[7]), \
;                 "+v"(hi_[0]), "+v"(hi_[1]), "+v"(hi_[2]), "+v"(hi_[3]), "+v"(hi_[4]), "+v"(hi_[5]), "+v"(hi_[6]), "+v"(hi_[7]))
; #define ATT_SMMA(sv, kf, c) do { _Pragma("unroll") for (int kb = 0; kb < 4; ++kb) { sv[kb] = (f32x4){sinit, sinit, sinit, sinit}; _Pragma("unroll") for (int ds = 0; ds < 2; ++ds) \
;                 sv[kb] = __builtin_amdgcn_mfma_f32_16x16x32_bf16(kf[kb * 2 + ds], qf[c][ds], sv[kb], 0, 0, 0); } } while (0)
; #define ATT_SB __builtin_amdgcn_sched_barrier(0)
; template <bool DIFF>
; __device__ __forceinline__ void attn_item(LAS unsigned char* lds, const bf16_t* Z, bf16_t* MIX, int b, int h, int t, float lam, float shift, const float* gain, int tid, int wid, int lane) {
;     ...
;             ATT_KREAD(kfA, 0); ATT_SB;
;             if (DIFF) { ATT_KREAD(kfB, NC - 1); ATT_SMMA(s0, kfA, 0); ATT_SB;
;                         ATT_VISSUE(vAl, vAh, 0); ATT_SMMA(s1, kfB, NC - 1); ATT_SOFT(s0, 0); ATT_SB;
;                         ATT_SOFT(s1, NC - 1); ATT_PVW(0, vAl, vAh, 0); ATT_SB;
;                         ATT_VISSUE(vBl, vBh, 4); ATT_PV(NC - 1, vAl, vAh, 0); ATT_SB;
;                         ATT_PVW(0, vBl, vBh, 4); ATT_PV(NC - 1, vBl, vBh, 4); ATT_SB; }
;             else      { ATT_VISSUE(vAl, vAh, 0); ATT_SMMA(s0, kfA, 0); ATT_SB;
;                         ATT_VISSUE(vBl, vBh, 4); ATT_SOFT(s0, 0); ATT_SB;
;                         ATT_VWAIT15(vAl, vAh); ATT_PV(0, vAl, vAh, 0); ATT_PVW(0, vBl, vBh, 4); ATT_SB; }
;     ...
;         }
;         if (kt + 1 < nkt) { if (more2) ATT_WAITBAR_ONE(); else ATT_WAITBAR_ALL(); }
;         bcur = bnx;
;     }
	v_mfma_f32_16x16x32_bf16 v[204:207], v[84:87], v[72:75], v[0:3]
	v_add_f32_e32 v131, v131, v188
	v_add_f32_e32 v131, v131, v189
	v_mfma_f32_16x16x32_bf16 v[208:211], v[88:91], v[72:75], v[0:3]
	v_add_f32_e32 v131, v131, v190
	v_add_f32_e32 v131, v131, v191
	v_mfma_f32_16x16x32_bf16 v[212:215], v[100:103], v[72:75], v[0:3]
	v_add_f32_e32 v131, v131, v192
	v_add_f32_e32 v131, v131, v193
	v_mfma_f32_16x16x32_bf16 v[216:219], v[104:107], v[72:75], v[0:3]
	v_add_f32_e32 v131, v131, v194
	v_add_f32_e32 v131, v131, v195
	v_mfma_f32_16x16x32_bf16 v[204:207], v[92:95], v[68:71], v[204:207]
	v_add_f32_e32 v131, v131, v196
	v_add_f32_e32 v131, v131, v197
	v_mfma_f32_16x16x32_bf16 v[208:211], v[96:99], v[68:71], v[208:211]
	v_add_f32_e32 v131, v131, v198
	v_add_f32_e32 v131, v131, v199
	v_mfma_f32_16x16x32_bf16 v[212:215], v[108:111], v[68:71], v[212:215]
	v_add_f32_e32 v131, v131, v200
	v_add_f32_e32 v131, v131, v201
	v_mfma_f32_16x16x32_bf16 v[216:219], v[112:115], v[68:71], v[216:219]
	v_add_f32_e32 v131, v131, v202
	v_add_f32_e32 v131, v131, v203
	v_add_u32_e32 v118, s0, v143
	v_add_u32_e32 v120, v118, v142
	v_add_u32_e32 v121, v118, v141
	v_add_u32_e32 v122, v118, v140
	v_add_u32_e32 v123, v118, v139
	ds_read_b64_tr_b16 v[148:149], v120
	ds_read_b64_tr_b16 v[150:151], v120 offset:4096
	ds_read_b64_tr_b16 v[152:153], v120 offset:8192
	ds_read_b64_tr_b16 v[154:155], v120 offset:12288
	ds_read_b64_tr_b16 v[156:157], v121
	ds_read_b64_tr_b16 v[158:159], v121 offset:4096
	ds_read_b64_tr_b16 v[160:161], v121 offset:8192
	ds_read_b64_tr_b16 v[162:163], v121 offset:12288
	ds_read_b64_tr_b16 v[164:165], v122
	ds_read_b64_tr_b16 v[166:167], v122 offset:4096
	ds_read_b64_tr_b16 v[168:169], v122 offset:8192
	ds_read_b64_tr_b16 v[170:171], v122 offset:12288
	ds_read_b64_tr_b16 v[172:173], v123
	ds_read_b64_tr_b16 v[174:175], v123 offset:4096
	ds_read_b64_tr_b16 v[176:177], v123 offset:8192
	ds_read_b64_tr_b16 v[178:179], v123 offset:12288
	v_cvt_pk_bf16_f32 v220, v188, v189
	v_cvt_pk_bf16_f32 v221, v190, v191
	v_cvt_pk_bf16_f32 v222, v192, v193
	v_cvt_pk_bf16_f32 v223, v194, v195
	v_cvt_pk_bf16_f32 v224, v196, v197
	v_cvt_pk_bf16_f32 v225, v198, v199
	v_cvt_pk_bf16_f32 v226, v200, v201
	v_cvt_pk_bf16_f32 v227, v202, v203
	v_exp_f32_e32 v204, v204
	v_exp_f32_e32 v205, v205
	v_exp_f32_e32 v206, v206
	v_add_f32_e32 v130, v130, v204
	v_exp_f32_e32 v207, v207
	v_add_f32_e32 v130, v130, v205
	v_exp_f32_e32 v208, v208
	v_add_f32_e32 v130, v130, v206
	v_exp_f32_e32 v209, v209
	v_add_f32_e32 v130, v130, v207
	v_exp_f32_e32 v210, v210
	v_add_f32_e32 v130, v130, v208
	v_exp_f32_e32 v211, v211
	v_add_f32_e32 v130, v130, v209
	v_exp_f32_e32 v212, v212
	v_add_f32_e32 v130, v130, v210
	v_exp_f32_e32 v213, v213
	v_add_f32_e32 v130, v130, v211
	v_exp_f32_e32 v214, v214
	v_add_f32_e32 v130, v130, v212
	v_exp_f32_e32 v215, v215
	v_add_f32_e32 v130, v130, v213
	v_exp_f32_e32 v216, v216
	v_add_f32_e32 v130, v130, v214
	v_exp_f32_e32 v217, v217
	v_add_f32_e32 v130, v130, v215
	v_exp_f32_e32 v218, v218
	v_add_f32_e32 v130, v130, v216
	v_exp_f32_e32 v219, v219
	v_add_f32_e32 v130, v130, v217
	v_add_f32_e32 v130, v130, v218
	v_add_f32_e32 v130, v130, v219
	v_cvt_pk_bf16_f32 v228, v204, v205
	v_cvt_pk_bf16_f32 v229, v206, v207
	v_cvt_pk_bf16_f32 v230, v208, v209
	v_cvt_pk_bf16_f32 v231, v210, v211
	v_cvt_pk_bf16_f32 v232, v212, v213
	v_cvt_pk_bf16_f32 v233, v214, v215
	v_cvt_pk_bf16_f32 v234, v216, v217
	v_cvt_pk_bf16_f32 v235, v218, v219
	s_branch .Ldx_end
.Ldx_pvo:
	s_waitcnt lgkmcnt(0)
	v_add_u32_e32 v118, s1, v143
	v_add_u32_e32 v120, v118, v138
	v_add_u32_e32 v121, v118, v137
	v_add_u32_e32 v122, v118, v136
	v_add_u32_e32 v123, v118, v129
	v_mfma_f32_16x16x32_bf16 v[64:67], v[148:151], v[220:223], v[64:67]
	v_mfma_f32_16x16x32_bf16 v[60:63], v[156:159], v[220:223], v[60:63]
	v_mfma_f32_16x16x32_bf16 v[56:59], v[148:151], v[228:231], v[56:59]
	v_mfma_f32_16x16x32_bf16 v[52:55], v[156:159], v[228:231], v[52:55]
	v_mfma_f32_16x16x32_bf16 v[64:67], v[152:155], v[224:227], v[64:67]
	v_mfma_f32_16x16x32_bf16 v[60:63], v[160:163], v[224:227], v[60:63]
	v_mfma_f32_16x16x32_bf16 v[56:59], v[152:155], v[232:235], v[56:59]
	v_mfma_f32_16x16x32_bf16 v[52:55], v[160:163], v[232:235], v[52:55]
	ds_read_b64_tr_b16 v[148:149], v120
	ds_read_b64_tr_b16 v[150:151], v120 offset:4096
	ds_read_b64_tr_b16 v[152:153], v120 offset:8192
	ds_read_b64_tr_b16 v[154:155], v120 offset:12288
	ds_read_b64_tr_b16 v[156:157], v121
	ds_read_b64_tr_b16 v[158:159], v121 offset:4096
	ds_read_b64_tr_b16 v[160:161], v121 offset:8192
	ds_read_b64_tr_b16 v[162:163], v121 offset:12288
	v_mfma_f32_16x16x32_bf16 v[48:51], v[164:167], v[220:223], v[48:51]
	v_mfma_f32_16x16x32_bf16 v[40:43], v[172:175], v[220:223], v[40:43]
	v_mfma_f32_16x16x32_bf16 v[44:47], v[164:167], v[228:231], v[44:47]
	v_mfma_f32_16x16x32_bf16 v[36:39], v[172:175], v[228:231], v[36:39]
	v_mfma_f32_16x16x32_bf16 v[48:51], v[168:171], v[224:227], v[48:51]
	v_mfma_f32_16x16x32_bf16 v[40:43], v[176:179], v[224:227], v[40:43]
	v_mfma_f32_16x16x32_bf16 v[44:47], v[168:171], v[232:235], v[44:47]
	v_mfma_f32_16x16x32_bf16 v[36:39], v[176:179], v[232:235], v[36:39]
	ds_read_b64_tr_b16 v[164:165], v122
	ds_read_b64_tr_b16 v[166:167], v122 offset:4096
	ds_read_b64_tr_b16 v[168:169], v122 offset:8192
	ds_read_b64_tr_b16 v[170:171], v122 offset:12288
	ds_read_b64_tr_b16 v[172:173], v123
	ds_read_b64_tr_b16 v[174:175], v123 offset:4096
	ds_read_b64_tr_b16 v[176:177], v123 offset:8192
	ds_read_b64_tr_b16 v[178:179], v123 offset:12288
	s_waitcnt lgkmcnt(8)
	v_mfma_f32_16x16x32_bf16 v[32:35], v[148:151], v[220:223], v[32:35]
	v_mfma_f32_16x16x32_bf16 v[24:27], v[156:159], v[220:223], v[24:27]
	v_mfma_f32_16x16x32_bf16 v[28:31], v[148:151], v[228:231], v[28:31]
	v_mfma_f32_16x16x32_bf16 v[20:23], v[156:159], v[228:231], v[20:23]
	v_mfma_f32_16x16x32_bf16 v[32:35], v[152:155], v[224:227], v[32:35]
	v_mfma_f32_16x16x32_bf16 v[24:27], v[160:163], v[224:227], v[24:27]
	v_mfma_f32_16x16x32_bf16 v[28:31], v[152:155], v[232:235], v[28:31]
	v_mfma_f32_16x16x32_bf16 v[20:23], v[160:163], v[232:235], v[20:23]
	s_waitcnt lgkmcnt(0)
	v_mfma_f32_16x16x32_bf16 v[16:19], v[164:167], v[220:223], v[16:19]
	v_mfma_f32_16x16x32_bf16 v[8:11], v[172:175], v[220:223], v[8:11]
	v_mfma_f32_16x16x32_bf16 v[12:15], v[164:167], v[228:231], v[12:15]
	v_mfma_f32_16x16x32_bf16 v[4:7], v[172:175], v[228:231], v[4:7]
	v_mfma_f32_16x16x32_bf16 v[16:19], v[168:171], v[224:227], v[16:19]
	v_mfma_f32_16x16x32_bf16 v[8:11], v[176:179], v[224:227], v[8:11]
	v_mfma_f32_16x16x32_bf16 v[12:15], v[168:171], v[232:235], v[12:15]
	v_mfma_f32_16x16x32_bf16 v[4:7], v[176:179], v[232:235], v[4:7]
.Ldx_end:
	s_add_i32 s15, s15, 1
	s_add_i32 s2, s70, 2
	s_cmp_ge_u32 s15, s2
	s_cbranch_scc1 .Ldx_exit
	s_cmp_le_u32 s15, s70
	s_cbranch_scc0 .Ldx_wz
	s_waitcnt vmcnt(4)
	s_branch .Ldx_bar

; template <bool DIFF>
; __device__ __forceinline__ void attn_item(LAS unsigned char* lds, const bf16_t* Z, bf16_t* MIX, int b, int h, int t, float lam, float shift, const float* gain, int tid, int wid, int lane) {
;     ...
;     float inv0 = 1.f, inv1 = 0.f;
;     if (DIFF) {
; #pragma unroll
;         for (int c = 0; c < NC; ++c) l[c] = quad_sum(l[c]);
;         inv0 = 1.0f / l[0]; inv1 = lam / l[NC - 1];
;     }
;     float ss = 0.f;
; #pragma unroll
;     for (int eb = 0; eb < 8; ++eb)
; #pragma unroll
;         for (int i = 0; i < 4; ++i) { float v = O[0][eb][i] * inv0; if (DIFF) v -= O[NC - 1][eb][i] * inv1; O[0][eb][i] = v; ss += v * v; }
;     ss = quad_sum(ss);
;     const float r = rsqrtf(ss * (1.0f / 128.0f) + EPS) * (DIFF ? 0.8f : 1.0f);
;     const int row = row0 + q16;
;     const bf16_t* gp = Z + (size_t)row * DIN + gcol + 4 * quad;
;     bf16_t* op = MIX + (size_t)row * DM + (DIFF ? 1024 : 0) + 128 * h + 4 * quad;
; #pragma unroll
;     for (int eb = 0; eb < 8; ++eb) {
;         const u32x2 gw = *(const u32x2*)(gp + 16 * eb);
;         const f32x4 gn = *(const f32x4*)(gain + 16 * eb + 4 * quad);
.Ldx_bar:
	s_barrier
	s_branch .Ldx_loop
.Ldx_exit:
	s_add_i32 s2, s70, 1
	s_cmp_le_u32 s2, s83
	s_cbranch_scc0 .Ldx_done
	s_and_b32 s1, s2, 3
	s_lshl_b32 s1, s1, 15
	s_waitcnt lgkmcnt(0)
	v_add_u32_e32 v118, s1, v143
	v_add_u32_e32 v120, v118, v138
	v_add_u32_e32 v121, v118, v137
	v_add_u32_e32 v122, v118, v136
	v_add_u32_e32 v123, v118, v129
	v_mfma_f32_16x16x32_bf16 v[64:67], v[148:151], v[220:223], v[64:67]
	v_mfma_f32_16x16x32_bf16 v[60:63], v[156:159], v[220:223], v[60:63]
	v_mfma_f32_16x16x32_bf16 v[56:59], v[148:151], v[228:231], v[56:59]
	v_mfma_f32_16x16x32_bf16 v[52:55], v[156:159], v[228:231], v[52:55]
	v_mfma_f32_16x16x32_bf16 v[64:67], v[152:155], v[224:227], v[64:67]
	v_mfma_f32_16x16x32_bf16 v[60:63], v[160:163], v[224:227], v[60:63]
	v_mfma_f32_16x16x32_bf16 v[56:59], v[152:155], v[232:235], v[56:59]
	v_mfma_f32_16x16x32_bf16 v[52:55], v[160:163], v[232:235], v[52:55]
	ds_read_b64_tr_b16 v[148:149], v120
	ds_read_b64_tr_b16 v[150:151], v120 offset:4096
	ds_read_b64_tr_b16 v[152:153], v120 offset:8192
	ds_read_b64_tr_b16 v[154:155], v120 offset:12288
	ds_read_b64_tr_b16 v[156:157], v121
	ds_read_b64_tr_b16 v[158:159], v121 offset:4096
	ds_read_b64_tr_b16 v[160:161], v121 offset:8192
	ds_read_b64_tr_b16 v[162:163], v121 offset:12288
	v_mfma_f32_16x16x32_bf16 v[48:51], v[164:167], v[220:223], v[48:51]
	v_mfma_f32_16x16x32_bf16 v[40:43], v[172:175], v[220:223], v[40:43]
	v_mfma_f32_16x16x32_bf16 v[44:47], v[164:167], v[228:231], v[44:47]
	v_mfma_f32_16x16x32_bf16 v[36:39], v[172:175], v[228:231], v[36:39]
	v_mfma_f32_16x16x32_bf16 v[48:51], v[168:171], v[224:227], v[48:51]
	v_mfma_f32_16x16x32_bf16 v[40:43], v[176:179], v[224:227], v[40:43]
	v_mfma_f32_16x16x32_bf16 v[44:47], v[168:171], v[232:235], v[44:47]
	v_mfma_f32_16x16x32_bf16 v[36:39], v[176:179], v[232:235], v[36:39]
	ds_read_b64_tr_b16 v[164:165], v122
	ds_read_b64_tr_b16 v[166:167], v122 offset:4096
	ds_read_b64_tr_b16 v[168:169], v122 offset:8192
	ds_read_b64_tr_b16 v[170:171], v122 offset:12288
	ds_read_b64_tr_b16 v[172:173], v123
	ds_read_b64_tr_b16 v[174:175], v123 offset:4096
	ds_read_b64_tr_b16 v[176:177], v123 offset:8192
	ds_read_b64_tr_b16 v[178:179], v123 offset:12288
	s_waitcnt lgkmcnt(8)
	v_mfma_f32_16x16x32_bf16 v[32:35], v[148:151], v[220:223], v[32:35]
	v_mfma_f32_16x16x32_bf16 v[24:27], v[156:159], v[220:223], v[24:27]
	v_mfma_f32_16x16x32_bf16 v[28:31], v[148:151], v[228:231], v[28:31]
	v_mfma_f32_16x16x32_bf16 v[20:23], v[156:159], v[228:231], v[20:23]
	v_mfma_f32_16x16x32_bf16 v[32:35], v[152:155], v[224:227], v[32:35]
	v_mfma_f32_16x16x32_bf16 v[24:27], v[160:163], v[224:227], v[24:27]
	v_mfma_f32_16x16x32_bf16 v[28:31], v[152:155], v[232:235], v[28:31]
	v_mfma_f32_16x16x32_bf16 v[20:23], v[160:163], v[232:235], v[20:23]
	s_waitcnt lgkmcnt(0)
	v_mfma_f32_16x16x32_bf16 v[16:19], v[164:167], v[220:223], v[16:19]
	v_mfma_f32_16x16x32_bf16 v[8:11], v[172:175], v[220:223], v[8:11]
	v_mfma_f32_16x16x32_bf16 v[12:15], v[164:167], v[228:231], v[12:15]
	v_mfma_f32_16x16x32_bf16 v[4:7], v[172:175], v[228:231], v[4:7]
	v_mfma_f32_16x16x32_bf16 v[16:19], v[168:171], v[224:227], v[16:19]
	v_mfma_f32_16x16x32_bf16 v[8:11], v[176:179], v[224:227], v[8:11]
	v_mfma_f32_16x16x32_bf16 v[12:15], v[168:171], v[232:235], v[12:15]
	v_mfma_f32_16x16x32_bf16 v[4:7], v[176:179], v[232:235], v[4:7]
.Ldx_done:
.LBB0_574:
	s_waitcnt lgkmcnt(0)
	ds_swizzle_b32 v68, v131 offset:swizzle(SWAP,16)
	ds_swizzle_b32 v69, v130 offset:swizzle(SWAP,16)
	v_ashrrev_i32_e32 v129, 31, v128
	v_lshlrev_b64 v[80:81], 1, v[128:129]
	s_lshl_b32 s86, s80, 1
	s_waitcnt lgkmcnt(0)
	v_add_f32_e32 v68, v131, v68
	v_mov_b32_e32 v70, v68
	s_nop 1
	v_permlane32_swap_b32_e32 v68, v70
	v_add_f32_e32 v68, v68, v70
	v_div_scale_f32 v70, s[0:1], v68, v68, 1.0
	v_rcp_f32_e32 v72, v70
	v_add_f32_e32 v69, v130, v69
	v_mov_b32_e32 v71, v69
	s_nop 1
	v_permlane32_swap_b32_e32 v69, v71
	v_add_f32_e32 v69, v69, v71
	v_fma_f32 v71, -v70, v72, 1.0
	v_fmac_f32_e32 v72, v71, v72
	v_div_scale_f32 v71, vcc, 1.0, v68, 1.0
	v_mul_f32_e32 v73, v71, v72
	v_fma_f32 v74, -v70, v73, v71
	v_fmac_f32_e32 v73, v74, v72
	v_fma_f32 v70, -v70, v73, v71
	v_div_scale_f32 v71, s[0:1], v69, v69, s28
	v_rcp_f32_e32 v74, v71
	v_div_fmas_f32 v70, v70, v72, v73
	v_div_fixup_f32 v76, v70, v68, 1.0
	s_movk_i32 s0, 0x3000
	v_fma_f32 v68, -v71, v74, 1.0
	v_fmac_f32_e32 v74, v68, v74
	v_div_scale_f32 v68, vcc, s28, v69, s28
	v_mul_f32_e32 v70, v68, v74
	v_fma_f32 v72, -v71, v70, v68
	v_fmac_f32_e32 v70, v72, v74
	v_fma_f32 v68, -v71, v70, v68
	v_lshl_add_u64 v[72:73], v[126:127], 0, v[80:81]
	v_div_fmas_f32 v68, v68, v74, v70
	v_lshl_add_u64 v[70:71], v[72:73], 0, s[92:93]
	v_add_co_u32_e32 v72, vcc, s0, v72
	v_div_fixup_f32 v78, v68, v69, s28
	v_lshlrev_b64 v[68:69], 12, v[124:125]
	v_addc_co_u32_e32 v73, vcc, 0, v73, vcc
	v_lshl_add_u64 v[82:83], s[88:89], 0, v[68:69]
	v_lshl_add_u64 v[68:69], v[128:129], 2, s[84:85]
	global_load_dwordx2 v[116:117], v[70:71], off
	global_load_dwordx4 v[84:87], v[68:69], off
	global_load_dwordx2 v[118:119], v[70:71], off offset:32
	global_load_dwordx4 v[88:91], v[68:69], off offset:64
	global_load_dwordx2 v[120:121], v[70:71], off offset:64
	global_load_dwordx4 v[92:95], v[68:69], off offset:128
	global_load_dwordx2 v[122:123], v[70:71], off offset:96
	global_load_dwordx4 v[96:99], v[68:69], off offset:192
	global_load_dwordx2 v[132:133], v[70:71], off offset:128
	global_load_dwordx4 v[100:103], v[68:69], off offset:256
	global_load_dwordx2 v[134:135], v[70:71], off offset:160
	global_load_dwordx4 v[104:107], v[68:69], off offset:320
	global_load_dwordx2 v[136:137], v[70:71], off offset:192
; template <bool DIFF>
; __device__ __forceinline__ void attn_item(LAS unsigned char* lds, const bf16_t* Z, bf16_t* MIX, int b, int h, int t, float lam, float shift, const float* gain, int tid, int wid, int lane) {
;     ...
;     float ss = 0.f;
; #pragma unroll
;     for (int eb = 0; eb < 8; ++eb)
; #pragma unroll
;         for (int i = 0; i < 4; ++i) { float v = O[0][eb][i] * inv0; if (DIFF) v -= O[NC - 1][eb][i] * inv1; O[0][eb][i] = v; ss += v * v; }
;     ss = quad_sum(ss);
;     const float r = rsqrtf(ss * (1.0f / 128.0f) + EPS) * (DIFF ? 0.8f : 1.0f);
;     const int row = row0 + q16;
;     const bf16_t* gp = Z + (size_t)row * DIN + gcol + 4 * quad;
;     bf16_t* op = MIX + (size_t)row * DM + (DIFF ? 1024 : 0) + 128 * h + 4 * quad;
; #pragma unroll
;     for (int eb = 0; eb < 8; ++eb) {
;         const u32x2 gw = *(const u32x2*)(gp + 16 * eb);
;         const f32x4 gn = *(const f32x4*)(gain + 16 * eb + 4 * quad);
	global_load_dwordx4 v[108:111], v[68:69], off offset:384
	global_load_dwordx2 v[138:139], v[70:71], off offset:224
	global_load_dwordx4 v[112:115], v[68:69], off offset:448
	v_pk_mul_f32 v[56:57], v[56:57], v[78:79] op_sel_hi:[1,0]
	v_pk_mul_f32 v[58:59], v[58:59], v[78:79] op_sel_hi:[1,0]
	v_pk_fma_f32 v[56:57], v[64:65], v[76:77], v[56:57] op_sel_hi:[1,0,1] neg_lo:[0,0,1] neg_hi:[0,0,1]
	v_pk_fma_f32 v[58:59], v[66:67], v[76:77], v[58:59] op_sel_hi:[1,0,1] neg_lo:[0,0,1] neg_hi:[0,0,1]
	v_pk_mul_f32 v[64:65], v[56:57], v[56:57]
	v_pk_mul_f32 v[66:67], v[58:59], v[58:59]
	v_pk_mul_f32 v[52:53], v[52:53], v[78:79] op_sel_hi:[1,0]
	v_add_f32_e32 v64, v64, v65
	v_pk_fma_f32 v[52:53], v[60:61], v[76:77], v[52:53] op_sel_hi:[1,0,1] neg_lo:[0,0,1] neg_hi:[0,0,1]
	v_add_f32_e32 v64, v66, v64
	v_pk_mul_f32 v[54:55], v[54:55], v[78:79] op_sel_hi:[1,0]
	v_pk_mul_f32 v[60:61], v[52:53], v[52:53]
	v_add_f32_e32 v64, v67, v64
	v_pk_fma_f32 v[54:55], v[62:63], v[76:77], v[54:55] op_sel_hi:[1,0,1] neg_lo:[0,0,1] neg_hi:[0,0,1]
	v_add_f32_e32 v60, v60, v64
	v_pk_mul_f32 v[62:63], v[54:55], v[54:55]
	v_pk_mul_f32 v[44:45], v[44:45], v[78:79] op_sel_hi:[1,0]
	v_add_f32_e32 v60, v61, v60
	v_pk_fma_f32 v[44:45], v[48:49], v[76:77], v[44:45] op_sel_hi:[1,0,1] neg_lo:[0,0,1] neg_hi:[0,0,1]
	v_add_f32_e32 v60, v62, v60
	v_pk_mul_f32 v[46:47], v[46:47], v[78:79] op_sel_hi:[1,0]
	v_pk_mul_f32 v[48:49], v[44:45], v[44:45]
	v_add_f32_e32 v60, v63, v60
	v_pk_fma_f32 v[46:47], v[50:51], v[76:77], v[46:47] op_sel_hi:[1,0,1] neg_lo:[0,0,1] neg_hi:[0,0,1]
	v_add_f32_e32 v48, v48, v60
	v_pk_mul_f32 v[50:51], v[46:47], v[46:47]
	v_pk_mul_f32 v[36:37], v[36:37], v[78:79] op_sel_hi:[1,0]
	v_add_f32_e32 v48, v49, v48
	v_pk_fma_f32 v[36:37], v[40:41], v[76:77], v[36:37] op_sel_hi:[1,0,1] neg_lo:[0,0,1] neg_hi:[0,0,1]
	v_add_f32_e32 v48, v50, v48
	v_pk_mul_f32 v[38:39], v[38:39], v[78:79] op_sel_hi:[1,0]
	v_pk_mul_f32 v[40:41], v[36:37], v[36:37]
	v_add_f32_e32 v48, v51, v48
	v_pk_fma_f32 v[38:39], v[42:43], v[76:77], v[38:39] op_sel_hi:[1,0,1] neg_lo:[0,0,1] neg_hi:[0,0,1]
	v_add_f32_e32 v40, v40, v48
	v_pk_mul_f32 v[42:43], v[38:39], v[38:39]
	v_pk_mul_f32 v[28:29], v[28:29], v[78:79] op_sel_hi:[1,0]
	v_add_f32_e32 v40, v41, v40
	v_pk_fma_f32 v[28:29], v[32:33], v[76:77], v[28:29] op_sel_hi:[1,0,1] neg_lo:[0,0,1] neg_hi:[0,0,1]
	v_add_f32_e32 v40, v42, v40
	v_pk_mul_f32 v[30:31], v[30:31], v[78:79] op_sel_hi:[1,0]
	v_pk_mul_f32 v[32:33], v[28:29], v[28:29]
	v_add_f32_e32 v40, v43, v40
	v_pk_fma_f32 v[30:31], v[34:35], v[76:77], v[30:31] op_sel_hi:[1,0,1] neg_lo:[0,0,1] neg_hi:[0,0,1]
	v_add_f32_e32 v32, v32, v40
	v_pk_mul_f32 v[34:35], v[30:31], v[30:31]
	v_pk_mul_f32 v[20:21], v[20:21], v[78:79] op_sel_hi:[1,0]
	v_add_f32_e32 v32, v33, v32
	v_pk_fma_f32 v[20:21], v[24:25], v[76:77], v[20:21] op_sel_hi:[1,0,1] neg_lo:[0,0,1] neg_hi:[0,0,1]
	v_add_f32_e32 v32, v34, v32
	v_pk_mul_f32 v[22:23], v[22:23], v[78:79] op_sel_hi:[1,0]
	v_pk_mul_f32 v[24:25], v[20:21], v[20:21]
	v_add_f32_e32 v32, v35, v32
	v_pk_fma_f32 v[22:23], v[26:27], v[76:77], v[22:23] op_sel_hi:[1,0,1] neg_lo:[0,0,1] neg_hi:[0,0,1]
	v_add_f32_e32 v24, v24, v32
	v_pk_mul_f32 v[26:27], v[22:23], v[22:23]
	v_pk_mul_f32 v[12:13], v[12:13], v[78:79] op_sel_hi:[1,0]
	v_add_f32_e32 v24, v25, v24
	v_pk_fma_f32 v[12:13], v[16:17], v[76:77], v[12:13] op_sel_hi:[1,0,1] neg_lo:[0,0,1] neg_hi:[0,0,1]
	v_add_f32_e32 v24, v26, v24
	v_pk_mul_f32 v[14:15], v[14:15], v[78:79] op_sel_hi:[1,0]
	v_pk_mul_f32 v[16:17], v[12:13], v[12:13]
	v_add_f32_e32 v24, v27, v24
	v_pk_fma_f32 v[14:15], v[18:19], v[76:77], v[14:15] op_sel_hi:[1,0,1] neg_lo:[0,0,1] neg_hi:[0,0,1]
	v_add_f32_e32 v16, v16, v24
	v_pk_mul_f32 v[18:19], v[14:15], v[14:15]
	v_pk_mul_f32 v[4:5], v[4:5], v[78:79] op_sel_hi:[1,0]
	v_add_f32_e32 v16, v17, v16
	v_pk_fma_f32 v[8:9], v[8:9], v[76:77], v[4:5] op_sel_hi:[1,0,1] neg_lo:[0,0,1] neg_hi:[0,0,1]
	v_add_f32_e32 v16, v18, v16
	v_pk_mul_f32 v[6:7], v[6:7], v[78:79] op_sel_hi:[1,0]
	v_pk_mul_f32 v[4:5], v[8:9], v[8:9]
	v_add_f32_e32 v16, v19, v16
	v_pk_fma_f32 v[10:11], v[10:11], v[76:77], v[6:7] op_sel_hi:[1,0,1] neg_lo:[0,0,1] neg_hi:[0,0,1]
	v_add_f32_e32 v4, v4, v16
	v_pk_mul_f32 v[6:7], v[10:11], v[10:11]
	v_add_f32_e32 v4, v5, v4
	v_add_f32_e32 v4, v6, v4
	v_add_f32_e32 v6, v7, v4
	ds_swizzle_b32 v7, v6 offset:swizzle(SWAP,16)
	v_mov_b32_e32 v18, 0x358637bd
	s_mov_b32 s87, s27
	v_lshl_add_u64 v[4:5], v[82:83], 0, s[86:87]
	v_lshl_add_u64 v[16:17], v[4:5], 0, v[80:81]
	s_waitcnt lgkmcnt(0)
	v_add_f32_e32 v6, v6, v7
	v_mov_b32_e32 v7, v6
	s_nop 1
	v_permlane32_swap_b32_e32 v6, v7
	v_add_f32_e32 v6, v6, v7
	v_fmamk_f32 v6, v6, 0x3c000000, v18
	v_mul_f32_e32 v7, 0x4b800000, v6
	v_cmp_gt_f32_e32 vcc, s42, v6
	s_nop 1
	v_cndmask_b32_e32 v6, v6, v7, vcc
	v_rsq_f32_e32 v24, v6
	s_nop 0
	v_mul_f32_e32 v25, 0x45800000, v24
	v_cndmask_b32_e32 v24, v24, v25, vcc
	v_mul_f32_e32 v24, 0x3f4ccccd, v24
	s_waitcnt vmcnt(0)
; __device__ __forceinline__ unsigned cvtpk(float lo, float hi) { f32x2 v = {lo, hi}; bf16x2_t b = __builtin_convertvector(v, bf16x2_t); return __builtin_bit_cast(unsigned, b); }
; __device__ __forceinline__ float bflo(unsigned u) { return __uint_as_float(u << 16); }
; __device__ __forceinline__ float bfhi(unsigned u) { return __uint_as_float(u & 0xffff0000u); }
; template <bool DIFF>
; __device__ __forceinline__ void attn_item(LAS unsigned char* lds, const bf16_t* Z, bf16_t* MIX, int b, int h, int t, float lam, float shift, const float* gain, int tid, int wid, int lane) {
;     ...
;     for (int eb = 0; eb < 8; ++eb) {
;         const u32x2 gw = *(const u32x2*)(gp + 16 * eb);
;         const f32x4 gn = *(const f32x4*)(gain + 16 * eb + 4 * quad);
;         u32x2 w; w.x = cvtpk(O[0][eb][0] * r * gn.x * bflo(gw.x), O[0][eb][1] * r * gn.y * bfhi(gw.x));
;         w.y = cvtpk(O[0][eb][2] * r * gn.z * bflo(gw.y), O[0][eb][3] * r * gn.w * bfhi(gw.y));
;         *(u32x2*)(op + 16 * eb) = w;
;     }
; __global__ void __launch_bounds__(NWAVES * 64, 2) fwd(Args args) {
;     ...
;         for (int pi = vcu; pi < 256; pi += G) {
;             const int bh = pi >> 3, tp = pi & 7, b = bh >> 3, h = bh & 7;
;             attn_item<true>(lds, Z, MIX, b, h, 15 - tp, lam, shift, subln, 0, wid, 0);
;             ret_pair(lds, Z, MIX, b, h, 15 - tp, tp, ret_gn + 128 * h, wid);
;             attn_item<true>(lds, Z, MIX, b, h, tp, lam, shift, subln, 0, wid, 0);
	v_pk_mul_f32 v[56:57], v[56:57], v[24:25] op_sel_hi:[1,0]
	v_pk_mul_f32 v[58:59], v[58:59], v[24:25] op_sel_hi:[1,0]
	v_lshlrev_b32_e32 v60, 16, v116
	v_and_b32_e32 v61, 0xffff0000, v116
	v_lshlrev_b32_e32 v62, 16, v117
	v_and_b32_e32 v63, 0xffff0000, v117
	v_pk_mul_f32 v[56:57], v[84:85], v[56:57]
	v_pk_mul_f32 v[58:59], v[86:87], v[58:59]
	v_pk_mul_f32 v[56:57], v[56:57], v[60:61]
	v_pk_mul_f32 v[58:59], v[58:59], v[62:63]
	v_cvt_pk_bf16_f32 v56, v56, v57
	v_cvt_pk_bf16_f32 v57, v58, v59
	global_store_dwordx2 v[16:17], v[56:57], off offset:2048
	v_pk_mul_f32 v[52:53], v[52:53], v[24:25] op_sel_hi:[1,0]
	v_pk_mul_f32 v[54:55], v[54:55], v[24:25] op_sel_hi:[1,0]
	v_lshlrev_b32_e32 v40, 16, v118
	v_and_b32_e32 v41, 0xffff0000, v118
	v_lshlrev_b32_e32 v42, 16, v119
	v_and_b32_e32 v43, 0xffff0000, v119
	v_pk_mul_f32 v[52:53], v[88:89], v[52:53]
	v_pk_mul_f32 v[54:55], v[90:91], v[54:55]
	v_pk_mul_f32 v[52:53], v[52:53], v[40:41]
	v_pk_mul_f32 v[54:55], v[54:55], v[42:43]
	v_cvt_pk_bf16_f32 v52, v52, v53
	v_cvt_pk_bf16_f32 v53, v54, v55
	global_store_dwordx2 v[16:17], v[52:53], off offset:2080
	v_pk_mul_f32 v[44:45], v[44:45], v[24:25] op_sel_hi:[1,0]
	v_pk_mul_f32 v[46:47], v[46:47], v[24:25] op_sel_hi:[1,0]
	v_lshlrev_b32_e32 v60, 16, v120
	v_and_b32_e32 v61, 0xffff0000, v120
	v_lshlrev_b32_e32 v62, 16, v121
	v_and_b32_e32 v63, 0xffff0000, v121
	v_pk_mul_f32 v[44:45], v[92:93], v[44:45]
	v_pk_mul_f32 v[46:47], v[94:95], v[46:47]
	v_pk_mul_f32 v[44:45], v[44:45], v[60:61]
	v_pk_mul_f32 v[46:47], v[46:47], v[62:63]
	v_cvt_pk_bf16_f32 v44, v44, v45
	v_cvt_pk_bf16_f32 v45, v46, v47
	global_store_dwordx2 v[16:17], v[44:45], off offset:2112
	v_pk_mul_f32 v[36:37], v[36:37], v[24:25] op_sel_hi:[1,0]
	v_pk_mul_f32 v[38:39], v[38:39], v[24:25] op_sel_hi:[1,0]
	v_lshlrev_b32_e32 v40, 16, v122
	v_and_b32_e32 v41, 0xffff0000, v122
	v_lshlrev_b32_e32 v42, 16, v123
	v_and_b32_e32 v43, 0xffff0000, v123
	v_pk_mul_f32 v[36:37], v[96:97], v[36:37]
	v_pk_mul_f32 v[38:39], v[98:99], v[38:39]
	v_pk_mul_f32 v[36:37], v[36:37], v[40:41]
	v_pk_mul_f32 v[38:39], v[38:39], v[42:43]
	v_cvt_pk_bf16_f32 v36, v36, v37
	v_cvt_pk_bf16_f32 v37, v38, v39
	global_store_dwordx2 v[16:17], v[36:37], off offset:2144
	v_pk_mul_f32 v[28:29], v[28:29], v[24:25] op_sel_hi:[1,0]
	v_pk_mul_f32 v[30:31], v[30:31], v[24:25] op_sel_hi:[1,0]
	v_lshlrev_b32_e32 v60, 16, v132
	v_and_b32_e32 v61, 0xffff0000, v132
	v_lshlrev_b32_e32 v62, 16, v133
	v_and_b32_e32 v63, 0xffff0000, v133
	v_pk_mul_f32 v[28:29], v[100:101], v[28:29]
	v_pk_mul_f32 v[30:31], v[102:103], v[30:31]
	v_pk_mul_f32 v[28:29], v[28:29], v[60:61]
	v_pk_mul_f32 v[30:31], v[30:31], v[62:63]
	v_cvt_pk_bf16_f32 v28, v28, v29
	v_cvt_pk_bf16_f32 v29, v30, v31
	global_store_dwordx2 v[16:17], v[28:29], off offset:2176
	v_pk_mul_f32 v[20:21], v[20:21], v[24:25] op_sel_hi:[1,0]
	v_pk_mul_f32 v[22:23], v[22:23], v[24:25] op_sel_hi:[1,0]
	v_lshlrev_b32_e32 v40, 16, v134
	v_and_b32_e32 v41, 0xffff0000, v134
	v_lshlrev_b32_e32 v42, 16, v135
	v_and_b32_e32 v43, 0xffff0000, v135
	v_pk_mul_f32 v[20:21], v[104:105], v[20:21]
	v_pk_mul_f32 v[22:23], v[106:107], v[22:23]
	v_pk_mul_f32 v[20:21], v[20:21], v[40:41]
	v_pk_mul_f32 v[22:23], v[22:23], v[42:43]
	v_cvt_pk_bf16_f32 v20, v20, v21
	v_cvt_pk_bf16_f32 v21, v22, v23
	global_store_dwordx2 v[16:17], v[20:21], off offset:2208
	v_pk_mul_f32 v[12:13], v[12:13], v[24:25] op_sel_hi:[1,0]
	v_pk_mul_f32 v[14:15], v[14:15], v[24:25] op_sel_hi:[1,0]
	v_lshlrev_b32_e32 v60, 16, v136
	v_and_b32_e32 v61, 0xffff0000, v136
	v_lshlrev_b32_e32 v62, 16, v137
	v_and_b32_e32 v63, 0xffff0000, v137
	v_pk_mul_f32 v[12:13], v[108:109], v[12:13]
	v_pk_mul_f32 v[14:15], v[110:111], v[14:15]
	v_pk_mul_f32 v[12:13], v[12:13], v[60:61]
	v_pk_mul_f32 v[14:15], v[14:15], v[62:63]
	v_cvt_pk_bf16_f32 v12, v12, v13
	v_cvt_pk_bf16_f32 v13, v14, v15
	global_store_dwordx2 v[16:17], v[12:13], off offset:2240
	v_pk_mul_f32 v[8:9], v[8:9], v[24:25] op_sel_hi:[1,0]
	v_pk_mul_f32 v[10:11], v[10:11], v[24:25] op_sel_hi:[1,0]
	v_lshlrev_b32_e32 v40, 16, v138
	v_and_b32_e32 v41, 0xffff0000, v138
	v_lshlrev_b32_e32 v42, 16, v139
	v_and_b32_e32 v43, 0xffff0000, v139
	v_pk_mul_f32 v[8:9], v[112:113], v[8:9]
	v_pk_mul_f32 v[10:11], v[114:115], v[10:11]
	v_pk_mul_f32 v[8:9], v[8:9], v[40:41]
	v_pk_mul_f32 v[10:11], v[10:11], v[42:43]
	v_cvt_pk_bf16_f32 v8, v8, v9
	v_cvt_pk_bf16_f32 v9, v10, v11
	global_store_dwordx2 v[16:17], v[8:9], off offset:2272
	v_mov_b32_e32 v15, v183
	s_cmp_lg_u32 s98, 0
	s_cbranch_scc1 .Lp2_item_done
	s_cmp_lt_i32 s9, 3
	s_cbranch_scc1 .LBB0_579
	s_cmp_lt_i32 s9, 4
	s_cbranch_scc1 .LBB0_580
	s_cmp_lt_i32 s9, 5
	s_cbranch_scc1 .LBB0_581
	s_cmp_lg_u32 s9, 5
	s_cbranch_scc0 .LBB0_582
	s_cmp_eq_u32 s9, 6
	s_cselect_b64 vcc, -1, 0
	v_mov_b32_e32 v4, 0xba38b001
	v_mov_b32_e32 v5, 0xbab8b5c7
	v_cndmask_b32_e32 v12, v4, v5, vcc
	s_cbranch_execz .LBB0_583
	s_branch .LBB0_584

; #define LAS __attribute__((address_space(3)))
; __device__ __forceinline__ int lane_id() { return (int)__builtin_amdgcn_mbcnt_hi(~0u, __builtin_amdgcn_mbcnt_lo(~0u, 0u)); }
; __device__ __forceinline__ void ret_pair(LAS unsigned char* lds, const bf16_t* Z, bf16_t* MIX, int b, int h, int tA, int tB, const float* gain, int wid) {
;     int lane = lane_id(); asm volatile("" : "+v"(lane));
;     const int q16 = lane & 15, quad = lane >> 4;
;     const int rowA0 = b * SEQ + 128 * tA + 16 * wid, rowB0 = b * SEQ + 128 * tB + 16 * wid;
;     const int cqA = 2 * tA + (wid >> 2), cqB = 2 * tB + (wid >> 2), nkt = 2 * tA + 2;
;     const int qcol = 64 * h, kcol = 512 + 64 * h, vcol = 1024 + 128 * h, gcol = 2048 + 128 * h;
;     const float lg = lg2gamma(h);
;     bf16x8 qfA[2], qfB[2];
;     { const bf16_t* qa = Z + (size_t)(rowA0 + q16) * DIN + qcol; const bf16_t* qb = Z + (size_t)(rowB0 + q16) * DIN + qcol;
; #pragma unroll
;       for (int ds = 0; ds < 2; ++ds) { qfA[ds] = __builtin_nontemporal_load((const bf16x8*)(qa + 32 * ds + 8 * quad)); qfB[ds] = __builtin_nontemporal_load((const bf16x8*)(qb + 32 * ds + 8 * quad)); } }
;     f32x4 OA[8], OB[8];
; #pragma unroll
;     for (int eb = 0; eb < 8; ++eb) { OA[eb] = (f32x4){0.f, 0.f, 0.f, 0.f}; OB[eb] = OA[eb]; }
;     const char* kbase = (const char*)(Z + (size_t)(b * SEQ) * DIN + kcol);
;     const char* vbase = (const char*)(Z + (size_t)(b * SEQ) * DIN + vcol);
;     const unsigned krow = (unsigned)(8 * wid + (lane >> 3));
;     const unsigned kso = (krow * DIN + 8u * ((unsigned)(lane & 7) ^ (krow & 7u))) * 2u;
;     const unsigned vrow = (unsigned)(4 * wid + (lane >> 4));
;     const unsigned vso = (vrow * DIN + 8u * (2u * ((((unsigned)lane & 15u) >> 1) ^ (vrow & 7u)) + ((unsigned)lane & 1u))) * 2u;
;     constexpr int RING = 32768;
;     ...
;     asm volatile("s_waitcnt lgkmcnt(0)\n\ts_barrier" ::: "memory");
;     RP_DMA(0, 0); RP_DMA(1, 1);
;     asm volatile("s_waitcnt vmcnt(3) lgkmcnt(0)\n\ts_barrier" ::: "memory");
;     const unsigned kfo = (unsigned)(q16 * 128), ksw = (unsigned)(q16 & 7);
;     const unsigned vrr = (unsigned)(4 * quad + (q16 >> 2)), vx32 = (vrr & 7u) * 32u, vb0 = 16384u + vrr * 256u + 8u * (unsigned)(q16 & 3);
;     const float iqA = (float)(128 * tA + 16 * wid + q16), iqB = (float)(128 * tB + 16 * wid + q16);
.LBB0_595:
	s_lshl_b32 s1, s10, 2
	s_lshr_b32 s1, 0x76543210, s1
	s_and_b32 s1, s1, 15
	s_lshl_b32 s14, s1, 8
	s_or_b32 s0, s14, s11
	v_writelane_b32 v255, s95, 1
	s_add_i32 s5, s0, s29
	s_add_i32 s8, s14, 0x80
	s_or_b32 s45, s8, s11
	s_add_i32 s45, s45, s29
	s_lshl_b32 s82, s1, 2
	s_add_i32 s70, s82, 2
	s_add_i32 s83, s70, s66
	s_add_i32 s0, s70, -1
	s_cmp_lt_u32 s0, s83
	s_cselect_b64 s[2:3], -1, 0
	v_writelane_b32 v254, s2, 60
	v_writelane_b32 v254, s3, 61
	v_writelane_b32 v254, s0, 62
	s_cmp_lt_u32 s70, s83
	s_cselect_b64 s[2:3], -1, 0
	v_writelane_b32 v254, s2, 63
	v_writelane_b32 v255, s3, 0
	v_writelane_b32 v255, s44, 2
	s_mov_b32 s0, s82
	s_add_i32 s91, s82, s66
	v_writelane_b32 v255, s0, 3
	s_add_i32 s72, s66, s0
	v_readlane_b32 s0, v254, 28
	s_add_u32 s0, s0, s7
	v_readlane_b32 s1, v254, 29
	s_addc_u32 s1, s1, s6
	s_add_u32 s2, s0, s26
	s_addc_u32 s3, s1, 0
	v_readlane_b32 s0, v254, 30
	s_add_u32 s0, s0, s7
	v_readlane_b32 s1, v254, 31
	v_and_b32_e32 v14, 15, v15
	s_addc_u32 s1, s1, s6
	s_lshl_b32 s4, s9, 7
	s_add_u32 s84, s0, s4
	v_or_b32_e32 v6, s45, v14
	v_mov_b64_e32 v[4:5], s[30:31]
	s_addc_u32 s85, s1, 0
	v_mad_i64_i32 v[6:7], s[0:1], v6, s36, v[4:5]
	v_writelane_b32 v255, s45, 4
	s_mov_b32 s1, s27
	v_writelane_b32 v255, s0, 5
	v_or_b32_e32 v8, s5, v14
	s_mov_b32 s81, s27
	v_writelane_b32 v255, s1, 6
	v_mad_i64_i32 v[4:5], s[0:1], v8, s36, v[4:5]
	s_add_u32 s9, s12, s80
	v_ashrrev_i32_e32 v13, 3, v15
	v_ashrrev_i32_e32 v17, 4, v15
	v_lshl_add_u64 v[6:7], v[6:7], 0, s[80:81]
	v_lshl_add_u64 v[4:5], v[4:5], 0, s[80:81]
	s_addc_u32 s81, s13, 0
	v_add_u32_e32 v16, s34, v13
	v_xor_b32_e32 v13, v13, v15
	v_lshlrev_b32_e32 v8, 3, v17
	s_add_u32 s4, s9, 0x400
	v_mul_lo_u32 v16, v16, s37
	v_lshlrev_b32_e32 v13, 3, v13
	v_writelane_b32 v255, s5, 7
	v_ashrrev_i32_e32 v9, 31, v8
	s_addc_u32 s5, s81, 0
	v_and_or_b32 v13, v13, 56, v16
	v_lshlrev_b64 v[8:9], 1, v[8:9]
	s_add_u32 s0, s71, 0x800
	v_lshlrev_b32_e32 v180, 1, v13
	v_add_u32_e32 v13, s35, v17
	v_lshl_add_u64 v[6:7], v[6:7], 0, v[8:9]
	v_lshl_add_u64 v[4:5], v[4:5], 0, v[8:9]
	s_addc_u32 s1, s94, 0
	v_lshlrev_b32_e32 v16, 1, v13
	global_load_dwordx4 v[32:35], v[6:7], off nt
	global_load_dwordx4 v[8:11], v[4:5], off nt
	global_load_dwordx4 v[28:31], v[6:7], off offset:64 nt
	s_nop 0
	global_load_dwordx4 v[4:7], v[4:5], off offset:64 nt
	v_xor_b32_e32 v16, v16, v15
	v_and_b32_e32 v18, 1, v15
	s_waitcnt lgkmcnt(0)
	s_barrier
	s_add_u32 s6, s0, 0x70000
	v_and_or_b32 v16, v16, 14, v18
	v_mul_lo_u32 v13, v13, s36
	s_addc_u32 s7, s1, 0
	s_mov_b32 m0, s90
	v_lshl_or_b32 v184, v16, 4, v13
	global_load_lds_dwordx4 v180, s[4:5]
	s_mov_b32 m0, s43
	v_lshlrev_b32_e32 v16, 2, v17
	global_load_lds_dwordx4 v184, s[0:1]
	s_add_u32 s0, s9, 0xe0400
	s_addc_u32 s1, s81, 0
	s_add_u32 s4, s71, 0xe0800
	v_bfe_u32 v13, v15, 2, 2
	v_lshlrev_b32_e32 v19, 3, v15
	s_mov_b32 m0, s38
	s_addc_u32 s5, s94, 0
	v_or_b32_e32 v18, v16, v13
	v_and_b32_e32 v19, 24, v19
	global_load_lds_dwordx4 v184, s[6:7]
	s_add_u32 s6, s4, 0x70000
	v_lshlrev_b32_e32 v13, 5, v18
	v_lshl_or_b32 v18, v18, 8, v19
	v_bitop3_b32 v19, v17, v15, 7 bitop3:0x78
	v_add_u32_e32 v17, 4, v17
	s_addc_u32 s7, s5, 0
	s_add_i32 s8, s8, s29
	v_bitop3_b32 v15, v17, v15, 7 bitop3:0x78
	v_add_u32_e32 v188, 0x4000, v18
	v_or_b32_e32 v18, s8, v14
	v_lshlrev_b32_e32 v205, 4, v15
	v_lshl_add_u32 v15, s83, 6, v16
	v_cvt_f32_u32_e32 v18, v18
	v_cvt_f32_i32_e32 v17, v15
	s_mov_b32 m0, s39
	v_writelane_b32 v255, s9, 8
	v_sub_f32_e32 v17, v17, v18
	global_load_lds_dwordx4 v180, s[0:1]
	v_cmp_lt_f32_e64 s[0:1], 0, v17
	v_mul_f32_e32 v17, v17, v12
	v_exp_f32_e32 v189, v17
	v_or_b32_e32 v17, 1, v15
	v_cvt_f32_i32_e32 v17, v17
	s_mov_b32 m0, s40
	s_add_i32 s14, s14, s29
	global_load_lds_dwordx4 v184, s[4:5]
	v_sub_f32_e32 v17, v17, v18
	v_cmp_lt_f32_e64 s[68:69], 0, v17
	v_mul_f32_e32 v17, v17, v12
	v_exp_f32_e32 v190, v17
	v_or_b32_e32 v17, 2, v15
	v_cvt_f32_i32_e32 v17, v17
	s_mov_b32 m0, s41
	v_lshlrev_b32_e32 v201, 7, v14
	global_load_lds_dwordx4 v184, s[6:7]
	v_sub_f32_e32 v17, v17, v18
	v_cmp_lt_f32_e64 s[4:5], 0, v17
	v_mul_f32_e32 v17, v17, v12
	v_exp_f32_e32 v191, v17
	v_or_b32_e32 v17, 3, v15
	v_cvt_f32_i32_e32 v17, v17
	v_or_b32_e32 v14, s14, v14
	v_cvt_f32_u32_e32 v14, v14
	s_waitcnt vmcnt(3) lgkmcnt(0)
	s_barrier
; __device__ __forceinline__ void ret_pair(LAS unsigned char* lds, const bf16_t* Z, bf16_t* MIX, int b, int h, int tA, int tB, const float* gain, int wid) {
;     ...
;     const float iqA = (float)(128 * tA + 16 * wid + q16), iqB = (float)(128 * tB + 16 * wid + q16);
	v_sub_f32_e32 v17, v17, v18
	v_cmp_lt_f32_e64 s[6:7], 0, v17
	v_mul_f32_e32 v17, v17, v12
	v_exp_f32_e32 v192, v17
	v_add_u32_e32 v17, 16, v15
	v_cvt_f32_i32_e32 v17, v17
	v_mov_b32_e32 v48, v181
	v_mov_b32_e32 v49, v181
	v_mov_b32_e32 v50, v181
	v_sub_f32_e32 v17, v17, v18
	v_cmp_lt_f32_e64 s[8:9], 0, v17
	v_mul_f32_e32 v17, v17, v12
	v_exp_f32_e32 v193, v17
	v_add_u32_e32 v17, 17, v15
	v_cvt_f32_i32_e32 v17, v17
	v_mov_b32_e32 v51, v181
	v_and_b32_e32 v187, 0xe0, v13
	v_lshlrev_b32_e32 v204, 4, v19
	v_sub_f32_e32 v17, v17, v18
	v_cmp_lt_f32_e64 s[10:11], 0, v17
	v_mul_f32_e32 v17, v17, v12
	v_exp_f32_e32 v194, v17
	v_add_u32_e32 v17, 18, v15
	v_cvt_f32_i32_e32 v17, v17
	v_bitop3_b32 v207, v13, 32, v186 bitop3:0x6c
	v_bitop3_b32 v226, v13, 64, v186 bitop3:0x6c
	v_bitop3_b32 v224, v13, s73, v186 bitop3:0x6c
	v_sub_f32_e32 v17, v17, v18
	v_cmp_lt_f32_e64 s[12:13], 0, v17
	v_mul_f32_e32 v17, v17, v12
	v_exp_f32_e32 v195, v17
	v_add_u32_e32 v17, 19, v15
	v_cvt_f32_i32_e32 v17, v17
	v_bitop3_b32 v221, v13, s74, v186 bitop3:0x6c
	v_bitop3_b32 v220, v13, s75, v186 bitop3:0x6c
	v_bitop3_b32 v217, v13, s79, v186 bitop3:0x6c
	v_sub_f32_e32 v17, v17, v18
	v_cmp_lt_f32_e64 s[14:15], 0, v17
	v_mul_f32_e32 v17, v17, v12
	v_exp_f32_e32 v196, v17
	v_add_u32_e32 v17, 32, v15
	v_cvt_f32_i32_e32 v17, v17
	v_bitop3_b32 v216, v13, s67, v13 bitop3:0xc
	v_mov_b64_e32 v[44:45], v[48:49]
	v_mov_b64_e32 v[40:41], v[48:49]
	v_sub_f32_e32 v17, v17, v18
	v_cmp_lt_f32_e64 s[16:17], 0, v17
	v_mul_f32_e32 v17, v17, v12
	v_exp_f32_e32 v197, v17
	v_add_u32_e32 v17, 33, v15
	v_cvt_f32_i32_e32 v17, v17
	v_mov_b64_e32 v[36:37], v[48:49]
	v_mov_b64_e32 v[24:25], v[48:49]
	v_mov_b64_e32 v[20:21], v[48:49]
	v_sub_f32_e32 v17, v17, v18
	v_cmp_lt_f32_e64 s[18:19], 0, v17
	v_mul_f32_e32 v17, v17, v12
	v_exp_f32_e32 v198, v17
	v_add_u32_e32 v17, 34, v15
	v_cvt_f32_i32_e32 v17, v17
	v_mov_b64_e32 v[82:83], v[50:51]
	v_mov_b64_e32 v[78:79], v[50:51]
	v_mov_b64_e32 v[74:75], v[50:51]
	v_sub_f32_e32 v17, v17, v18
	v_cmp_lt_f32_e64 s[20:21], 0, v17
	v_mul_f32_e32 v17, v17, v12
	v_exp_f32_e32 v199, v17
	v_add_u32_e32 v17, 35, v15
	v_cvt_f32_i32_e32 v17, v17
	v_mov_b64_e32 v[70:71], v[50:51]
	v_mov_b64_e32 v[66:67], v[50:51]
	v_mov_b64_e32 v[62:63], v[50:51]
	v_sub_f32_e32 v17, v17, v18
	v_cmp_lt_f32_e64 s[22:23], 0, v17
	v_mul_f32_e32 v17, v17, v12
	v_exp_f32_e32 v200, v17
	v_add_u32_e32 v17, 48, v15
	v_cvt_f32_i32_e32 v17, v17
	v_mov_b64_e32 v[58:59], v[50:51]
	v_mov_b64_e32 v[54:55], v[50:51]
	v_mov_b32_e32 v185, v181
	v_sub_f32_e32 v17, v17, v18
	v_cmp_lt_f32_e64 s[24:25], 0, v17
	v_mul_f32_e32 v17, v17, v12
	v_exp_f32_e32 v203, v17
	v_add_u32_e32 v17, 49, v15
	v_cvt_f32_i32_e32 v17, v17
	s_mov_b32 s66, 0
	v_mov_b64_e32 v[46:47], v[50:51]
	v_mov_b64_e32 v[42:43], v[50:51]
	v_sub_f32_e32 v17, v17, v18
	v_cmp_lt_f32_e64 s[26:27], 0, v17
	v_mul_f32_e32 v17, v17, v12
	v_exp_f32_e32 v206, v17
	v_add_u32_e32 v17, 50, v15
	v_add_u32_e32 v15, 51, v15
	v_cvt_f32_i32_e32 v15, v15
	v_cvt_f32_i32_e32 v17, v17
	v_mov_b64_e32 v[38:39], v[50:51]
	v_mov_b64_e32 v[26:27], v[50:51]
	v_sub_f32_e32 v15, v15, v18
	v_cmp_lt_f32_e64 s[34:35], 0, v15
	v_mul_f32_e32 v15, v15, v12
	v_exp_f32_e32 v211, v15
	v_lshl_add_u32 v15, s91, 6, v16
	v_cvt_f32_i32_e32 v16, v15
	v_sub_f32_e32 v17, v17, v18
	v_cmp_lt_f32_e64 s[28:29], 0, v17
	v_mul_f32_e32 v17, v17, v12
	v_sub_f32_e32 v16, v16, v14
	v_cmp_lt_f32_e64 s[30:31], 0, v16
	v_mul_f32_e32 v16, v16, v12
	v_exp_f32_e32 v208, v16
	v_or_b32_e32 v16, 1, v15
	v_cvt_f32_i32_e32 v16, v16
	v_exp_f32_e32 v209, v17
	v_mov_b64_e32 v[22:23], v[50:51]
	v_mov_b64_e32 v[80:81], v[48:49]
	v_sub_f32_e32 v16, v16, v14
	v_cmp_lt_f32_e64 s[36:37], 0, v16
	v_mul_f32_e32 v16, v16, v12
	v_exp_f32_e32 v210, v16
	v_or_b32_e32 v16, 2, v15
	v_cvt_f32_i32_e32 v16, v16
	v_mov_b64_e32 v[76:77], v[48:49]
	v_mov_b64_e32 v[72:73], v[48:49]
	v_mov_b64_e32 v[68:69], v[48:49]
	v_sub_f32_e32 v16, v16, v14
	v_cmp_lt_f32_e64 s[38:39], 0, v16
	v_mul_f32_e32 v16, v16, v12
	v_exp_f32_e32 v252, v16
	v_or_b32_e32 v16, 3, v15
	v_cvt_f32_i32_e32 v16, v16
	v_mov_b64_e32 v[64:65], v[48:49]
	v_mov_b64_e32 v[60:61], v[48:49]
	v_mov_b64_e32 v[56:57], v[48:49]
	v_sub_f32_e32 v16, v16, v14
	v_cmp_lt_f32_e64 s[40:41], 0, v16
	v_mul_f32_e32 v16, v16, v12
	v_exp_f32_e32 v253, v16
	v_add_u32_e32 v16, 16, v15
	v_cvt_f32_i32_e32 v16, v16
	v_mov_b64_e32 v[52:53], v[48:49]
	s_mov_b32 s73, 0
	v_sub_f32_e32 v16, v16, v14
	v_cmp_lt_f32_e64 s[42:43], 0, v16
	v_mul_f32_e32 v16, v16, v12
	v_exp_f32_e32 v202, v16
	v_add_u32_e32 v16, 17, v15
	v_cvt_f32_i32_e32 v16, v16
	v_sub_f32_e32 v16, v16, v14
	v_cmp_lt_f32_e64 s[44:45], 0, v16
	v_mul_f32_e32 v16, v16, v12
	v_exp_f32_e32 v182, v16
	v_add_u32_e32 v16, 18, v15
	v_cvt_f32_i32_e32 v16, v16
	v_sub_f32_e32 v16, v16, v14
	v_cmp_lt_f32_e64 s[46:47], 0, v16
	v_mul_f32_e32 v16, v16, v12
	v_exp_f32_e32 v218, v16
	v_add_u32_e32 v16, 19, v15
	v_cvt_f32_i32_e32 v16, v16
	v_sub_f32_e32 v16, v16, v14
	v_cmp_lt_f32_e64 s[48:49], 0, v16
	v_mul_f32_e32 v16, v16, v12
	v_exp_f32_e32 v219, v16
	v_add_u32_e32 v16, 32, v15
	v_cvt_f32_i32_e32 v16, v16
	v_sub_f32_e32 v16, v16, v14
	v_cmp_lt_f32_e64 s[50:51], 0, v16
	v_mul_f32_e32 v16, v16, v12
	v_exp_f32_e32 v222, v16
	v_add_u32_e32 v16, 33, v15
	v_cvt_f32_i32_e32 v16, v16
	v_sub_f32_e32 v16, v16, v14
	v_cmp_lt_f32_e64 s[52:53], 0, v16
	v_mul_f32_e32 v16, v16, v12
	v_exp_f32_e32 v223, v16
	v_add_u32_e32 v16, 34, v15
	v_cvt_f32_i32_e32 v16, v16
	v_sub_f32_e32 v16, v16, v14
	v_cmp_lt_f32_e64 s[54:55], 0, v16
	v_mul_f32_e32 v16, v16, v12
	v_exp_f32_e32 v225, v16
	v_add_u32_e32 v16, 35, v15
	v_cvt_f32_i32_e32 v16, v16
	v_sub_f32_e32 v16, v16, v14
; __device__ __forceinline__ void ret_pair(LAS unsigned char* lds, const bf16_t* Z, bf16_t* MIX, int b, int h, int tA, int tB, const float* gain, int wid) {
;     ...
;     int bcur = 0;
;     for (int kt = 0; kt < nkt; ++kt) {
;         const int bnx = (bcur == 2) ? 0 : bcur + 1, bn2 = (bnx == 2) ? 0 : bnx + 1;
;         const bool more2 = (kt + 2 < nkt);
;         if (more2) RP_DMA(kt + 2, bn2);
	v_cmp_lt_f32_e64 s[56:57], 0, v16
	v_mul_f32_e32 v16, v16, v12
	v_exp_f32_e32 v227, v16
	v_add_u32_e32 v16, 48, v15
	v_cvt_f32_i32_e32 v16, v16
	v_sub_f32_e32 v16, v16, v14
	v_cmp_lt_f32_e64 s[58:59], 0, v16
	v_mul_f32_e32 v16, v16, v12
	v_exp_f32_e32 v228, v16
	v_add_u32_e32 v16, 49, v15
	v_cvt_f32_i32_e32 v16, v16
	v_sub_f32_e32 v16, v16, v14
	v_cmp_lt_f32_e64 s[60:61], 0, v16
	v_mul_f32_e32 v16, v16, v12
	v_exp_f32_e32 v229, v16
	v_add_u32_e32 v16, 50, v15
	v_add_u32_e32 v15, 51, v15
	v_cvt_f32_i32_e32 v16, v16
	v_cvt_f32_i32_e32 v15, v15
	v_sub_f32_e32 v16, v16, v14
	v_sub_f32_e32 v14, v15, v14
	v_cmp_lt_f32_e64 s[62:63], 0, v16
	v_mul_f32_e32 v16, v16, v12
	v_mul_f32_e32 v12, v14, v12
	v_exp_f32_e32 v230, v16
	v_exp_f32_e32 v231, v12
	v_cmp_lt_f32_e64 s[64:65], 0, v14
	v_mov_b64_e32 v[16:17], v[48:49]
	v_mov_b64_e32 v[12:13], v[48:49]
	v_mov_b64_e32 v[18:19], v[50:51]
	v_mov_b64_e32 v[14:15], v[50:51]
	s_mov_b32 s98, 0
	s_and_b32 s72, s98, 3
	s_lshl_b32 s72, s72, 15
	s_add_i32 s73, s98, 3
	s_and_b32 s73, s73, 3
	s_lshl_b32 s73, s73, 15
	s_add_i32 s74, s98, 2
	s_and_b32 s74, s74, 3
	s_lshl_b32 s74, s74, 15
	s_add_i32 s74, s74, s90
	v_add_u32_e32 v212, s72, v201
	v_add_u32_e32 v213, v212, v204
	v_add_u32_e32 v214, v212, v205
	ds_read_b128 v[84:87], v213
	ds_read_b128 v[88:91], v213 offset:2048
	ds_read_b128 v[92:95], v214
	ds_read_b128 v[96:99], v214 offset:2048
	ds_read_b128 v[100:103], v213 offset:4096
	ds_read_b128 v[104:107], v213 offset:6144
	ds_read_b128 v[108:111], v214 offset:4096
	ds_read_b128 v[112:115], v214 offset:6144
	s_cmp_ge_u32 s98, s70
	s_cbranch_scc1 .Lrx_ndf
	s_add_u32 s78, s2, 0x70000
	s_addc_u32 s79, s3, 0
	s_mov_b32 m0, s74
	s_nop 0
	global_load_lds_dwordx4 v180, s[84:85]
	s_add_i32 m0, s74, 0x4000
	s_nop 0
	global_load_lds_dwordx4 v184, s[2:3]
	s_add_i32 m0, s74, 0x6000
	s_nop 0
	global_load_lds_dwordx4 v184, s[78:79]
	s_add_u32 s2, s2, 0xe0000
	s_addc_u32 s3, s3, 0
	s_add_u32 s84, s84, 0xe0000
	s_addc_u32 s85, s85, 0
.Lrx_ndf:
	s_waitcnt lgkmcnt(0)
	v_mfma_f32_16x16x32_bf16 v[148:151], v[84:87], v[32:35], 0
	v_mfma_f32_16x16x32_bf16 v[152:155], v[88:91], v[32:35], 0
	v_mfma_f32_16x16x32_bf16 v[156:159], v[100:103], v[32:35], 0
	v_mfma_f32_16x16x32_bf16 v[160:163], v[104:107], v[32:35], 0
	v_mfma_f32_16x16x32_bf16 v[148:151], v[92:95], v[28:31], v[148:151]
	v_mfma_f32_16x16x32_bf16 v[152:155], v[96:99], v[28:31], v[152:155]
	v_mfma_f32_16x16x32_bf16 v[156:159], v[108:111], v[28:31], v[156:159]
	v_mfma_f32_16x16x32_bf16 v[160:163], v[112:115], v[28:31], v[160:163]
	v_mfma_f32_16x16x32_bf16 v[164:167], v[84:87], v[8:11], 0
	v_mfma_f32_16x16x32_bf16 v[168:171], v[88:91], v[8:11], 0
	v_mfma_f32_16x16x32_bf16 v[172:175], v[100:103], v[8:11], 0
	v_mfma_f32_16x16x32_bf16 v[176:179], v[104:107], v[8:11], 0
	v_mfma_f32_16x16x32_bf16 v[164:167], v[92:95], v[4:7], v[164:167]
	v_mfma_f32_16x16x32_bf16 v[168:171], v[96:99], v[4:7], v[168:171]
	v_mfma_f32_16x16x32_bf16 v[172:175], v[108:111], v[4:7], v[172:175]
	v_mfma_f32_16x16x32_bf16 v[176:179], v[112:115], v[4:7], v[176:179]
	v_add_u32_e32 v215, s72, v188
	v_add_u32_e32 v248, v215, v187
	v_add_u32_e32 v249, v215, v207
	v_add_u32_e32 v250, v215, v226
	v_add_u32_e32 v251, v215, v224
	ds_read_b64_tr_b16 v[116:117], v248
	ds_read_b64_tr_b16 v[118:119], v248 offset:4096
	ds_read_b64_tr_b16 v[120:121], v248 offset:8192
	ds_read_b64_tr_b16 v[122:123], v248 offset:12288
	ds_read_b64_tr_b16 v[124:125], v249
	ds_read_b64_tr_b16 v[126:127], v249 offset:4096
	ds_read_b64_tr_b16 v[128:129], v249 offset:8192
	ds_read_b64_tr_b16 v[130:131], v249 offset:12288
	ds_read_b64_tr_b16 v[132:133], v250
	ds_read_b64_tr_b16 v[134:135], v250 offset:4096
	ds_read_b64_tr_b16 v[136:137], v250 offset:8192
	ds_read_b64_tr_b16 v[138:139], v250 offset:12288
	ds_read_b64_tr_b16 v[140:141], v251
	ds_read_b64_tr_b16 v[142:143], v251 offset:4096
	ds_read_b64_tr_b16 v[144:145], v251 offset:8192
	ds_read_b64_tr_b16 v[146:147], v251 offset:12288
	s_cmp_lg_u32 s98, s83
	s_cbranch_scc1 .Lrx_daf
	v_mul_f32_e32 v212, v189, v148
	v_cndmask_b32_e64 v148, v148, v212, s[0:1]
	v_mul_f32_e32 v212, v190, v149
	v_cndmask_b32_e64 v149, v149, v212, s[68:69]
	v_mul_f32_e32 v212, v191, v150
	v_cndmask_b32_e64 v150, v150, v212, s[4:5]
	v_mul_f32_e32 v212, v192, v151
	v_cndmask_b32_e64 v151, v151, v212, s[6:7]
	v_mul_f32_e32 v212, v193, v152
	v_cndmask_b32_e64 v152, v152, v212, s[8:9]
	v_mul_f32_e32 v212, v194, v153
	v_cndmask_b32_e64 v153, v153, v212, s[10:11]
	v_mul_f32_e32 v212, v195, v154
	v_cndmask_b32_e64 v154, v154, v212, s[12:13]
	v_mul_f32_e32 v212, v196, v155
	v_cndmask_b32_e64 v155, v155, v212, s[14:15]
	v_mul_f32_e32 v212, v197, v156
	v_cndmask_b32_e64 v156, v156, v212, s[16:17]
	v_mul_f32_e32 v212, v198, v157
	v_cndmask_b32_e64 v157, v157, v212, s[18:19]
	v_mul_f32_e32 v212, v199, v158
	v_cndmask_b32_e64 v158, v158, v212, s[20:21]
	v_mul_f32_e32 v212, v200, v159
	v_cndmask_b32_e64 v159, v159, v212, s[22:23]
	v_mul_f32_e32 v212, v203, v160
	v_cndmask_b32_e64 v160, v160, v212, s[24:25]
	v_mul_f32_e32 v212, v206, v161
	v_cndmask_b32_e64 v161, v161, v212, s[26:27]
	v_mul_f32_e32 v212, v209, v162
	v_cndmask_b32_e64 v162, v162, v212, s[28:29]
	v_mul_f32_e32 v212, v211, v163
	v_cndmask_b32_e64 v163, v163, v212, s[34:35]
.Lrx_daf:
	v_cvt_pk_bf16_f32 v232, v148, v149
	v_cvt_pk_bf16_f32 v233, v150, v151
	v_cvt_pk_bf16_f32 v234, v152, v153
	v_cvt_pk_bf16_f32 v235, v154, v155
	v_cvt_pk_bf16_f32 v236, v156, v157
	v_cvt_pk_bf16_f32 v237, v158, v159
	v_cvt_pk_bf16_f32 v238, v160, v161
	v_cvt_pk_bf16_f32 v239, v162, v163
	s_cmp_lg_u32 s98, s91
	s_cbranch_scc1 .Lrx_dbf
	v_mul_f32_e32 v212, v208, v164
	v_cndmask_b32_e64 v164, v164, v212, s[30:31]
	v_mul_f32_e32 v212, v210, v165
	v_cndmask_b32_e64 v165, v165, v212, s[36:37]
	v_mul_f32_e32 v212, v252, v166
	v_cndmask_b32_e64 v166, v166, v212, s[38:39]
	v_mul_f32_e32 v212, v253, v167
	v_cndmask_b32_e64 v167, v167, v212, s[40:41]
	v_mul_f32_e32 v212, v202, v168
	v_cndmask_b32_e64 v168, v168, v212, s[42:43]
	v_mul_f32_e32 v212, v182, v169
	v_cndmask_b32_e64 v169, v169, v212, s[44:45]
	v_mul_f32_e32 v212, v218, v170
	v_cndmask_b32_e64 v170, v170, v212, s[46:47]
	v_mul_f32_e32 v212, v219, v171
	v_cndmask_b32_e64 v171, v171, v212, s[48:49]
	v_mul_f32_e32 v212, v222, v172
	v_cndmask_b32_e64 v172, v172, v212, s[50:51]
	v_mul_f32_e32 v212, v223, v173
	v_cndmask_b32_e64 v173, v173, v212, s[52:53]
	v_mul_f32_e32 v212, v225, v174
	v_cndmask_b32_e64 v174, v174, v212, s[54:55]
	v_mul_f32_e32 v212, v227, v175
	v_cndmask_b32_e64 v175, v175, v212, s[56:57]
	v_mul_f32_e32 v212, v228, v176
	v_cndmask_b32_e64 v176, v176, v212, s[58:59]
	v_mul_f32_e32 v212, v229, v177
	v_cndmask_b32_e64 v177, v177, v212, s[60:61]
	v_mul_f32_e32 v212, v230, v178
	v_cndmask_b32_e64 v178, v178, v212, s[62:63]
	v_mul_f32_e32 v212, v231, v179
	v_cndmask_b32_e64 v179, v179, v212, s[64:65]
.Lrx_dbf:
	v_cvt_pk_bf16_f32 v240, v164, v165
	v_cvt_pk_bf16_f32 v241, v166, v167
	v_cvt_pk_bf16_f32 v242, v168, v169
	v_cvt_pk_bf16_f32 v243, v170, v171
	v_cvt_pk_bf16_f32 v244, v172, v173
	v_cvt_pk_bf16_f32 v245, v174, v175
	v_cvt_pk_bf16_f32 v246, v176, v177
	v_cvt_pk_bf16_f32 v247, v178, v179
	s_cmp_eq_u32 s70, 0
	s_cbranch_scc1 .Lrx_w00
	s_waitcnt vmcnt(3)
	s_branch .Lrx_b0

; __device__ __forceinline__ void ret_pair(LAS unsigned char* lds, const bf16_t* Z, bf16_t* MIX, int b, int h, int tA, int tB, const float* gain, int wid) {
;     ...
;     int bcur = 0;
;     for (int kt = 0; kt < nkt; ++kt) {
;         const int bnx = (bcur == 2) ? 0 : bcur + 1, bn2 = (bnx == 2) ? 0 : bnx + 1;
;         const bool more2 = (kt + 2 < nkt);
;         if (more2) RP_DMA(kt + 2, bn2);
;         if (kt <= cqA) {
;             if (kt <= cqB) RP_BODY(true); else RP_BODY(false);
;         }
;         if (kt + 1 < nkt) { if (more2) asm volatile("s_waitcnt vmcnt(3) lgkmcnt(0)\n\ts_barrier" ::: "memory"); else asm volatile("s_waitcnt vmcnt(0) lgkmcnt(0)\n\ts_barrier" ::: "memory"); }
;         bcur = bnx;
.Lrx_b0:
	s_barrier
	s_mov_b32 s98, 1
.Lrx_loop:
	s_and_b32 s72, s98, 3
	s_lshl_b32 s72, s72, 15
	s_add_i32 s73, s98, 3
	s_and_b32 s73, s73, 3
	s_lshl_b32 s73, s73, 15
	s_add_i32 s74, s98, 2
	s_and_b32 s74, s74, 3
	s_lshl_b32 s74, s74, 15
	s_add_i32 s74, s74, s90
	s_cmp_gt_u32 s98, s83
	s_cbranch_scc1 .Lrx_pvo
	s_cmp_le_u32 s98, s91
	s_cbranch_scc1 .Lrx_sab
	s_add_i32 s75, s98, -1
	s_cmp_le_u32 s75, s91
	s_cbranch_scc1 .Lrx_sapab
	s_waitcnt lgkmcnt(0)
	v_add_u32_e32 v212, s72, v201
	v_add_u32_e32 v213, v212, v204
	v_add_u32_e32 v214, v212, v205
	ds_read_b128 v[84:87], v213
	ds_read_b128 v[88:91], v213 offset:2048
	ds_read_b128 v[92:95], v214
	ds_read_b128 v[96:99], v214 offset:2048
	ds_read_b128 v[100:103], v213 offset:4096
	ds_read_b128 v[104:107], v213 offset:6144
	ds_read_b128 v[108:111], v214 offset:4096
	ds_read_b128 v[112:115], v214 offset:6144
	v_add_u32_e32 v215, s73, v188
	v_add_u32_e32 v248, v215, v221
	v_add_u32_e32 v249, v215, v220
	v_add_u32_e32 v250, v215, v217
	v_add_u32_e32 v251, v215, v216
	v_mfma_f32_16x16x32_bf16 v[80:83], v[116:119], v[232:235], v[80:83]
	v_mfma_f32_16x16x32_bf16 v[76:79], v[124:127], v[232:235], v[76:79]
	v_mfma_f32_16x16x32_bf16 v[80:83], v[120:123], v[236:239], v[80:83]
	v_mfma_f32_16x16x32_bf16 v[76:79], v[128:131], v[236:239], v[76:79]
	ds_read_b64_tr_b16 v[116:117], v248
	ds_read_b64_tr_b16 v[118:119], v248 offset:4096
	ds_read_b64_tr_b16 v[120:121], v248 offset:8192
	ds_read_b64_tr_b16 v[122:123], v248 offset:12288
	ds_read_b64_tr_b16 v[124:125], v249
	ds_read_b64_tr_b16 v[126:127], v249 offset:4096
	ds_read_b64_tr_b16 v[128:129], v249 offset:8192
	ds_read_b64_tr_b16 v[130:131], v249 offset:12288
	v_mfma_f32_16x16x32_bf16 v[72:75], v[132:135], v[232:235], v[72:75]
	v_mfma_f32_16x16x32_bf16 v[68:71], v[140:143], v[232:235], v[68:71]
	v_mfma_f32_16x16x32_bf16 v[72:75], v[136:139], v[236:239], v[72:75]
	v_mfma_f32_16x16x32_bf16 v[68:71], v[144:147], v[236:239], v[68:71]
	ds_read_b64_tr_b16 v[132:133], v250
	ds_read_b64_tr_b16 v[134:135], v250 offset:4096
	ds_read_b64_tr_b16 v[136:137], v250 offset:8192
	ds_read_b64_tr_b16 v[138:139], v250 offset:12288
	ds_read_b64_tr_b16 v[140:141], v251
	ds_read_b64_tr_b16 v[142:143], v251 offset:4096
	ds_read_b64_tr_b16 v[144:145], v251 offset:8192
	ds_read_b64_tr_b16 v[146:147], v251 offset:12288
	s_cmp_ge_u32 s98, s70
	s_cbranch_scc1 .Lrx_ndaa
	s_add_u32 s78, s2, 0x70000
	s_addc_u32 s79, s3, 0
	s_mov_b32 m0, s74
	s_nop 0
	global_load_lds_dwordx4 v180, s[84:85]
	s_add_i32 m0, s74, 0x4000
	s_nop 0
	global_load_lds_dwordx4 v184, s[2:3]
	s_add_i32 m0, s74, 0x6000
	s_nop 0
	global_load_lds_dwordx4 v184, s[78:79]
	s_add_u32 s2, s2, 0xe0000
	s_addc_u32 s3, s3, 0
	s_add_u32 s84, s84, 0xe0000
	s_addc_u32 s85, s85, 0
.Lrx_ndaa:
	s_waitcnt lgkmcnt(15)
	v_mfma_f32_16x16x32_bf16 v[148:151], v[84:87], v[32:35], 0
	v_mfma_f32_16x16x32_bf16 v[152:155], v[88:91], v[32:35], 0
	v_mfma_f32_16x16x32_bf16 v[156:159], v[100:103], v[32:35], 0
	v_mfma_f32_16x16x32_bf16 v[160:163], v[104:107], v[32:35], 0
	v_mfma_f32_16x16x32_bf16 v[148:151], v[92:95], v[28:31], v[148:151]
	v_mfma_f32_16x16x32_bf16 v[152:155], v[96:99], v[28:31], v[152:155]
	v_mfma_f32_16x16x32_bf16 v[156:159], v[108:111], v[28:31], v[156:159]
	v_mfma_f32_16x16x32_bf16 v[160:163], v[112:115], v[28:31], v[160:163]
	s_waitcnt lgkmcnt(8)
	v_mfma_f32_16x16x32_bf16 v[64:67], v[116:119], v[232:235], v[64:67]
	v_mfma_f32_16x16x32_bf16 v[60:63], v[124:127], v[232:235], v[60:63]
	v_mfma_f32_16x16x32_bf16 v[64:67], v[120:123], v[236:239], v[64:67]
	v_mfma_f32_16x16x32_bf16 v[60:63], v[128:131], v[236:239], v[60:63]
	s_waitcnt lgkmcnt(0)
	v_mfma_f32_16x16x32_bf16 v[56:59], v[132:135], v[232:235], v[56:59]
	v_mfma_f32_16x16x32_bf16 v[52:55], v[140:143], v[232:235], v[52:55]
	v_mfma_f32_16x16x32_bf16 v[56:59], v[136:139], v[236:239], v[56:59]
	v_mfma_f32_16x16x32_bf16 v[52:55], v[144:147], v[236:239], v[52:55]
	v_add_u32_e32 v215, s72, v188
	v_add_u32_e32 v248, v215, v187
	v_add_u32_e32 v249, v215, v207
	v_add_u32_e32 v250, v215, v226
	v_add_u32_e32 v251, v215, v224
	ds_read_b64_tr_b16 v[116:117], v248
	ds_read_b64_tr_b16 v[118:119], v248 offset:4096
	ds_read_b64_tr_b16 v[120:121], v248 offset:8192
	ds_read_b64_tr_b16 v[122:123], v248 offset:12288
	ds_read_b64_tr_b16 v[124:125], v249
	ds_read_b64_tr_b16 v[126:127], v249 offset:4096
	ds_read_b64_tr_b16 v[128:129], v249 offset:8192
	ds_read_b64_tr_b16 v[130:131], v249 offset:12288
	ds_read_b64_tr_b16 v[132:133], v250
	ds_read_b64_tr_b16 v[134:135], v250 offset:4096
	ds_read_b64_tr_b16 v[136:137], v250 offset:8192
	ds_read_b64_tr_b16 v[138:139], v250 offset:12288
	ds_read_b64_tr_b16 v[140:141], v251
	ds_read_b64_tr_b16 v[142:143], v251 offset:4096
	ds_read_b64_tr_b16 v[144:145], v251 offset:8192
	ds_read_b64_tr_b16 v[146:147], v251 offset:12288
	s_cmp_lg_u32 s98, s83
	s_cbranch_scc1 .Lrx_daaa
	v_mul_f32_e32 v212, v189, v148
	v_cndmask_b32_e64 v148, v148, v212, s[0:1]
	v_mul_f32_e32 v212, v190, v149
	v_cndmask_b32_e64 v149, v149, v212, s[68:69]
	v_mul_f32_e32 v212, v191, v150
	v_cndmask_b32_e64 v150, v150, v212, s[4:5]
	v_mul_f32_e32 v212, v192, v151
	v_cndmask_b32_e64 v151, v151, v212, s[6:7]
	v_mul_f32_e32 v212, v193, v152
	v_cndmask_b32_e64 v152, v152, v212, s[8:9]
	v_mul_f32_e32 v212, v194, v153
	v_cndmask_b32_e64 v153, v153, v212, s[10:11]
	v_mul_f32_e32 v212, v195, v154
	v_cndmask_b32_e64 v154, v154, v212, s[12:13]
	v_mul_f32_e32 v212, v196, v155
	v_cndmask_b32_e64 v155, v155, v212, s[14:15]
	v_mul_f32_e32 v212, v197, v156
	v_cndmask_b32_e64 v156, v156, v212, s[16:17]
	v_mul_f32_e32 v212, v198, v157
	v_cndmask_b32_e64 v157, v157, v212, s[18:19]
	v_mul_f32_e32 v212, v199, v158
	v_cndmask_b32_e64 v158, v158, v212, s[20:21]
	v_mul_f32_e32 v212, v200, v159
	v_cndmask_b32_e64 v159, v159, v212, s[22:23]
	v_mul_f32_e32 v212, v203, v160
	v_cndmask_b32_e64 v160, v160, v212, s[24:25]
	v_mul_f32_e32 v212, v206, v161
	v_cndmask_b32_e64 v161, v161, v212, s[26:27]
	v_mul_f32_e32 v212, v209, v162
	v_cndmask_b32_e64 v162, v162, v212, s[28:29]
	v_mul_f32_e32 v212, v211, v163
	v_cndmask_b32_e64 v163, v163, v212, s[34:35]
.Lrx_daaa:
	v_cvt_pk_bf16_f32 v232, v148, v149
	v_cvt_pk_bf16_f32 v233, v150, v151
	v_cvt_pk_bf16_f32 v234, v152, v153
	v_cvt_pk_bf16_f32 v235, v154, v155
	v_cvt_pk_bf16_f32 v236, v156, v157
	v_cvt_pk_bf16_f32 v237, v158, v159
	v_cvt_pk_bf16_f32 v238, v160, v161
	v_cvt_pk_bf16_f32 v239, v162, v163
	s_branch .Lrx_end
.Lrx_sapab:
	s_waitcnt lgkmcnt(0)
	v_add_u32_e32 v212, s72, v201
	v_add_u32_e32 v213, v212, v204
	v_add_u32_e32 v214, v212, v205
	ds_read_b128 v[84:87], v213
	ds_read_b128 v[88:91], v213 offset:2048
	ds_read_b128 v[92:95], v214
	ds_read_b128 v[96:99], v214 offset:2048
	ds_read_b128 v[100:103], v213 offset:4096
	ds_read_b128 v[104:107], v213 offset:6144
	ds_read_b128 v[108:111], v214 offset:4096
	ds_read_b128 v[112:115], v214 offset:6144
	v_add_u32_e32 v215, s73, v188
	v_add_u32_e32 v248, v215, v221
	v_add_u32_e32 v249, v215, v220
	v_add_u32_e32 v250, v215, v217
	v_add_u32_e32 v251, v215, v216
	v_mfma_f32_16x16x32_bf16 v[80:83], v[116:119], v[232:235], v[80:83]
	v_mfma_f32_16x16x32_bf16 v[76:79], v[124:127], v[232:235], v[76:79]
	v_mfma_f32_16x16x32_bf16 v[48:51], v[116:119], v[240:243], v[48:51]
	v_mfma_f32_16x16x32_bf16 v[44:47], v[124:127], v[240:243], v[44:47]
	v_mfma_f32_16x16x32_bf16 v[80:83], v[120:123], v[236:239], v[80:83]
	v_mfma_f32_16x16x32_bf16 v[76:79], v[128:131], v[236:239], v[76:79]
	v_mfma_f32_16x16x32_bf16 v[48:51], v[120:123], v[244:247], v[48:51]
	v_mfma_f32_16x16x32_bf16 v[44:47], v[128:131], v[244:247], v[44:47]
	ds_read_b64_tr_b16 v[116:117], v248
	ds_read_b64_tr_b16 v[118:119], v248 offset:4096
	ds_read_b64_tr_b16 v[120:121], v248 offset:8192
	ds_read_b64_tr_b16 v[122:123], v248 offset:12288
	ds_read_b64_tr_b16 v[124:125], v249
	ds_read_b64_tr_b16 v[126:127], v249 offset:4096
	ds_read_b64_tr_b16 v[128:129], v249 offset:8192
	ds_read_b64_tr_b16 v[130:131], v249 offset:12288
	v_mfma_f32_16x16x32_bf16 v[72:75], v[132:135], v[232:235], v[72:75]
	v_mfma_f32_16x16x32_bf16 v[68:71], v[140:143], v[232:235], v[68:71]
	v_mfma_f32_16x16x32_bf16 v[40:43], v[132:135], v[240:243], v[40:43]
	v_mfma_f32_16x16x32_bf16 v[36:39], v[140:143], v[240:243], v[36:39]
	v_mfma_f32_16x16x32_bf16 v[72:75], v[136:139], v[236:239], v[72:75]
	v_mfma_f32_16x16x32_bf16 v[68:71], v[144:147], v[236:239], v[68:71]
	v_mfma_f32_16x16x32_bf16 v[40:43], v[136:139], v[244:247], v[40:43]
	v_mfma_f32_16x16x32_bf16 v[36:39], v[144:147], v[244:247], v[36:39]
	ds_read_b64_tr_b16 v[132:133], v250
	ds_read_b64_tr_b16 v[134:135], v250 offset:4096
	ds_read_b64_tr_b16 v[136:137], v250 offset:8192
	ds_read_b64_tr_b16 v[138:139], v250 offset:12288
	ds_read_b64_tr_b16 v[140:141], v251
	ds_read_b64_tr_b16 v[142:143], v251 offset:4096
	ds_read_b64_tr_b16 v[144:145], v251 offset:8192
	ds_read_b64_tr_b16 v[146:147], v251 offset:12288
	s_cmp_ge_u32 s98, s70
	s_cbranch_scc1 .Lrx_ndab
	s_add_u32 s78, s2, 0x70000
	s_addc_u32 s79, s3, 0
	s_mov_b32 m0, s74
	s_nop 0
	global_load_lds_dwordx4 v180, s[84:85]
	s_add_i32 m0, s74, 0x4000
	s_nop 0
	global_load_lds_dwordx4 v184, s[2:3]
	s_add_i32 m0, s74, 0x6000
	s_nop 0
	global_load_lds_dwordx4 v184, s[78:79]
	s_add_u32 s2, s2, 0xe0000
	s_addc_u32 s3, s3, 0
	s_add_u32 s84, s84, 0xe0000
	s_addc_u32 s85, s85, 0
.Lrx_ndab:
	s_waitcnt lgkmcnt(15)
	v_mfma_f32_16x16x32_bf16 v[148:151], v[84:87], v[32:35], 0
	v_mfma_f32_16x16x32_bf16 v[152:155], v[88:91], v[32:35], 0
	v_mfma_f32_16x16x32_bf16 v[156:159], v[100:103], v[32:35], 0
	v_mfma_f32_16x16x32_bf16 v[160:163], v[104:107], v[32:35], 0
	v_mfma_f32_16x16x32_bf16 v[148:151], v[92:95], v[28:31], v[148:151]
	v_mfma_f32_16x16x32_bf16 v[152:155], v[96:99], v[28:31], v[152:155]
	v_mfma_f32_16x16x32_bf16 v[156:159], v[108:111], v[28:31], v[156:159]
	v_mfma_f32_16x16x32_bf16 v[160:163], v[112:115], v[28:31], v[160:163]
	s_waitcnt lgkmcnt(8)
	v_mfma_f32_16x16x32_bf16 v[64:67], v[116:119], v[232:235], v[64:67]
	v_mfma_f32_16x16x32_bf16 v[60:63], v[124:127], v[232:235], v[60:63]
	v_mfma_f32_16x16x32_bf16 v[24:27], v[116:119], v[240:243], v[24:27]
	v_mfma_f32_16x16x32_bf16 v[20:23], v[124:127], v[240:243], v[20:23]
	v_mfma_f32_16x16x32_bf16 v[64:67], v[120:123], v[236:239], v[64:67]
	v_mfma_f32_16x16x32_bf16 v[60:63], v[128:131], v[236:239], v[60:63]
	v_mfma_f32_16x16x32_bf16 v[24:27], v[120:123], v[244:247], v[24:27]
	v_mfma_f32_16x16x32_bf16 v[20:23], v[128:131], v[244:247], v[20:23]
	s_waitcnt lgkmcnt(0)
	v_mfma_f32_16x16x32_bf16 v[56:59], v[132:135], v[232:235], v[56:59]
	v_mfma_f32_16x16x32_bf16 v[52:55], v[140:143], v[232:235], v[52:55]
	v_mfma_f32_16x16x32_bf16 v[16:19], v[132:135], v[240:243], v[16:19]
	v_mfma_f32_16x16x32_bf16 v[12:15], v[140:143], v[240:243], v[12:15]
	v_mfma_f32_16x16x32_bf16 v[56:59], v[136:139], v[236:239], v[56:59]
	v_mfma_f32_16x16x32_bf16 v[52:55], v[144:147], v[236:239], v[52:55]
	v_mfma_f32_16x16x32_bf16 v[16:19], v[136:139], v[244:247], v[16:19]
	v_mfma_f32_16x16x32_bf16 v[12:15], v[144:147], v[244:247], v[12:15]
	v_add_u32_e32 v215, s72, v188
	v_add_u32_e32 v248, v215, v187
	v_add_u32_e32 v249, v215, v207
	v_add_u32_e32 v250, v215, v226
	v_add_u32_e32 v251, v215, v224
	ds_read_b64_tr_b16 v[116:117], v248
	ds_read_b64_tr_b16 v[118:119], v248 offset:4096
	ds_read_b64_tr_b16 v[120:121], v248 offset:8192
	ds_read_b64_tr_b16 v[122:123], v248 offset:12288
	ds_read_b64_tr_b16 v[124:125], v249
	ds_read_b64_tr_b16 v[126:127], v249 offset:4096
	ds_read_b64_tr_b16 v[128:129], v249 offset:8192
	ds_read_b64_tr_b16 v[130:131], v249 offset:12288
	ds_read_b64_tr_b16 v[132:133], v250
	ds_read_b64_tr_b16 v[134:135], v250 offset:4096
	ds_read_b64_tr_b16 v[136:137], v250 offset:8192
	ds_read_b64_tr_b16 v[138:139], v250 offset:12288
	ds_read_b64_tr_b16 v[140:141], v251
	ds_read_b64_tr_b16 v[142:143], v251 offset:4096
	ds_read_b64_tr_b16 v[144:145], v251 offset:8192
	ds_read_b64_tr_b16 v[146:147], v251 offset:12288
	s_cmp_lg_u32 s98, s83
	s_cbranch_scc1 .Lrx_daab
	v_mul_f32_e32 v212, v189, v148
	v_cndmask_b32_e64 v148, v148, v212, s[0:1]
	v_mul_f32_e32 v212, v190, v149
	v_cndmask_b32_e64 v149, v149, v212, s[68:69]
	v_mul_f32_e32 v212, v191, v150
	v_cndmask_b32_e64 v150, v150, v212, s[4:5]
	v_mul_f32_e32 v212, v192, v151
	v_cndmask_b32_e64 v151, v151, v212, s[6:7]
	v_mul_f32_e32 v212, v193, v152
	v_cndmask_b32_e64 v152, v152, v212, s[8:9]
	v_mul_f32_e32 v212, v194, v153
	v_cndmask_b32_e64 v153, v153, v212, s[10:11]
	v_mul_f32_e32 v212, v195, v154
	v_cndmask_b32_e64 v154, v154, v212, s[12:13]
	v_mul_f32_e32 v212, v196, v155
	v_cndmask_b32_e64 v155, v155, v212, s[14:15]
	v_mul_f32_e32 v212, v197, v156
	v_cndmask_b32_e64 v156, v156, v212, s[16:17]
	v_mul_f32_e32 v212, v198, v157
	v_cndmask_b32_e64 v157, v157, v212, s[18:19]
	v_mul_f32_e32 v212, v199, v158
	v_cndmask_b32_e64 v158, v158, v212, s[20:21]
	v_mul_f32_e32 v212, v200, v159
	v_cndmask_b32_e64 v159, v159, v212, s[22:23]
	v_mul_f32_e32 v212, v203, v160
	v_cndmask_b32_e64 v160, v160, v212, s[24:25]
	v_mul_f32_e32 v212, v206, v161
	v_cndmask_b32_e64 v161, v161, v212, s[26:27]
	v_mul_f32_e32 v212, v209, v162
	v_cndmask_b32_e64 v162, v162, v212, s[28:29]
	v_mul_f32_e32 v212, v211, v163
	v_cndmask_b32_e64 v163, v163, v212, s[34:35]

.Lrx_ndbb:
	s_waitcnt lgkmcnt(15)
	v_mfma_f32_16x16x32_bf16 v[148:151], v[84:87], v[32:35], 0
	v_mfma_f32_16x16x32_bf16 v[152:155], v[88:91], v[32:35], 0
	v_mfma_f32_16x16x32_bf16 v[156:159], v[100:103], v[32:35], 0
	v_mfma_f32_16x16x32_bf16 v[160:163], v[104:107], v[32:35], 0
	v_mfma_f32_16x16x32_bf16 v[148:151], v[92:95], v[28:31], v[148:151]
	v_mfma_f32_16x16x32_bf16 v[152:155], v[96:99], v[28:31], v[152:155]
	v_mfma_f32_16x16x32_bf16 v[156:159], v[108:111], v[28:31], v[156:159]
	v_mfma_f32_16x16x32_bf16 v[160:163], v[112:115], v[28:31], v[160:163]
	v_mfma_f32_16x16x32_bf16 v[164:167], v[84:87], v[8:11], 0
	v_mfma_f32_16x16x32_bf16 v[168:171], v[88:91], v[8:11], 0
	v_mfma_f32_16x16x32_bf16 v[172:175], v[100:103], v[8:11], 0
	v_mfma_f32_16x16x32_bf16 v[176:179], v[104:107], v[8:11], 0
	v_mfma_f32_16x16x32_bf16 v[164:167], v[92:95], v[4:7], v[164:167]
	v_mfma_f32_16x16x32_bf16 v[168:171], v[96:99], v[4:7], v[168:171]
	v_mfma_f32_16x16x32_bf16 v[172:175], v[108:111], v[4:7], v[172:175]
	v_mfma_f32_16x16x32_bf16 v[176:179], v[112:115], v[4:7], v[176:179]
	s_waitcnt lgkmcnt(8)
	v_mfma_f32_16x16x32_bf16 v[64:67], v[116:119], v[232:235], v[64:67]
	v_mfma_f32_16x16x32_bf16 v[60:63], v[124:127], v[232:235], v[60:63]
	v_mfma_f32_16x16x32_bf16 v[24:27], v[116:119], v[240:243], v[24:27]
	v_mfma_f32_16x16x32_bf16 v[20:23], v[124:127], v[240:243], v[20:23]
	v_mfma_f32_16x16x32_bf16 v[64:67], v[120:123], v[236:239], v[64:67]
	v_mfma_f32_16x16x32_bf16 v[60:63], v[128:131], v[236:239], v[60:63]
	v_mfma_f32_16x16x32_bf16 v[24:27], v[120:123], v[244:247], v[24:27]
	v_mfma_f32_16x16x32_bf16 v[20:23], v[128:131], v[244:247], v[20:23]
	s_waitcnt lgkmcnt(0)
	v_mfma_f32_16x16x32_bf16 v[56:59], v[132:135], v[232:235], v[56:59]
	v_mfma_f32_16x16x32_bf16 v[52:55], v[140:143], v[232:235], v[52:55]
	v_mfma_f32_16x16x32_bf16 v[16:19], v[132:135], v[240:243], v[16:19]
	v_mfma_f32_16x16x32_bf16 v[12:15], v[140:143], v[240:243], v[12:15]
	v_mfma_f32_16x16x32_bf16 v[56:59], v[136:139], v[236:239], v[56:59]
	v_mfma_f32_16x16x32_bf16 v[52:55], v[144:147], v[236:239], v[52:55]
	v_mfma_f32_16x16x32_bf16 v[16:19], v[136:139], v[244:247], v[16:19]
	v_mfma_f32_16x16x32_bf16 v[12:15], v[144:147], v[244:247], v[12:15]
	v_add_u32_e32 v215, s72, v188
	v_add_u32_e32 v248, v215, v187
	v_add_u32_e32 v249, v215, v207
	v_add_u32_e32 v250, v215, v226
	v_add_u32_e32 v251, v215, v224
	ds_read_b64_tr_b16 v[116:117], v248
	ds_read_b64_tr_b16 v[118:119], v248 offset:4096
	ds_read_b64_tr_b16 v[120:121], v248 offset:8192
	ds_read_b64_tr_b16 v[122:123], v248 offset:12288
	ds_read_b64_tr_b16 v[124:125], v249
	ds_read_b64_tr_b16 v[126:127], v249 offset:4096
	ds_read_b64_tr_b16 v[128:129], v249 offset:8192
	ds_read_b64_tr_b16 v[130:131], v249 offset:12288
	ds_read_b64_tr_b16 v[132:133], v250
	ds_read_b64_tr_b16 v[134:135], v250 offset:4096
	ds_read_b64_tr_b16 v[136:137], v250 offset:8192
	ds_read_b64_tr_b16 v[138:139], v250 offset:12288
	ds_read_b64_tr_b16 v[140:141], v251
	ds_read_b64_tr_b16 v[142:143], v251 offset:4096
	ds_read_b64_tr_b16 v[144:145], v251 offset:8192
	ds_read_b64_tr_b16 v[146:147], v251 offset:12288
	s_cmp_lg_u32 s98, s83
	s_cbranch_scc1 .Lrx_dabb
	v_mul_f32_e32 v212, v189, v148
	v_cndmask_b32_e64 v148, v148, v212, s[0:1]
	v_mul_f32_e32 v212, v190, v149
	v_cndmask_b32_e64 v149, v149, v212, s[68:69]
	v_mul_f32_e32 v212, v191, v150
	v_cndmask_b32_e64 v150, v150, v212, s[4:5]
	v_mul_f32_e32 v212, v192, v151
	v_cndmask_b32_e64 v151, v151, v212, s[6:7]
	v_mul_f32_e32 v212, v193, v152
	v_cndmask_b32_e64 v152, v152, v212, s[8:9]
	v_mul_f32_e32 v212, v194, v153
	v_cndmask_b32_e64 v153, v153, v212, s[10:11]
	v_mul_f32_e32 v212, v195, v154
	v_cndmask_b32_e64 v154, v154, v212, s[12:13]
	v_mul_f32_e32 v212, v196, v155
	v_cndmask_b32_e64 v155, v155, v212, s[14:15]
	v_mul_f32_e32 v212, v197, v156
	v_cndmask_b32_e64 v156, v156, v212, s[16:17]
	v_mul_f32_e32 v212, v198, v157
	v_cndmask_b32_e64 v157, v157, v212, s[18:19]
	v_mul_f32_e32 v212, v199, v158
	v_cndmask_b32_e64 v158, v158, v212, s[20:21]
	v_mul_f32_e32 v212, v200, v159
	v_cndmask_b32_e64 v159, v159, v212, s[22:23]
	v_mul_f32_e32 v212, v203, v160
	v_cndmask_b32_e64 v160, v160, v212, s[24:25]
	v_mul_f32_e32 v212, v206, v161
	v_cndmask_b32_e64 v161, v161, v212, s[26:27]
	v_mul_f32_e32 v212, v209, v162
	v_cndmask_b32_e64 v162, v162, v212, s[28:29]
	v_mul_f32_e32 v212, v211, v163
	v_cndmask_b32_e64 v163, v163, v212, s[34:35]

; __device__ __forceinline__ void ret_pair(LAS unsigned char* lds, const bf16_t* Z, bf16_t* MIX, int b, int h, int tA, int tB, const float* gain, int wid) {
;     ...
;     int bcur = 0;
;     for (int kt = 0; kt < nkt; ++kt) {
;         const int bnx = (bcur == 2) ? 0 : bcur + 1, bn2 = (bnx == 2) ? 0 : bnx + 1;
;         const bool more2 = (kt + 2 < nkt);
;         if (more2) RP_DMA(kt + 2, bn2);
;         if (kt <= cqA) {
;             if (kt <= cqB) RP_BODY(true); else RP_BODY(false);
;         }
;         if (kt + 1 < nkt) { if (more2) asm volatile("s_waitcnt vmcnt(3) lgkmcnt(0)\n\ts_barrier" ::: "memory"); else asm volatile("s_waitcnt vmcnt(0) lgkmcnt(0)\n\ts_barrier" ::: "memory"); }
;         bcur = bnx;
;     }
.Lrx_dbbb:
	v_cvt_pk_bf16_f32 v240, v164, v165
	v_cvt_pk_bf16_f32 v241, v166, v167
	v_cvt_pk_bf16_f32 v242, v168, v169
	v_cvt_pk_bf16_f32 v243, v170, v171
	v_cvt_pk_bf16_f32 v244, v172, v173
	v_cvt_pk_bf16_f32 v245, v174, v175
	v_cvt_pk_bf16_f32 v246, v176, v177
	v_cvt_pk_bf16_f32 v247, v178, v179
	s_branch .Lrx_end
.Lrx_pvo:
	s_waitcnt lgkmcnt(0)
	v_add_u32_e32 v215, s73, v188
	v_add_u32_e32 v248, v215, v221
	v_add_u32_e32 v249, v215, v220
	v_add_u32_e32 v250, v215, v217
	v_add_u32_e32 v251, v215, v216
	v_mfma_f32_16x16x32_bf16 v[80:83], v[116:119], v[232:235], v[80:83]
	v_mfma_f32_16x16x32_bf16 v[76:79], v[124:127], v[232:235], v[76:79]
	v_mfma_f32_16x16x32_bf16 v[80:83], v[120:123], v[236:239], v[80:83]
	v_mfma_f32_16x16x32_bf16 v[76:79], v[128:131], v[236:239], v[76:79]
	ds_read_b64_tr_b16 v[116:117], v248
	ds_read_b64_tr_b16 v[118:119], v248 offset:4096
	ds_read_b64_tr_b16 v[120:121], v248 offset:8192
	ds_read_b64_tr_b16 v[122:123], v248 offset:12288
	ds_read_b64_tr_b16 v[124:125], v249
	ds_read_b64_tr_b16 v[126:127], v249 offset:4096
	ds_read_b64_tr_b16 v[128:129], v249 offset:8192
	ds_read_b64_tr_b16 v[130:131], v249 offset:12288
	v_mfma_f32_16x16x32_bf16 v[72:75], v[132:135], v[232:235], v[72:75]
	v_mfma_f32_16x16x32_bf16 v[68:71], v[140:143], v[232:235], v[68:71]
	v_mfma_f32_16x16x32_bf16 v[72:75], v[136:139], v[236:239], v[72:75]
	v_mfma_f32_16x16x32_bf16 v[68:71], v[144:147], v[236:239], v[68:71]
	ds_read_b64_tr_b16 v[132:133], v250
	ds_read_b64_tr_b16 v[134:135], v250 offset:4096
	ds_read_b64_tr_b16 v[136:137], v250 offset:8192
	ds_read_b64_tr_b16 v[138:139], v250 offset:12288
	ds_read_b64_tr_b16 v[140:141], v251
	ds_read_b64_tr_b16 v[142:143], v251 offset:4096
	ds_read_b64_tr_b16 v[144:145], v251 offset:8192
	ds_read_b64_tr_b16 v[146:147], v251 offset:12288
	s_waitcnt lgkmcnt(8)
	v_mfma_f32_16x16x32_bf16 v[64:67], v[116:119], v[232:235], v[64:67]
	v_mfma_f32_16x16x32_bf16 v[60:63], v[124:127], v[232:235], v[60:63]
	v_mfma_f32_16x16x32_bf16 v[64:67], v[120:123], v[236:239], v[64:67]
	v_mfma_f32_16x16x32_bf16 v[60:63], v[128:131], v[236:239], v[60:63]
	s_waitcnt lgkmcnt(0)
	v_mfma_f32_16x16x32_bf16 v[56:59], v[132:135], v[232:235], v[56:59]
	v_mfma_f32_16x16x32_bf16 v[52:55], v[140:143], v[232:235], v[52:55]
	v_mfma_f32_16x16x32_bf16 v[56:59], v[136:139], v[236:239], v[56:59]
	v_mfma_f32_16x16x32_bf16 v[52:55], v[144:147], v[236:239], v[52:55]
.Lrx_end:
	s_add_i32 s98, s98, 1
	s_add_i32 s75, s70, 2
	s_cmp_ge_u32 s98, s75
	s_cbranch_scc1 .Lrx_exit
	s_cmp_le_u32 s98, s70
	s_cbranch_scc0 .Lrx_wz
	s_waitcnt vmcnt(3)
	s_branch .Lrx_bar

; __device__ __forceinline__ int lane_id() { return (int)__builtin_amdgcn_mbcnt_hi(~0u, __builtin_amdgcn_mbcnt_lo(~0u, 0u)); }
; __device__ __forceinline__ void ret_pair(LAS unsigned char* lds, const bf16_t* Z, bf16_t* MIX, int b, int h, int tA, int tB, const float* gain, int wid) {
;     ...
;     int lf = lane_id(); asm volatile("" : "+v"(lf)); const int q16f = lf & 15, quadf = (lf >> 4) & 3;
; #pragma unroll
;     for (int which = 0; which < 2; ++which) {
;         f32x4 (&O)[8] = which ? OB : OA;
;         float ss = 0.f;
; #pragma unroll
;         for (int eb = 0; eb < 8; ++eb)
; #pragma unroll
;             for (int i = 0; i < 4; ++i) ss += O[eb][i] * O[eb][i];
;         ss = quad_sum(ss);
;         const float r = rsqrtf(ss * (1.0f / 128.0f) + EPS);
;         const int row = (which ? rowB0 : rowA0) + q16f;
;         const bf16_t* gp = Z + (size_t)row * DIN + gcol + 4 * quadf;
;         bf16_t* op = MIX + (size_t)row * DM + 128 * h + 4 * quadf;
; #pragma unroll
;         for (int eb = 0; eb < 8; ++eb) {
;             const u32x2 gw = *(const u32x2*)(gp + 16 * eb);
;             const f32x4 gn = *(const f32x4*)(gain + 16 * eb + 4 * quadf);
.Lrx_exit:
	s_add_i32 s75, s70, 1
	s_cmp_le_u32 s75, s83
	s_cbranch_scc0 .Lrx_done
	s_and_b32 s73, s75, 3
	s_lshl_b32 s73, s73, 15
	s_waitcnt lgkmcnt(0)
	v_add_u32_e32 v215, s73, v188
	v_add_u32_e32 v248, v215, v221
	v_add_u32_e32 v249, v215, v220
	v_add_u32_e32 v250, v215, v217
	v_add_u32_e32 v251, v215, v216
	v_mfma_f32_16x16x32_bf16 v[80:83], v[116:119], v[232:235], v[80:83]
	v_mfma_f32_16x16x32_bf16 v[76:79], v[124:127], v[232:235], v[76:79]
	v_mfma_f32_16x16x32_bf16 v[80:83], v[120:123], v[236:239], v[80:83]
	v_mfma_f32_16x16x32_bf16 v[76:79], v[128:131], v[236:239], v[76:79]
	ds_read_b64_tr_b16 v[116:117], v248
	ds_read_b64_tr_b16 v[118:119], v248 offset:4096
	ds_read_b64_tr_b16 v[120:121], v248 offset:8192
	ds_read_b64_tr_b16 v[122:123], v248 offset:12288
	ds_read_b64_tr_b16 v[124:125], v249
	ds_read_b64_tr_b16 v[126:127], v249 offset:4096
	ds_read_b64_tr_b16 v[128:129], v249 offset:8192
	ds_read_b64_tr_b16 v[130:131], v249 offset:12288
	v_mfma_f32_16x16x32_bf16 v[72:75], v[132:135], v[232:235], v[72:75]
	v_mfma_f32_16x16x32_bf16 v[68:71], v[140:143], v[232:235], v[68:71]
	v_mfma_f32_16x16x32_bf16 v[72:75], v[136:139], v[236:239], v[72:75]
	v_mfma_f32_16x16x32_bf16 v[68:71], v[144:147], v[236:239], v[68:71]
	ds_read_b64_tr_b16 v[132:133], v250
	ds_read_b64_tr_b16 v[134:135], v250 offset:4096
	ds_read_b64_tr_b16 v[136:137], v250 offset:8192
	ds_read_b64_tr_b16 v[138:139], v250 offset:12288
	ds_read_b64_tr_b16 v[140:141], v251
	ds_read_b64_tr_b16 v[142:143], v251 offset:4096
	ds_read_b64_tr_b16 v[144:145], v251 offset:8192
	ds_read_b64_tr_b16 v[146:147], v251 offset:12288
	s_waitcnt lgkmcnt(8)
	v_mfma_f32_16x16x32_bf16 v[64:67], v[116:119], v[232:235], v[64:67]
	v_mfma_f32_16x16x32_bf16 v[60:63], v[124:127], v[232:235], v[60:63]
	v_mfma_f32_16x16x32_bf16 v[64:67], v[120:123], v[236:239], v[64:67]
	v_mfma_f32_16x16x32_bf16 v[60:63], v[128:131], v[236:239], v[60:63]
	s_waitcnt lgkmcnt(0)
	v_mfma_f32_16x16x32_bf16 v[56:59], v[132:135], v[232:235], v[56:59]
	v_mfma_f32_16x16x32_bf16 v[52:55], v[140:143], v[232:235], v[52:55]
	v_mfma_f32_16x16x32_bf16 v[56:59], v[136:139], v[236:239], v[56:59]
	v_mfma_f32_16x16x32_bf16 v[52:55], v[144:147], v[236:239], v[52:55]
.Lrx_done:
	v_readlane_b32 s26, v255, 5
	v_readlane_b32 s30, v254, 37
	v_readlane_b32 s66, v254, 33
	v_readlane_b32 s27, v255, 6
	v_readlane_b32 s28, v254, 36
	v_readlane_b32 s31, v254, 38
	v_readlane_b32 s29, v254, 41
	v_readlane_b32 s34, v254, 42
	v_readlane_b32 s35, v254, 43
	s_movk_i32 s36, 0x3800
	s_mov_b64 s[14:15], 0x1800
	s_movk_i32 s16, 0x1000
	s_movk_i32 s37, 0x1c00
	v_readlane_b32 s17, v254, 44
	v_readlane_b32 s38, v254, 45
	v_readlane_b32 s39, v254, 46
	v_readlane_b32 s18, v254, 47
	v_readlane_b32 s40, v254, 48
	v_readlane_b32 s41, v254, 49
	s_movk_i32 s67, 0xe0
	s_movk_i32 s73, 0x60
	v_readlane_b32 s43, v254, 50
	v_readlane_b32 s44, v255, 2
	v_readlane_b32 s5, v255, 4
	v_readlane_b32 s88, v254, 39
	v_readlane_b32 s89, v254, 40
	v_readlane_b32 s84, v254, 34
	v_readlane_b32 s85, v254, 35
	v_readlane_b32 s95, v255, 1
	v_readlane_b32 s78, v254, 32
	s_movk_i32 s74, 0x80
	s_movk_i32 s75, 0xa0
	s_movk_i32 s79, 0xc0
.LBB0_640:
	s_lshl_b32 s0, s80, 2
	v_readlane_b32 s1, v254, 24
	s_add_u32 s0, s1, s0
	v_readlane_b32 s1, v254, 23
	v_readlane_b32 s2, v255, 3
	s_waitcnt lgkmcnt(0)
	v_mov_b32_e32 v4, v183
	s_addc_u32 s1, s1, 0
	s_add_i32 s4, s2, 1
	s_add_u32 s2, s30, s86
	v_and_b32_e32 v93, 15, v4
	v_lshrrev_b32_e32 v4, 2, v4
	s_addc_u32 s3, s31, 0
	v_and_b32_e32 v4, 12, v4
	v_lshlrev_b32_e32 v180, 1, v4
	v_lshlrev_b32_e32 v4, 2, v4
	v_mov_b32_e32 v5, v181
	v_or_b32_e32 v32, s5, v93
	v_mov_b64_e32 v[6:7], s[2:3]
	v_lshl_add_u64 v[4:5], s[0:1], 0, v[4:5]
	v_readlane_b32 s3, v255, 7
	s_mov_b64 s[6:7], 0x1000
	v_mad_i64_i32 v[8:9], vcc, v32, s36, v[6:7]
	v_mov_b32_e32 v29, v181
	v_or_b32_e32 v30, s3, v93
	v_lshl_add_u64 v[10:11], v[8:9], 0, v[180:181]
	v_mad_i64_i32 v[6:7], vcc, v30, s36, v[6:7]
	v_lshl_add_u64 v[10:11], v[10:11], 0, s[6:7]
	v_lshl_add_u64 v[6:7], v[6:7], 0, v[180:181]
	s_add_u32 s0, s88, s86
	s_addc_u32 s1, s89, 0
	v_lshl_add_u64 v[6:7], v[6:7], 0, s[6:7]
	global_load_dwordx4 v[96:99], v[4:5], off
	global_load_dwordx2 v[134:135], v[10:11], off
	global_load_dwordx2 v[150:151], v[6:7], off
	global_load_dwordx4 v[100:103], v[4:5], off offset:64
	global_load_dwordx2 v[136:137], v[10:11], off offset:32
	global_load_dwordx2 v[152:153], v[6:7], off offset:32
	global_load_dwordx4 v[104:107], v[4:5], off offset:128
	global_load_dwordx2 v[138:139], v[10:11], off offset:64
	global_load_dwordx2 v[154:155], v[6:7], off offset:64
	global_load_dwordx4 v[108:111], v[4:5], off offset:192
	global_load_dwordx2 v[140:141], v[10:11], off offset:96
	global_load_dwordx2 v[156:157], v[6:7], off offset:96
	global_load_dwordx4 v[112:115], v[4:5], off offset:256
	global_load_dwordx2 v[142:143], v[10:11], off offset:128
	global_load_dwordx2 v[158:159], v[6:7], off offset:128
	global_load_dwordx4 v[116:119], v[4:5], off offset:320
	global_load_dwordx2 v[144:145], v[10:11], off offset:160
	global_load_dwordx2 v[160:161], v[6:7], off offset:160
	global_load_dwordx4 v[120:123], v[4:5], off offset:384
	global_load_dwordx2 v[146:147], v[10:11], off offset:192
	global_load_dwordx2 v[162:163], v[6:7], off offset:192
	global_load_dwordx4 v[124:127], v[4:5], off offset:448
	global_load_dwordx2 v[148:149], v[10:11], off offset:224
	global_load_dwordx2 v[164:165], v[6:7], off offset:224
	v_lshl_add_u64 v[8:9], s[0:1], 0, v[180:181]
	v_mov_b32_e32 v28, v32
	v_mov_b32_e32 v31, v181
	v_lshlrev_b64 v[28:29], 12, v[28:29]
	v_lshlrev_b64 v[30:31], 12, v[30:31]
	v_lshl_add_u64 v[166:167], v[8:9], 0, v[28:29]
	v_lshl_add_u64 v[168:169], v[8:9], 0, v[30:31]
	v_mul_f32_e32 v33, v81, v81
	v_fmac_f32_e32 v33, v80, v80
	v_fmac_f32_e32 v33, v82, v82
	v_fmac_f32_e32 v33, v83, v83
	v_fmac_f32_e32 v33, v76, v76
	v_fmac_f32_e32 v33, v77, v77
	v_fmac_f32_e32 v33, v78, v78
	v_fmac_f32_e32 v33, v79, v79
	v_fmac_f32_e32 v33, v72, v72
	v_fmac_f32_e32 v33, v73, v73
	v_fmac_f32_e32 v33, v74, v74
	v_fmac_f32_e32 v33, v75, v75
	v_fmac_f32_e32 v33, v68, v68
	v_fmac_f32_e32 v33, v69, v69
	v_fmac_f32_e32 v33, v70, v70
	v_fmac_f32_e32 v33, v71, v71
	v_fmac_f32_e32 v33, v64, v64
	v_fmac_f32_e32 v33, v65, v65
	v_fmac_f32_e32 v33, v66, v66
	v_fmac_f32_e32 v33, v67, v67
	v_fmac_f32_e32 v33, v60, v60
	v_fmac_f32_e32 v33, v61, v61
	v_fmac_f32_e32 v33, v62, v62
	v_fmac_f32_e32 v33, v63, v63
	v_pk_mul_f32 v[84:85], v[56:57], v[56:57]
	v_pk_mul_f32 v[8:9], v[58:59], v[58:59]
	v_add_f32_e32 v33, v84, v33
	v_add_f32_e32 v33, v85, v33
	v_add_f32_e32 v8, v8, v33
	v_add_f32_e32 v33, v9, v8
	v_pk_mul_f32 v[84:85], v[52:53], v[52:53]
	v_pk_mul_f32 v[8:9], v[54:55], v[54:55]
	v_add_f32_e32 v33, v84, v33
	v_add_f32_e32 v33, v85, v33
	v_add_f32_e32 v8, v8, v33
	v_add_f32_e32 v33, v9, v8
	ds_swizzle_b32 v84, v33 offset:swizzle(SWAP,16)
	v_pk_mul_f32 v[90:91], v[16:17], v[16:17]
	v_pk_mul_f32 v[88:89], v[18:19], v[18:19]
	s_waitcnt lgkmcnt(0)
; __device__ __forceinline__ unsigned cvtpk(float lo, float hi) { f32x2 v = {lo, hi}; bf16x2_t b = __builtin_convertvector(v, bf16x2_t); return __builtin_bit_cast(unsigned, b); }
; __device__ __forceinline__ float bflo(unsigned u) { return __uint_as_float(u << 16); }
; __device__ __forceinline__ float bfhi(unsigned u) { return __uint_as_float(u & 0xffff0000u); }
; __device__ __forceinline__ void ret_pair(LAS unsigned char* lds, const bf16_t* Z, bf16_t* MIX, int b, int h, int tA, int tB, const float* gain, int wid) {
;     ...
;         float ss = 0.f;
; #pragma unroll
;         for (int eb = 0; eb < 8; ++eb)
; #pragma unroll
;             for (int i = 0; i < 4; ++i) ss += O[eb][i] * O[eb][i];
;         ss = quad_sum(ss);
;         const float r = rsqrtf(ss * (1.0f / 128.0f) + EPS);
;         const int row = (which ? rowB0 : rowA0) + q16f;
;         const bf16_t* gp = Z + (size_t)row * DIN + gcol + 4 * quadf;
;         bf16_t* op = MIX + (size_t)row * DM + 128 * h + 4 * quadf;
; #pragma unroll
;         for (int eb = 0; eb < 8; ++eb) {
;             const u32x2 gw = *(const u32x2*)(gp + 16 * eb);
;             const f32x4 gn = *(const f32x4*)(gain + 16 * eb + 4 * quadf);
;             u32x2 w; w.x = cvtpk(O[eb][0] * r * gn.x * bflo(gw.x), O[eb][1] * r * gn.y * bfhi(gw.x));
;             w.y = cvtpk(O[eb][2] * r * gn.z * bflo(gw.y), O[eb][3] * r * gn.w * bfhi(gw.y));
;             *(u32x2*)(op + 16 * eb) = w;
;         }
	v_add_f32_e32 v85, v33, v84
	v_mul_f32_e32 v84, v49, v49
	v_fmac_f32_e32 v84, v48, v48
	v_fmac_f32_e32 v84, v50, v50
	v_fmac_f32_e32 v84, v51, v51
	v_fmac_f32_e32 v84, v44, v44
	v_fmac_f32_e32 v84, v45, v45
	v_fmac_f32_e32 v84, v46, v46
	v_fmac_f32_e32 v84, v47, v47
	v_fmac_f32_e32 v84, v40, v40
	v_fmac_f32_e32 v84, v41, v41
	v_fmac_f32_e32 v84, v42, v42
	v_fmac_f32_e32 v84, v43, v43
	v_fmac_f32_e32 v84, v36, v36
	v_fmac_f32_e32 v84, v37, v37
	v_fmac_f32_e32 v84, v38, v38
	v_fmac_f32_e32 v84, v39, v39
	v_fmac_f32_e32 v84, v24, v24
	v_fmac_f32_e32 v84, v25, v25
	v_fmac_f32_e32 v84, v26, v26
	v_fmac_f32_e32 v84, v27, v27
	v_fmac_f32_e32 v84, v20, v20
	v_fmac_f32_e32 v84, v21, v21
	v_fmac_f32_e32 v84, v22, v22
	v_fmac_f32_e32 v84, v23, v23
	v_add_f32_e32 v84, v90, v84
	v_add_f32_e32 v84, v91, v84
	v_add_f32_e32 v84, v88, v84
	v_add_f32_e32 v84, v89, v84
	v_pk_mul_f32 v[90:91], v[12:13], v[12:13]
	v_pk_mul_f32 v[88:89], v[14:15], v[14:15]
	v_add_f32_e32 v84, v90, v84
	v_add_f32_e32 v84, v91, v84
	v_add_f32_e32 v84, v88, v84
	v_add_f32_e32 v84, v89, v84
	ds_swizzle_b32 v86, v84 offset:swizzle(SWAP,16)
	v_mov_b32_e32 v87, v85
	s_nop 1
	v_permlane32_swap_b32_e32 v85, v87
	s_waitcnt lgkmcnt(0)
	v_add_f32_e32 v84, v84, v86
	v_mov_b32_e32 v86, v84
	s_nop 1
	v_permlane32_swap_b32_e32 v84, v86
	v_pk_add_f32 v[84:85], v[84:85], v[86:87]
	s_brev_b32 s0, 60
	v_mov_b32_e32 v34, 0x358637bd
	v_pk_fma_f32 v[84:85], v[84:85], s[0:1], v[34:35] op_sel_hi:[1,0,0]
	s_mov_b32 s2, 0x800000
	v_mul_f32_e32 v34, 0x4b800000, v85
	v_cmp_gt_f32_e32 vcc, s2, v85
	v_mul_f32_e32 v35, 0x4b800000, v84
	v_cmp_gt_f32_e64 s[0:1], s2, v84
	v_cndmask_b32_e32 v34, v85, v34, vcc
	v_rsq_f32_e32 v85, v34
	v_cndmask_b32_e64 v35, v84, v35, s[0:1]
	v_rsq_f32_e32 v84, v35
	v_mul_f32_e32 v92, 0x45800000, v85
	v_cndmask_b32_e32 v92, v85, v92, vcc
	v_mul_f32_e32 v94, 0x45800000, v84
	v_cndmask_b32_e64 v94, v84, v94, s[0:1]
	s_mov_b32 s87, s27
	s_mov_b32 m0, s90
	s_mov_b32 s42, 0x800000
	s_mov_b32 s5, 0
	s_waitcnt vmcnt(0)
	v_pk_mul_f32 v[80:81], v[80:81], v[92:93] op_sel_hi:[1,0]
	v_pk_mul_f32 v[82:83], v[82:83], v[92:93] op_sel_hi:[1,0]
	v_lshlrev_b32_e32 v28, 16, v134
	v_and_b32_e32 v29, 0xffff0000, v134
	v_lshlrev_b32_e32 v30, 16, v135
	v_and_b32_e32 v31, 0xffff0000, v135
	v_pk_mul_f32 v[80:81], v[96:97], v[80:81]
	v_pk_mul_f32 v[82:83], v[98:99], v[82:83]
	v_pk_mul_f32 v[80:81], v[80:81], v[28:29]
	v_pk_mul_f32 v[82:83], v[82:83], v[30:31]
	v_cvt_pk_bf16_f32 v80, v80, v81
	v_cvt_pk_bf16_f32 v81, v82, v83
	global_store_dwordx2 v[166:167], v[80:81], off
	v_pk_mul_f32 v[48:49], v[48:49], v[94:95] op_sel_hi:[1,0]
	v_pk_mul_f32 v[50:51], v[50:51], v[94:95] op_sel_hi:[1,0]
	v_lshlrev_b32_e32 v170, 16, v150
	v_and_b32_e32 v171, 0xffff0000, v150
	v_lshlrev_b32_e32 v172, 16, v151
	v_and_b32_e32 v173, 0xffff0000, v151
	v_pk_mul_f32 v[48:49], v[96:97], v[48:49]
	v_pk_mul_f32 v[50:51], v[98:99], v[50:51]
	v_pk_mul_f32 v[48:49], v[48:49], v[170:171]
	v_pk_mul_f32 v[50:51], v[50:51], v[172:173]
	v_cvt_pk_bf16_f32 v48, v48, v49
	v_cvt_pk_bf16_f32 v49, v50, v51
	global_store_dwordx2 v[168:169], v[48:49], off
	v_pk_mul_f32 v[76:77], v[76:77], v[92:93] op_sel_hi:[1,0]
	v_pk_mul_f32 v[78:79], v[78:79], v[92:93] op_sel_hi:[1,0]
	v_lshlrev_b32_e32 v28, 16, v136
	v_and_b32_e32 v29, 0xffff0000, v136
	v_lshlrev_b32_e32 v30, 16, v137
	v_and_b32_e32 v31, 0xffff0000, v137
	v_pk_mul_f32 v[76:77], v[100:101], v[76:77]
	v_pk_mul_f32 v[78:79], v[102:103], v[78:79]
	v_pk_mul_f32 v[76:77], v[76:77], v[28:29]
	v_pk_mul_f32 v[78:79], v[78:79], v[30:31]
	v_cvt_pk_bf16_f32 v76, v76, v77
	v_cvt_pk_bf16_f32 v77, v78, v79
	global_store_dwordx2 v[166:167], v[76:77], off offset:32
	v_pk_mul_f32 v[44:45], v[44:45], v[94:95] op_sel_hi:[1,0]
	v_pk_mul_f32 v[46:47], v[46:47], v[94:95] op_sel_hi:[1,0]
	v_lshlrev_b32_e32 v170, 16, v152
	v_and_b32_e32 v171, 0xffff0000, v152
	v_lshlrev_b32_e32 v172, 16, v153
	v_and_b32_e32 v173, 0xffff0000, v153
	v_pk_mul_f32 v[44:45], v[100:101], v[44:45]
	v_pk_mul_f32 v[46:47], v[102:103], v[46:47]
	v_pk_mul_f32 v[44:45], v[44:45], v[170:171]
	v_pk_mul_f32 v[46:47], v[46:47], v[172:173]
	v_cvt_pk_bf16_f32 v44, v44, v45
	v_cvt_pk_bf16_f32 v45, v46, v47
	global_store_dwordx2 v[168:169], v[44:45], off offset:32
	v_pk_mul_f32 v[72:73], v[72:73], v[92:93] op_sel_hi:[1,0]
	v_pk_mul_f32 v[74:75], v[74:75], v[92:93] op_sel_hi:[1,0]
	v_lshlrev_b32_e32 v28, 16, v138
	v_and_b32_e32 v29, 0xffff0000, v138
	v_lshlrev_b32_e32 v30, 16, v139
	v_and_b32_e32 v31, 0xffff0000, v139
	v_pk_mul_f32 v[72:73], v[104:105], v[72:73]
	v_pk_mul_f32 v[74:75], v[106:107], v[74:75]
	v_pk_mul_f32 v[72:73], v[72:73], v[28:29]
	v_pk_mul_f32 v[74:75], v[74:75], v[30:31]
	v_cvt_pk_bf16_f32 v72, v72, v73
	v_cvt_pk_bf16_f32 v73, v74, v75
	global_store_dwordx2 v[166:167], v[72:73], off offset:64
	v_pk_mul_f32 v[40:41], v[40:41], v[94:95] op_sel_hi:[1,0]
	v_pk_mul_f32 v[42:43], v[42:43], v[94:95] op_sel_hi:[1,0]
	v_lshlrev_b32_e32 v170, 16, v154
	v_and_b32_e32 v171, 0xffff0000, v154
	v_lshlrev_b32_e32 v172, 16, v155
	v_and_b32_e32 v173, 0xffff0000, v155
	v_pk_mul_f32 v[40:41], v[104:105], v[40:41]
	v_pk_mul_f32 v[42:43], v[106:107], v[42:43]
	v_pk_mul_f32 v[40:41], v[40:41], v[170:171]
	v_pk_mul_f32 v[42:43], v[42:43], v[172:173]
	v_cvt_pk_bf16_f32 v40, v40, v41
	v_cvt_pk_bf16_f32 v41, v42, v43
	global_store_dwordx2 v[168:169], v[40:41], off offset:64
	v_pk_mul_f32 v[68:69], v[68:69], v[92:93] op_sel_hi:[1,0]
	v_pk_mul_f32 v[70:71], v[70:71], v[92:93] op_sel_hi:[1,0]
	v_lshlrev_b32_e32 v28, 16, v140
	v_and_b32_e32 v29, 0xffff0000, v140
	v_lshlrev_b32_e32 v30, 16, v141
	v_and_b32_e32 v31, 0xffff0000, v141
	v_pk_mul_f32 v[68:69], v[108:109], v[68:69]
; __device__ __forceinline__ unsigned cvtpk(float lo, float hi) { f32x2 v = {lo, hi}; bf16x2_t b = __builtin_convertvector(v, bf16x2_t); return __builtin_bit_cast(unsigned, b); }
; __device__ __forceinline__ float bflo(unsigned u) { return __uint_as_float(u << 16); }
; __device__ __forceinline__ float bfhi(unsigned u) { return __uint_as_float(u & 0xffff0000u); }
; __device__ __forceinline__ void ret_pair(LAS unsigned char* lds, const bf16_t* Z, bf16_t* MIX, int b, int h, int tA, int tB, const float* gain, int wid) {
;     ...
;         for (int eb = 0; eb < 8; ++eb) {
;             const u32x2 gw = *(const u32x2*)(gp + 16 * eb);
;             const f32x4 gn = *(const f32x4*)(gain + 16 * eb + 4 * quadf);
;             u32x2 w; w.x = cvtpk(O[eb][0] * r * gn.x * bflo(gw.x), O[eb][1] * r * gn.y * bfhi(gw.x));
;             w.y = cvtpk(O[eb][2] * r * gn.z * bflo(gw.y), O[eb][3] * r * gn.w * bfhi(gw.y));
;             *(u32x2*)(op + 16 * eb) = w;
;         }
; __global__ void __launch_bounds__(NWAVES * 64, 2) fwd(Args args) {
;     ...
;         for (int pi = vcu; pi < 256; pi += G) {
;             const int bh = pi >> 3, tp = pi & 7, b = bh >> 3, h = bh & 7;
;             attn_item<true>(lds, Z, MIX, b, h, 15 - tp, lam, shift, subln, 0, wid, 0);
;             ret_pair(lds, Z, MIX, b, h, 15 - tp, tp, ret_gn + 128 * h, wid);
;             attn_item<true>(lds, Z, MIX, b, h, tp, lam, shift, subln, 0, wid, 0);
	v_pk_mul_f32 v[70:71], v[110:111], v[70:71]
	v_pk_mul_f32 v[68:69], v[68:69], v[28:29]
	v_pk_mul_f32 v[70:71], v[70:71], v[30:31]
	v_cvt_pk_bf16_f32 v68, v68, v69
	v_cvt_pk_bf16_f32 v69, v70, v71
	global_store_dwordx2 v[166:167], v[68:69], off offset:96
	v_pk_mul_f32 v[36:37], v[36:37], v[94:95] op_sel_hi:[1,0]
	v_pk_mul_f32 v[38:39], v[38:39], v[94:95] op_sel_hi:[1,0]
	v_lshlrev_b32_e32 v170, 16, v156
	v_and_b32_e32 v171, 0xffff0000, v156
	v_lshlrev_b32_e32 v172, 16, v157
	v_and_b32_e32 v173, 0xffff0000, v157
	v_pk_mul_f32 v[36:37], v[108:109], v[36:37]
	v_pk_mul_f32 v[38:39], v[110:111], v[38:39]
	v_pk_mul_f32 v[36:37], v[36:37], v[170:171]
	v_pk_mul_f32 v[38:39], v[38:39], v[172:173]
	v_cvt_pk_bf16_f32 v36, v36, v37
	v_cvt_pk_bf16_f32 v37, v38, v39
	global_store_dwordx2 v[168:169], v[36:37], off offset:96
	v_pk_mul_f32 v[64:65], v[64:65], v[92:93] op_sel_hi:[1,0]
	v_pk_mul_f32 v[66:67], v[66:67], v[92:93] op_sel_hi:[1,0]
	v_lshlrev_b32_e32 v28, 16, v142
	v_and_b32_e32 v29, 0xffff0000, v142
	v_lshlrev_b32_e32 v30, 16, v143
	v_and_b32_e32 v31, 0xffff0000, v143
	v_pk_mul_f32 v[64:65], v[112:113], v[64:65]
	v_pk_mul_f32 v[66:67], v[114:115], v[66:67]
	v_pk_mul_f32 v[64:65], v[64:65], v[28:29]
	v_pk_mul_f32 v[66:67], v[66:67], v[30:31]
	v_cvt_pk_bf16_f32 v64, v64, v65
	v_cvt_pk_bf16_f32 v65, v66, v67
	global_store_dwordx2 v[166:167], v[64:65], off offset:128
	v_pk_mul_f32 v[24:25], v[24:25], v[94:95] op_sel_hi:[1,0]
	v_pk_mul_f32 v[26:27], v[26:27], v[94:95] op_sel_hi:[1,0]
	v_lshlrev_b32_e32 v170, 16, v158
	v_and_b32_e32 v171, 0xffff0000, v158
	v_lshlrev_b32_e32 v172, 16, v159
	v_and_b32_e32 v173, 0xffff0000, v159
	v_pk_mul_f32 v[24:25], v[112:113], v[24:25]
	v_pk_mul_f32 v[26:27], v[114:115], v[26:27]
	v_pk_mul_f32 v[24:25], v[24:25], v[170:171]
	v_pk_mul_f32 v[26:27], v[26:27], v[172:173]
	v_cvt_pk_bf16_f32 v24, v24, v25
	v_cvt_pk_bf16_f32 v25, v26, v27
	global_store_dwordx2 v[168:169], v[24:25], off offset:128
	v_pk_mul_f32 v[60:61], v[60:61], v[92:93] op_sel_hi:[1,0]
	v_pk_mul_f32 v[62:63], v[62:63], v[92:93] op_sel_hi:[1,0]
	v_lshlrev_b32_e32 v28, 16, v144
	v_and_b32_e32 v29, 0xffff0000, v144
	v_lshlrev_b32_e32 v30, 16, v145
	v_and_b32_e32 v31, 0xffff0000, v145
	v_pk_mul_f32 v[60:61], v[116:117], v[60:61]
	v_pk_mul_f32 v[62:63], v[118:119], v[62:63]
	v_pk_mul_f32 v[60:61], v[60:61], v[28:29]
	v_pk_mul_f32 v[62:63], v[62:63], v[30:31]
	v_cvt_pk_bf16_f32 v60, v60, v61
	v_cvt_pk_bf16_f32 v61, v62, v63
	global_store_dwordx2 v[166:167], v[60:61], off offset:160
	v_pk_mul_f32 v[20:21], v[20:21], v[94:95] op_sel_hi:[1,0]
	v_pk_mul_f32 v[22:23], v[22:23], v[94:95] op_sel_hi:[1,0]
	v_lshlrev_b32_e32 v170, 16, v160
	v_and_b32_e32 v171, 0xffff0000, v160
	v_lshlrev_b32_e32 v172, 16, v161
	v_and_b32_e32 v173, 0xffff0000, v161
	v_pk_mul_f32 v[20:21], v[116:117], v[20:21]
	v_pk_mul_f32 v[22:23], v[118:119], v[22:23]
	v_pk_mul_f32 v[20:21], v[20:21], v[170:171]
	v_pk_mul_f32 v[22:23], v[22:23], v[172:173]
	v_cvt_pk_bf16_f32 v20, v20, v21
	v_cvt_pk_bf16_f32 v21, v22, v23
	global_store_dwordx2 v[168:169], v[20:21], off offset:160
	v_pk_mul_f32 v[56:57], v[56:57], v[92:93] op_sel_hi:[1,0]
	v_pk_mul_f32 v[58:59], v[58:59], v[92:93] op_sel_hi:[1,0]
	v_lshlrev_b32_e32 v28, 16, v146
	v_and_b32_e32 v29, 0xffff0000, v146
	v_lshlrev_b32_e32 v30, 16, v147
	v_and_b32_e32 v31, 0xffff0000, v147
	v_pk_mul_f32 v[56:57], v[120:121], v[56:57]
	v_pk_mul_f32 v[58:59], v[122:123], v[58:59]
	v_pk_mul_f32 v[56:57], v[56:57], v[28:29]
	v_pk_mul_f32 v[58:59], v[58:59], v[30:31]
	v_cvt_pk_bf16_f32 v56, v56, v57
	v_cvt_pk_bf16_f32 v57, v58, v59
	global_store_dwordx2 v[166:167], v[56:57], off offset:192
	v_pk_mul_f32 v[16:17], v[16:17], v[94:95] op_sel_hi:[1,0]
	v_pk_mul_f32 v[18:19], v[18:19], v[94:95] op_sel_hi:[1,0]
	v_lshlrev_b32_e32 v170, 16, v162
	v_and_b32_e32 v171, 0xffff0000, v162
	v_lshlrev_b32_e32 v172, 16, v163
	v_and_b32_e32 v173, 0xffff0000, v163
	v_pk_mul_f32 v[16:17], v[120:121], v[16:17]
	v_pk_mul_f32 v[18:19], v[122:123], v[18:19]
	v_pk_mul_f32 v[16:17], v[16:17], v[170:171]
	v_pk_mul_f32 v[18:19], v[18:19], v[172:173]
	v_cvt_pk_bf16_f32 v16, v16, v17
	v_cvt_pk_bf16_f32 v17, v18, v19
	global_store_dwordx2 v[168:169], v[16:17], off offset:192
	v_pk_mul_f32 v[52:53], v[52:53], v[92:93] op_sel_hi:[1,0]
	v_pk_mul_f32 v[54:55], v[54:55], v[92:93] op_sel_hi:[1,0]
	v_lshlrev_b32_e32 v28, 16, v148
	v_and_b32_e32 v29, 0xffff0000, v148
	v_lshlrev_b32_e32 v30, 16, v149
	v_and_b32_e32 v31, 0xffff0000, v149
	v_pk_mul_f32 v[52:53], v[124:125], v[52:53]
	v_pk_mul_f32 v[54:55], v[126:127], v[54:55]
	v_pk_mul_f32 v[52:53], v[52:53], v[28:29]
	v_pk_mul_f32 v[54:55], v[54:55], v[30:31]
	v_cvt_pk_bf16_f32 v52, v52, v53
	v_cvt_pk_bf16_f32 v53, v54, v55
	global_store_dwordx2 v[166:167], v[52:53], off offset:224
	v_pk_mul_f32 v[12:13], v[12:13], v[94:95] op_sel_hi:[1,0]
	v_pk_mul_f32 v[14:15], v[14:15], v[94:95] op_sel_hi:[1,0]
	v_lshlrev_b32_e32 v170, 16, v164
	v_and_b32_e32 v171, 0xffff0000, v164
	v_lshlrev_b32_e32 v172, 16, v165
	v_and_b32_e32 v173, 0xffff0000, v165
	v_pk_mul_f32 v[12:13], v[124:125], v[12:13]
	v_pk_mul_f32 v[14:15], v[126:127], v[14:15]
	v_pk_mul_f32 v[12:13], v[12:13], v[170:171]
	v_pk_mul_f32 v[14:15], v[14:15], v[172:173]
	v_cvt_pk_bf16_f32 v12, v12, v13
	v_cvt_pk_bf16_f32 v13, v14, v15
	global_store_dwordx2 v[168:169], v[12:13], off offset:224
	v_readlane_b32 s17, v254, 44
	v_readlane_b32 s38, v254, 45
	v_readlane_b32 s39, v254, 46
	v_readlane_b32 s18, v254, 47
	v_readlane_b32 s40, v254, 48
	v_readlane_b32 s41, v254, 49
	v_readlane_b32 s43, v254, 50
	v_readlane_b32 s28, v254, 36
	v_readlane_b32 s30, v254, 37
	v_readlane_b32 s31, v254, 38
	v_readlane_b32 s88, v254, 39
	v_readlane_b32 s89, v254, 40
	v_readlane_b32 s29, v254, 41
	v_readlane_b32 s34, v254, 42
	v_readlane_b32 s35, v254, 43
	v_readlane_b32 s66, v254, 33
	v_readlane_b32 s84, v254, 34
	v_readlane_b32 s85, v254, 35
	v_readlane_b32 s78, v254, 32
	s_mov_b32 s27, 0
	s_movk_i32 s36, 0x3800
	s_mov_b64 s[14:15], 0x1800
	s_movk_i32 s16, 0x1000
	s_movk_i32 s37, 0x1c00
	s_mov_b64 s[96:97], 0x80
	s_movk_i32 s67, 0xe0
	s_movk_i32 s73, 0x60
	s_movk_i32 s74, 0x80
	s_movk_i32 s75, 0xa0
	s_movk_i32 s79, 0xc0
	s_mov_b64 s[92:93], 0x3000
	s_mov_b32 s42, 0x800000
	v_readlane_b32 s44, v255, 2
	v_readlane_b32 s2, v254, 51
	s_mov_b32 s98, 1
	s_mov_b32 s99, 0x01234567
	s_branch .LBB0_565

; #define GAS __attribute__((address_space(1)))
; __device__ __forceinline__ const float* ld_uptr(const unsigned char* tblbase, int k) {
;     const unsigned long long v = *(const GAS unsigned long long*)(tblbase + 8 * k);
;     const unsigned lo = __builtin_amdgcn_readfirstlane((unsigned)v), hi = __builtin_amdgcn_readfirstlane((unsigned)(v >> 32));
;     return (const float*)(((unsigned long long)hi << 32) | lo);
; }
; __global__ void __launch_bounds__(NWAVES * 64, 2) fwd(Args args) {
;     ...
;     if (IN(3)) {
;         unsigned char* wsp = ws; asm volatile("" : "+s"(wsp)); const unsigned char* tbl = wsp + WS_PTRS;
;         const float* x = ld_uptr(tbl, 0); float* out = (float*)ld_uptr(tbl, 16);
;         bf16_t* MIX = (bf16_t*)(wsp + WS_MIX); bf16_t* WoutT = (bf16_t*)(wsp + WS_WOUT); bf16_t* HB = (bf16_t*)(wsp + WS_HB); float* rowss = (float*)(wsp + WS_ROWSS);
;         pg8::Gemm g{MIX, WoutT, M, DM, DM}; pg8::StaticOrder S; S.init(M, DM, G, bx);
.LBB0_706:
	s_cmp_lt_i32 s82, 4
	s_cselect_b64 s[2:3], -1, 0
	s_and_b64 s[2:3], s[2:3], s[0:1]
	s_andn2_b64 vcc, exec, s[2:3]
	s_cbranch_vccnz .LBB0_745
	s_mov_b64 s[6:7], s[80:81]
	v_mov_b32_e32 v0, 0x20000
	global_load_dwordx2 v[250:251], v0, s[6:7]
	v_mbcnt_lo_u32_b32 v0, -1, 0
	v_mbcnt_hi_u32_b32 v200, -1, v0
	s_cmpk_lt_u32 s77, 0x100
	v_mov_b32_e32 v0, v200
	s_cselect_b64 s[0:1], -1, 0
	s_cmpk_gt_u32 s77, 0xff
	s_cbranch_scc1 .LBB0_709
	s_lshl_b32 s5, s77, 5
	s_lshr_b32 s4, s77, 3
	s_lshl_b32 s10, s77, 2
	s_and_b32 s5, s5, 32
	s_and_b32 s10, s10, 24
	s_or_b32 s4, s5, s4
	s_bfe_u32 s5, s77, 0x30003
	s_or_b32 s20, s10, s5
	s_lshr_b32 s22, s4, 3

; #define PG8_STAGE(bufoff, gbase, voff) do { unsigned long long _gb = (unsigned long long)(gbase); asm volatile("" : "+s"(_gb)); _Pragma("unroll") for (int _i = 0; _i < 2; ++_i) \
;         __builtin_amdgcn_global_load_lds((const GAS unsigned*)((const GAS char*)_gb + (voff)[_i]), (LAS unsigned*)(lds + (bufoff) + ldsw + _i * 8192), 16, 0, 0); } while (0)
; #define PG8_WAIT_V(n) asm volatile("s_waitcnt vmcnt(" #n ")" ::: "memory")
; #define PG8_BAR __builtin_amdgcn_s_barrier()
; template <class Epi, bool ALIGN_EPI>
; __device__ __forceinline__ void gemm_phase(LAS unsigned char* lds, const Gemm g, const StaticOrder& S, const Epi& E, const int wid) {
;     ...
;     const char* cA = (const char*)g.A + (size_t)cur.pm * tstep; const char* cB = (const char*)g.Bt + (size_t)cur.pn * tstep;
;     PG8_STAGE(PG8_SB(0, 0), cB, voffB); PG8_STAGE(PG8_SB(0, 1), cB + hstepB, voffB); PG8_STAGE(PG8_SA(0, 0), cA, voffA); PG8_STAGE(PG8_SA(0, 1), cA + hstep, voffA);
;     if (wr == 1) PG8_BAR;
;     PG8_WAIT_V(2); PG8_BAR;
;     PG8_STAGE(PG8_SB(1, 0), cB + kstep, voffB); PG8_STAGE(PG8_SA(1, 0), cA + kstep, voffA); PG8_STAGE(PG8_SB(1, 1), cB + hstepB + kstep, voffB);
;     PG8_WAIT_V(6); PG8_BAR;
.LBB0_712:
	s_add_u32 s10, s6, 0x5300000
	s_addc_u32 s11, s7, 0
	s_add_u32 s4, s24, 0x80
	s_addc_u32 s5, s25, 0
	s_waitcnt vmcnt(2)
	v_readfirstlane_b32 s9, v251
	v_readfirstlane_b32 s8, v250
	s_barrier
	s_add_i32 m0, s23, 0x18000
	v_lshl_add_u64 v[2:3], s[4:5], 0, v[178:179]
	global_load_lds_dwordx4 v[2:3], off
	s_add_i32 m0, s23, 0x1a000
	v_lshl_add_u64 v[2:3], s[4:5], 0, v[182:183]
	s_add_u32 s4, s26, 0x80
	s_addc_u32 s5, s27, 0
	s_add_i32 s42, s23, 0x8000
	global_load_lds_dwordx4 v[2:3], off
	s_mov_b32 m0, s42
	v_lshl_add_u64 v[2:3], s[4:5], 0, v[176:177]
	s_add_i32 s43, s23, 0xa000
	global_load_lds_dwordx4 v[2:3], off
	v_lshl_add_u64 v[2:3], s[4:5], 0, v[180:181]
	s_add_u32 s4, s24, 0x20080
	s_mov_b32 m0, s43
	s_addc_u32 s5, s25, 0
	global_load_lds_dwordx4 v[2:3], off
	s_add_i32 m0, s23, 0x1c000
	v_lshl_add_u64 v[2:3], s[4:5], 0, v[178:179]
	global_load_lds_dwordx4 v[2:3], off
	v_lshl_add_u64 v[2:3], s[4:5], 0, v[182:183]
	s_add_i32 m0, s23, 0x1e000
	v_and_b32_e32 v5, 48, v0
	global_load_lds_dwordx4 v[2:3], off
	v_and_b32_e32 v2, 15, v0
	v_or_b32_e32 v3, s79, v2
	v_lshlrev_b32_e32 v4, 6, v3
	s_movk_i32 s4, 0x3c0
	v_and_b32_e32 v1, 0xfffffc00, v1
	v_lshlrev_b32_e32 v3, 2, v3
	v_lshlrev_b32_e32 v0, 2, v0
	v_and_or_b32 v4, v4, s4, v5
	v_add_u32_e32 v6, s94, v1
	v_and_b32_e32 v3, 32, v3
	v_lshl_or_b32 v2, v2, 6, v5
	v_add_u32_e32 v1, s93, v1
	v_and_b32_e32 v0, 32, v0
	s_waitcnt vmcnt(6)
	v_bitop3_b32 v3, v4, v6, v3 bitop3:0xde
	v_bitop3_b32 v201, v2, v1, v0 bitop3:0xde
	s_add_i32 s45, 0, 0x10000
	s_add_i32 s46, 0, 0x14000
	s_ashr_i32 s44, s78, 31
	v_mov_b64_e32 v[184:185], 0x100
	v_mov_b64_e32 v[186:187], 0xff
	v_add_u32_e32 v203, s45, v201
	v_add_u32_e32 v204, s46, v201
	v_add_u32_e32 v205, 0, v3
	s_barrier
	s_branch .LBB0_715

; #define PG8_STAGE(bufoff, gbase, voff) do { unsigned long long _gb = (unsigned long long)(gbase); asm volatile("" : "+s"(_gb)); _Pragma("unroll") for (int _i = 0; _i < 2; ++_i) \
;         __builtin_amdgcn_global_load_lds((const GAS unsigned*)((const GAS char*)_gb + (voff)[_i]), (LAS unsigned*)(lds + (bufoff) + ldsw + _i * 8192), 16, 0, 0); } while (0)
; #define PG8_LDA(dst, b, h) do { _Pragma("unroll") for (int m = 0; m < 4; ++m) _Pragma("unroll") for (int k = 0; k < 2; ++k) dst[m][k] = *(const LAS bf16x8*)(lds + PG8_SA(b, h) + aoff + m * 2048 + k * 1024); } while (0)
; #define PG8_LDB(dst, b, h) do { _Pragma("unroll") for (int n = 0; n < 2; ++n) _Pragma("unroll") for (int k = 0; k < 2; ++k) dst[n][k] = *(const LAS bf16x8*)(lds + PG8_SB(b, h) + boff + n * 2048 + k * 1024); } while (0)
; #define PG8_MMA(ai, bj, At, Bt) do { __builtin_amdgcn_s_setprio(1); _Pragma("unroll") for (int m = 0; m < 4; ++m) _Pragma("unroll") for (int n = 0; n < 2; ++n) _Pragma("unroll") for (int k = 0; k < 2; ++k) \
;         acc[ai][bj][m][n] = __builtin_amdgcn_mfma_f32_16x16x32_bf16(Bt[n][k], At[m][k], acc[ai][bj][m][n], 0, 0, 0); __builtin_amdgcn_s_setprio(0); } while (0)
; #define PG8_WAIT_V(n) asm volatile("s_waitcnt vmcnt(" #n ")" ::: "memory")
; #define PG8_WAIT_L(n) asm volatile("s_waitcnt lgkmcnt(" #n ")" ::: "memory")
; #define PG8_BAR __builtin_amdgcn_s_barrier()
; #define PG8_SCHED __builtin_amdgcn_sched_barrier(0)
; template <class Epi, bool ALIGN_EPI>
; __device__ __forceinline__ void gemm_phase(LAS unsigned char* lds, const Gemm g, const StaticOrder& S, const Epi& E, const int wid) {
;     ...
;             PG8_LDB(B0, 0, 0); PG8_LDB(B1, 0, 1); PG8_SCHED; PG8_LDA(At, 0, 0); PG8_STAGE(PG8_SA(1, 1), a1 + hstep, voffA);
;             PG8_WAIT_V(8); PG8_WAIT_L(0); PG8_BAR; PG8_MMA(0, 0, At, B0); PG8_MMA(0, 1, At, B1); PG8_BAR; PG8_SCHED;
;             PG8_LDA(At, 0, 1); PG8_STAGE(PG8_SB(0, 0), b2, voffB); PG8_STAGE(PG8_SB(0, 1), b2 + hstepB, voffB); PG8_STAGE(PG8_SA(0, 0), a2, voffA);
;             PG8_WAIT_V(8); PG8_WAIT_L(0); PG8_BAR; PG8_MMA(1, 0, At, B0); PG8_MMA(1, 1, At, B1); PG8_BAR; PG8_SCHED;
.LBB0_722:
	ds_read_b128 v[128:131], v203
	ds_read_b128 v[132:135], v203 offset:1024
	ds_read_b128 v[136:139], v203 offset:2048
	ds_read_b128 v[140:143], v203 offset:3072
	ds_read_b128 v[144:147], v204
	ds_read_b128 v[148:151], v204 offset:1024
	ds_read_b128 v[152:155], v204 offset:2048
	ds_read_b128 v[156:159], v204 offset:3072
	s_cmp_eq_u32 s52, 28
	s_cselect_b32 s30, s21, s50
	s_cselect_b32 s31, s15, s51
	s_cselect_b32 s28, s47, s48
	s_cselect_b32 s29, s13, s49
	s_add_u32 s26, s30, 0x80
	s_addc_u32 s27, s31, 0
	s_mov_b64 s[54:55], s[24:25]
	ds_read_b128 v[160:163], v205
	ds_read_b128 v[164:167], v205 offset:1024
	ds_read_b128 v[168:171], v205 offset:2048
	ds_read_b128 v[172:175], v205 offset:3072
	ds_read_b128 v[188:191], v205 offset:4096
	ds_read_b128 v[192:195], v205 offset:5120
	ds_read_b128 v[196:199], v205 offset:6144
	ds_read_b128 v[206:209], v205 offset:7168
	s_add_i32 m0, s23, 0xc000
	v_lshl_add_u64 v[210:211], s[54:55], 0, v[176:177]
	global_load_lds_dwordx4 v[210:211], off
	v_lshl_add_u64 v[210:211], s[54:55], 0, v[180:181]
	s_add_i32 m0, s23, 0xe000
	s_nop 0
	global_load_lds_dwordx4 v[210:211], off
	s_waitcnt vmcnt(8)
	s_waitcnt lgkmcnt(0)
	s_barrier
	s_setprio 1
	v_mfma_f32_16x16x32_bf16 v[124:127], v[128:131], v[160:163], v[124:127]
	v_mfma_f32_16x16x32_bf16 v[120:123], v[136:139], v[160:163], v[120:123]
	v_mfma_f32_16x16x32_bf16 v[108:111], v[128:131], v[168:171], v[108:111]
	v_mfma_f32_16x16x32_bf16 v[104:107], v[136:139], v[168:171], v[104:107]
	v_mfma_f32_16x16x32_bf16 v[92:95], v[128:131], v[188:191], v[92:95]
	v_mfma_f32_16x16x32_bf16 v[88:91], v[136:139], v[188:191], v[88:91]
	v_mfma_f32_16x16x32_bf16 v[76:79], v[128:131], v[196:199], v[76:79]
	v_mfma_f32_16x16x32_bf16 v[72:75], v[136:139], v[196:199], v[72:75]
	v_mfma_f32_16x16x32_bf16 v[124:127], v[132:135], v[164:167], v[124:127]
	v_mfma_f32_16x16x32_bf16 v[120:123], v[140:143], v[164:167], v[120:123]
	v_mfma_f32_16x16x32_bf16 v[108:111], v[132:135], v[172:175], v[108:111]
	v_mfma_f32_16x16x32_bf16 v[104:107], v[140:143], v[172:175], v[104:107]
	v_mfma_f32_16x16x32_bf16 v[92:95], v[132:135], v[192:195], v[92:95]
	v_mfma_f32_16x16x32_bf16 v[88:91], v[140:143], v[192:195], v[88:91]
	v_mfma_f32_16x16x32_bf16 v[76:79], v[132:135], v[206:209], v[76:79]
	v_mfma_f32_16x16x32_bf16 v[72:75], v[140:143], v[206:209], v[72:75]
	v_mfma_f32_16x16x32_bf16 v[116:119], v[144:147], v[160:163], v[116:119]
	v_mfma_f32_16x16x32_bf16 v[112:115], v[152:155], v[160:163], v[112:115]
	v_mfma_f32_16x16x32_bf16 v[100:103], v[144:147], v[168:171], v[100:103]
	v_mfma_f32_16x16x32_bf16 v[96:99], v[152:155], v[168:171], v[96:99]
	v_mfma_f32_16x16x32_bf16 v[84:87], v[144:147], v[188:191], v[84:87]
	v_mfma_f32_16x16x32_bf16 v[80:83], v[152:155], v[188:191], v[80:83]
	v_mfma_f32_16x16x32_bf16 v[68:71], v[144:147], v[196:199], v[68:71]
	v_mfma_f32_16x16x32_bf16 v[64:67], v[152:155], v[196:199], v[64:67]
	v_mfma_f32_16x16x32_bf16 v[116:119], v[148:151], v[164:167], v[116:119]
	v_mfma_f32_16x16x32_bf16 v[112:115], v[156:159], v[164:167], v[112:115]
	v_mfma_f32_16x16x32_bf16 v[100:103], v[148:151], v[172:175], v[100:103]
	v_mfma_f32_16x16x32_bf16 v[96:99], v[156:159], v[172:175], v[96:99]
	v_mfma_f32_16x16x32_bf16 v[84:87], v[148:151], v[192:195], v[84:87]
	v_mfma_f32_16x16x32_bf16 v[80:83], v[156:159], v[192:195], v[80:83]
	v_mfma_f32_16x16x32_bf16 v[68:71], v[148:151], v[206:209], v[68:71]
	v_mfma_f32_16x16x32_bf16 v[64:67], v[156:159], v[206:209], v[64:67]
	s_setprio 0
	s_barrier
	s_mov_b64 s[54:55], s[28:29]
	s_add_i32 s53, s45, s33
	ds_read_b128 v[160:163], v205 offset:16384
	ds_read_b128 v[164:167], v205 offset:17408
	ds_read_b128 v[168:171], v205 offset:18432
	ds_read_b128 v[172:175], v205 offset:19456
	ds_read_b128 v[188:191], v205 offset:20480
	ds_read_b128 v[192:195], v205 offset:21504
	ds_read_b128 v[196:199], v205 offset:22528
	ds_read_b128 v[206:209], v205 offset:23552
	s_mov_b32 m0, s53
	v_lshl_add_u64 v[210:211], s[54:55], 0, v[178:179]
	global_load_lds_dwordx4 v[210:211], off
	s_add_i32 m0, s53, 0x2000
	v_lshl_add_u64 v[210:211], s[54:55], 0, v[182:183]
	s_add_u32 s54, s28, 0x20000
	s_addc_u32 s55, s29, 0
	s_add_i32 s53, s46, s33
	global_load_lds_dwordx4 v[210:211], off
	s_mov_b32 m0, s53
	v_lshl_add_u64 v[210:211], s[54:55], 0, v[178:179]
	global_load_lds_dwordx4 v[210:211], off
	v_lshl_add_u64 v[210:211], s[54:55], 0, v[182:183]
	s_add_i32 m0, s53, 0x2000
	s_mov_b64 s[54:55], s[30:31]
	global_load_lds_dwordx4 v[210:211], off
	s_mov_b32 m0, s23
	v_lshl_add_u64 v[210:211], s[54:55], 0, v[176:177]
	global_load_lds_dwordx4 v[210:211], off
	v_lshl_add_u64 v[210:211], s[54:55], 0, v[180:181]
	s_mov_b32 m0, s38
	s_nop 0
	global_load_lds_dwordx4 v[210:211], off
	s_waitcnt vmcnt(8)
	s_waitcnt lgkmcnt(0)
	s_barrier
; #define PG8_STAGE(bufoff, gbase, voff) do { unsigned long long _gb = (unsigned long long)(gbase); asm volatile("" : "+s"(_gb)); _Pragma("unroll") for (int _i = 0; _i < 2; ++_i) \
;         __builtin_amdgcn_global_load_lds((const GAS unsigned*)((const GAS char*)_gb + (voff)[_i]), (LAS unsigned*)(lds + (bufoff) + ldsw + _i * 8192), 16, 0, 0); } while (0)
; #define PG8_LDA(dst, b, h) do { _Pragma("unroll") for (int m = 0; m < 4; ++m) _Pragma("unroll") for (int k = 0; k < 2; ++k) dst[m][k] = *(const LAS bf16x8*)(lds + PG8_SA(b, h) + aoff + m * 2048 + k * 1024); } while (0)
; #define PG8_LDB(dst, b, h) do { _Pragma("unroll") for (int n = 0; n < 2; ++n) _Pragma("unroll") for (int k = 0; k < 2; ++k) dst[n][k] = *(const LAS bf16x8*)(lds + PG8_SB(b, h) + boff + n * 2048 + k * 1024); } while (0)
; #define PG8_MMA(ai, bj, At, Bt) do { __builtin_amdgcn_s_setprio(1); _Pragma("unroll") for (int m = 0; m < 4; ++m) _Pragma("unroll") for (int n = 0; n < 2; ++n) _Pragma("unroll") for (int k = 0; k < 2; ++k) \
;         acc[ai][bj][m][n] = __builtin_amdgcn_mfma_f32_16x16x32_bf16(Bt[n][k], At[m][k], acc[ai][bj][m][n], 0, 0, 0); __builtin_amdgcn_s_setprio(0); } while (0)
; template <class Epi, bool ALIGN_EPI>
; __device__ __forceinline__ void gemm_phase(LAS unsigned char* lds, const Gemm g, const StaticOrder& S, const Epi& E, const int wid) {
;     ...
;             PG8_LDB(B0, 0, 0); PG8_LDB(B1, 0, 1); PG8_SCHED; PG8_LDA(At, 0, 0); PG8_STAGE(PG8_SA(1, 1), a1 + hstep, voffA);
;             PG8_WAIT_V(8); PG8_WAIT_L(0); PG8_BAR; PG8_MMA(0, 0, At, B0); PG8_MMA(0, 1, At, B1); PG8_BAR; PG8_SCHED;
;             PG8_LDA(At, 0, 1); PG8_STAGE(PG8_SB(0, 0), b2, voffB); PG8_STAGE(PG8_SB(0, 1), b2 + hstepB, voffB); PG8_STAGE(PG8_SA(0, 0), a2, voffA);
;             PG8_WAIT_V(8); PG8_WAIT_L(0); PG8_BAR; PG8_MMA(1, 0, At, B0); PG8_MMA(1, 1, At, B1); PG8_BAR; PG8_SCHED;
;             PG8_LDB(B0, 1, 0); PG8_LDB(B1, 1, 1); PG8_SCHED; PG8_LDA(At, 1, 0); PG8_STAGE(PG8_SA(0, 1), a2 + hstep, voffA);
;             PG8_WAIT_V(8); PG8_WAIT_L(0); PG8_BAR; PG8_MMA(0, 0, At, B0); PG8_MMA(0, 1, At, B1); PG8_BAR; PG8_SCHED;
;             PG8_LDA(At, 1, 1); PG8_STAGE(PG8_SB(1, 0), b3, voffB); PG8_STAGE(PG8_SB(1, 1), b3 + hstepB, voffB); PG8_STAGE(PG8_SA(1, 0), a3, voffA);
;             PG8_WAIT_V(8); PG8_WAIT_L(0); PG8_BAR; PG8_MMA(1, 0, At, B0); PG8_MMA(1, 1, At, B1); PG8_BAR; PG8_SCHED;
	s_setprio 1
	v_mfma_f32_16x16x32_bf16 v[60:63], v[128:131], v[160:163], v[60:63]
	v_mfma_f32_16x16x32_bf16 v[56:59], v[136:139], v[160:163], v[56:59]
	v_mfma_f32_16x16x32_bf16 v[44:47], v[128:131], v[168:171], v[44:47]
	v_mfma_f32_16x16x32_bf16 v[40:43], v[136:139], v[168:171], v[40:43]
	v_mfma_f32_16x16x32_bf16 v[28:31], v[128:131], v[188:191], v[28:31]
	v_mfma_f32_16x16x32_bf16 v[24:27], v[136:139], v[188:191], v[24:27]
	v_mfma_f32_16x16x32_bf16 v[12:15], v[128:131], v[196:199], v[12:15]
	v_mfma_f32_16x16x32_bf16 v[8:11], v[136:139], v[196:199], v[8:11]
	v_mfma_f32_16x16x32_bf16 v[60:63], v[132:135], v[164:167], v[60:63]
	v_mfma_f32_16x16x32_bf16 v[56:59], v[140:143], v[164:167], v[56:59]
	v_mfma_f32_16x16x32_bf16 v[44:47], v[132:135], v[172:175], v[44:47]
	v_mfma_f32_16x16x32_bf16 v[40:43], v[140:143], v[172:175], v[40:43]
	v_mfma_f32_16x16x32_bf16 v[28:31], v[132:135], v[192:195], v[28:31]
	v_mfma_f32_16x16x32_bf16 v[24:27], v[140:143], v[192:195], v[24:27]
	v_mfma_f32_16x16x32_bf16 v[12:15], v[132:135], v[206:209], v[12:15]
	v_mfma_f32_16x16x32_bf16 v[8:11], v[140:143], v[206:209], v[8:11]
	v_mfma_f32_16x16x32_bf16 v[52:55], v[144:147], v[160:163], v[52:55]
	v_mfma_f32_16x16x32_bf16 v[48:51], v[152:155], v[160:163], v[48:51]
	v_mfma_f32_16x16x32_bf16 v[36:39], v[144:147], v[168:171], v[36:39]
	v_mfma_f32_16x16x32_bf16 v[32:35], v[152:155], v[168:171], v[32:35]
	v_mfma_f32_16x16x32_bf16 v[20:23], v[144:147], v[188:191], v[20:23]
	v_mfma_f32_16x16x32_bf16 v[16:19], v[152:155], v[188:191], v[16:19]
	v_mfma_f32_16x16x32_bf16 v[4:7], v[144:147], v[196:199], v[4:7]
	v_mfma_f32_16x16x32_bf16 v[0:3], v[152:155], v[196:199], v[0:3]
	v_mfma_f32_16x16x32_bf16 v[52:55], v[148:151], v[164:167], v[52:55]
	v_mfma_f32_16x16x32_bf16 v[48:51], v[156:159], v[164:167], v[48:51]
	v_mfma_f32_16x16x32_bf16 v[36:39], v[148:151], v[172:175], v[36:39]
	v_mfma_f32_16x16x32_bf16 v[32:35], v[156:159], v[172:175], v[32:35]
	v_mfma_f32_16x16x32_bf16 v[20:23], v[148:151], v[192:195], v[20:23]
	v_mfma_f32_16x16x32_bf16 v[16:19], v[156:159], v[192:195], v[16:19]
	v_mfma_f32_16x16x32_bf16 v[4:7], v[148:151], v[206:209], v[4:7]
	v_mfma_f32_16x16x32_bf16 v[0:3], v[156:159], v[206:209], v[0:3]
	s_setprio 0
	s_barrier
	s_add_i32 s53, 0, 0x18000
	s_add_i32 s54, 0, 0x1c000
	v_add_u32_e32 v140, s53, v201
	v_add_u32_e32 v156, s54, v201
	ds_read_b128 v[128:131], v140
	ds_read_b128 v[132:135], v140 offset:1024
	ds_read_b128 v[136:139], v140 offset:2048
	ds_read_b128 v[140:143], v140 offset:3072
	ds_read_b128 v[144:147], v156
	ds_read_b128 v[148:151], v156 offset:1024
	ds_read_b128 v[152:155], v156 offset:2048
	ds_read_b128 v[156:159], v156 offset:3072
	s_add_u32 s30, s30, 0x80000
	s_addc_u32 s31, s31, 0
	s_mov_b32 m0, s39
	ds_read_b128 v[160:163], v205 offset:32768
	ds_read_b128 v[164:167], v205 offset:33792
	ds_read_b128 v[168:171], v205 offset:34816
	ds_read_b128 v[172:175], v205 offset:35840
	ds_read_b128 v[188:191], v205 offset:36864
	ds_read_b128 v[192:195], v205 offset:37888
	ds_read_b128 v[196:199], v205 offset:38912
	ds_read_b128 v[206:209], v205 offset:39936
	s_nop 0
	v_lshl_add_u64 v[210:211], s[30:31], 0, v[176:177]
	global_load_lds_dwordx4 v[210:211], off
	v_lshl_add_u64 v[210:211], s[30:31], 0, v[180:181]
	s_mov_b32 m0, s40
	s_nop 0
	global_load_lds_dwordx4 v[210:211], off
	s_waitcnt vmcnt(8)
	s_waitcnt lgkmcnt(0)
	s_barrier
	s_setprio 1
	v_mfma_f32_16x16x32_bf16 v[124:127], v[128:131], v[160:163], v[124:127]
	v_mfma_f32_16x16x32_bf16 v[120:123], v[136:139], v[160:163], v[120:123]
	v_mfma_f32_16x16x32_bf16 v[108:111], v[128:131], v[168:171], v[108:111]
	v_mfma_f32_16x16x32_bf16 v[104:107], v[136:139], v[168:171], v[104:107]
	v_mfma_f32_16x16x32_bf16 v[92:95], v[128:131], v[188:191], v[92:95]
	v_mfma_f32_16x16x32_bf16 v[88:91], v[136:139], v[188:191], v[88:91]
	v_mfma_f32_16x16x32_bf16 v[76:79], v[128:131], v[196:199], v[76:79]
	v_mfma_f32_16x16x32_bf16 v[72:75], v[136:139], v[196:199], v[72:75]
	v_mfma_f32_16x16x32_bf16 v[124:127], v[132:135], v[164:167], v[124:127]
	v_mfma_f32_16x16x32_bf16 v[120:123], v[140:143], v[164:167], v[120:123]
	v_mfma_f32_16x16x32_bf16 v[108:111], v[132:135], v[172:175], v[108:111]
	v_mfma_f32_16x16x32_bf16 v[104:107], v[140:143], v[172:175], v[104:107]
	v_mfma_f32_16x16x32_bf16 v[92:95], v[132:135], v[192:195], v[92:95]
	v_mfma_f32_16x16x32_bf16 v[88:91], v[140:143], v[192:195], v[88:91]
	v_mfma_f32_16x16x32_bf16 v[76:79], v[132:135], v[206:209], v[76:79]
	v_mfma_f32_16x16x32_bf16 v[72:75], v[140:143], v[206:209], v[72:75]
	v_mfma_f32_16x16x32_bf16 v[116:119], v[144:147], v[160:163], v[116:119]
	v_mfma_f32_16x16x32_bf16 v[112:115], v[152:155], v[160:163], v[112:115]
	v_mfma_f32_16x16x32_bf16 v[100:103], v[144:147], v[168:171], v[100:103]
	v_mfma_f32_16x16x32_bf16 v[96:99], v[152:155], v[168:171], v[96:99]
	v_mfma_f32_16x16x32_bf16 v[84:87], v[144:147], v[188:191], v[84:87]
	v_mfma_f32_16x16x32_bf16 v[80:83], v[152:155], v[188:191], v[80:83]
	v_mfma_f32_16x16x32_bf16 v[68:71], v[144:147], v[196:199], v[68:71]
	v_mfma_f32_16x16x32_bf16 v[64:67], v[152:155], v[196:199], v[64:67]
	v_mfma_f32_16x16x32_bf16 v[116:119], v[148:151], v[164:167], v[116:119]
	v_mfma_f32_16x16x32_bf16 v[112:115], v[156:159], v[164:167], v[112:115]
	v_mfma_f32_16x16x32_bf16 v[100:103], v[148:151], v[172:175], v[100:103]
	v_mfma_f32_16x16x32_bf16 v[96:99], v[156:159], v[172:175], v[96:99]
	v_mfma_f32_16x16x32_bf16 v[84:87], v[148:151], v[192:195], v[84:87]
	v_mfma_f32_16x16x32_bf16 v[80:83], v[156:159], v[192:195], v[80:83]
	v_mfma_f32_16x16x32_bf16 v[68:71], v[148:151], v[206:209], v[68:71]
	v_mfma_f32_16x16x32_bf16 v[64:67], v[156:159], v[206:209], v[64:67]
	s_setprio 0
	s_barrier
; #define PG8_STAGE(bufoff, gbase, voff) do { unsigned long long _gb = (unsigned long long)(gbase); asm volatile("" : "+s"(_gb)); _Pragma("unroll") for (int _i = 0; _i < 2; ++_i) \
;         __builtin_amdgcn_global_load_lds((const GAS unsigned*)((const GAS char*)_gb + (voff)[_i]), (LAS unsigned*)(lds + (bufoff) + ldsw + _i * 8192), 16, 0, 0); } while (0)
; #define PG8_LDA(dst, b, h) do { _Pragma("unroll") for (int m = 0; m < 4; ++m) _Pragma("unroll") for (int k = 0; k < 2; ++k) dst[m][k] = *(const LAS bf16x8*)(lds + PG8_SA(b, h) + aoff + m * 2048 + k * 1024); } while (0)
; #define PG8_LDB(dst, b, h) do { _Pragma("unroll") for (int n = 0; n < 2; ++n) _Pragma("unroll") for (int k = 0; k < 2; ++k) dst[n][k] = *(const LAS bf16x8*)(lds + PG8_SB(b, h) + boff + n * 2048 + k * 1024); } while (0)
; #define PG8_MMA(ai, bj, At, Bt) do { __builtin_amdgcn_s_setprio(1); _Pragma("unroll") for (int m = 0; m < 4; ++m) _Pragma("unroll") for (int n = 0; n < 2; ++n) _Pragma("unroll") for (int k = 0; k < 2; ++k) \
;         acc[ai][bj][m][n] = __builtin_amdgcn_mfma_f32_16x16x32_bf16(Bt[n][k], At[m][k], acc[ai][bj][m][n], 0, 0, 0); __builtin_amdgcn_s_setprio(0); } while (0)
; #define PG8_WAIT_V(n) asm volatile("s_waitcnt vmcnt(" #n ")" ::: "memory")
; #define PG8_WAIT_L(n) asm volatile("s_waitcnt lgkmcnt(" #n ")" ::: "memory")
; #define PG8_BAR __builtin_amdgcn_s_barrier()
; #define PG8_SCHED __builtin_amdgcn_sched_barrier(0)
; template <class Epi, bool ALIGN_EPI>
; __device__ __forceinline__ void gemm_phase(LAS unsigned char* lds, const Gemm g, const StaticOrder& S, const Epi& E, const int wid) {
;     ...
;             PG8_LDB(B0, 1, 0); PG8_LDB(B1, 1, 1); PG8_SCHED; PG8_LDA(At, 1, 0); PG8_STAGE(PG8_SA(0, 1), a2 + hstep, voffA);
;             PG8_WAIT_V(8); PG8_WAIT_L(0); PG8_BAR; PG8_MMA(0, 0, At, B0); PG8_MMA(0, 1, At, B1); PG8_BAR; PG8_SCHED;
;             PG8_LDA(At, 1, 1); PG8_STAGE(PG8_SB(1, 0), b3, voffB); PG8_STAGE(PG8_SB(1, 1), b3 + hstepB, voffB); PG8_STAGE(PG8_SA(1, 0), a3, voffA);
;             PG8_WAIT_V(8); PG8_WAIT_L(0); PG8_BAR; PG8_MMA(1, 0, At, B0); PG8_MMA(1, 1, At, B1); PG8_BAR; PG8_SCHED;
;         }
	s_add_u32 s30, s28, 0x80
	s_addc_u32 s31, s29, 0
	s_add_i32 s53, s53, s33
	ds_read_b128 v[160:163], v205 offset:49152
	ds_read_b128 v[164:167], v205 offset:50176
	ds_read_b128 v[168:171], v205 offset:51200
	ds_read_b128 v[172:175], v205 offset:52224
	ds_read_b128 v[188:191], v205 offset:53248
	ds_read_b128 v[192:195], v205 offset:54272
	ds_read_b128 v[196:199], v205 offset:55296
	ds_read_b128 v[206:209], v205 offset:56320
	s_mov_b32 m0, s53
	v_lshl_add_u64 v[210:211], s[30:31], 0, v[178:179]
	global_load_lds_dwordx4 v[210:211], off
	s_add_i32 m0, s53, 0x2000
	s_add_u32 s28, s28, 0x20080
	v_lshl_add_u64 v[210:211], s[30:31], 0, v[182:183]
	s_addc_u32 s29, s29, 0
	s_add_i32 s30, s54, s33
	global_load_lds_dwordx4 v[210:211], off
	s_mov_b32 m0, s30
	v_lshl_add_u64 v[210:211], s[28:29], 0, v[178:179]
	global_load_lds_dwordx4 v[210:211], off
	v_lshl_add_u64 v[210:211], s[28:29], 0, v[182:183]
	s_add_i32 m0, s30, 0x2000
	s_nop 0
	global_load_lds_dwordx4 v[210:211], off
	s_mov_b32 m0, s42
	v_lshl_add_u64 v[210:211], s[26:27], 0, v[176:177]
	global_load_lds_dwordx4 v[210:211], off
	v_lshl_add_u64 v[210:211], s[26:27], 0, v[180:181]
	s_mov_b32 m0, s43
	s_nop 0
	global_load_lds_dwordx4 v[210:211], off
	s_waitcnt vmcnt(8)
	s_waitcnt lgkmcnt(0)
	s_barrier
	s_setprio 1
	v_mfma_f32_16x16x32_bf16 v[60:63], v[128:131], v[160:163], v[60:63]
	v_mfma_f32_16x16x32_bf16 v[56:59], v[136:139], v[160:163], v[56:59]
	v_mfma_f32_16x16x32_bf16 v[44:47], v[128:131], v[168:171], v[44:47]
	v_mfma_f32_16x16x32_bf16 v[40:43], v[136:139], v[168:171], v[40:43]
	v_mfma_f32_16x16x32_bf16 v[28:31], v[128:131], v[188:191], v[28:31]
	v_mfma_f32_16x16x32_bf16 v[24:27], v[136:139], v[188:191], v[24:27]
	v_mfma_f32_16x16x32_bf16 v[12:15], v[128:131], v[196:199], v[12:15]
	v_mfma_f32_16x16x32_bf16 v[8:11], v[136:139], v[196:199], v[8:11]
	v_mfma_f32_16x16x32_bf16 v[60:63], v[132:135], v[164:167], v[60:63]
	v_mfma_f32_16x16x32_bf16 v[56:59], v[140:143], v[164:167], v[56:59]
	v_mfma_f32_16x16x32_bf16 v[44:47], v[132:135], v[172:175], v[44:47]
	v_mfma_f32_16x16x32_bf16 v[40:43], v[140:143], v[172:175], v[40:43]
	v_mfma_f32_16x16x32_bf16 v[28:31], v[132:135], v[192:195], v[28:31]
	v_mfma_f32_16x16x32_bf16 v[24:27], v[140:143], v[192:195], v[24:27]
	v_mfma_f32_16x16x32_bf16 v[12:15], v[132:135], v[206:209], v[12:15]
	v_mfma_f32_16x16x32_bf16 v[8:11], v[140:143], v[206:209], v[8:11]
	v_mfma_f32_16x16x32_bf16 v[52:55], v[144:147], v[160:163], v[52:55]
	v_mfma_f32_16x16x32_bf16 v[48:51], v[152:155], v[160:163], v[48:51]
	v_mfma_f32_16x16x32_bf16 v[36:39], v[144:147], v[168:171], v[36:39]
	v_mfma_f32_16x16x32_bf16 v[32:35], v[152:155], v[168:171], v[32:35]
	v_mfma_f32_16x16x32_bf16 v[20:23], v[144:147], v[188:191], v[20:23]
	v_mfma_f32_16x16x32_bf16 v[16:19], v[152:155], v[188:191], v[16:19]
	v_mfma_f32_16x16x32_bf16 v[4:7], v[144:147], v[196:199], v[4:7]
	v_mfma_f32_16x16x32_bf16 v[0:3], v[152:155], v[196:199], v[0:3]
	v_mfma_f32_16x16x32_bf16 v[52:55], v[148:151], v[164:167], v[52:55]
	v_mfma_f32_16x16x32_bf16 v[48:51], v[156:159], v[164:167], v[48:51]
	v_mfma_f32_16x16x32_bf16 v[36:39], v[148:151], v[172:175], v[36:39]
	v_mfma_f32_16x16x32_bf16 v[32:35], v[156:159], v[172:175], v[32:35]
	v_mfma_f32_16x16x32_bf16 v[20:23], v[148:151], v[192:195], v[20:23]
	v_mfma_f32_16x16x32_bf16 v[16:19], v[156:159], v[192:195], v[16:19]
	v_mfma_f32_16x16x32_bf16 v[4:7], v[148:151], v[206:209], v[4:7]
	v_mfma_f32_16x16x32_bf16 v[0:3], v[156:159], v[206:209], v[0:3]
	s_setprio 0
	s_barrier
	s_add_i32 s52, s52, 2
	s_add_u32 s48, s48, 0x100
	s_addc_u32 s49, s49, 0
	s_add_u32 s24, s24, 0x100
	s_addc_u32 s25, s25, 0
	s_add_u32 s50, s50, 0x100
	s_addc_u32 s51, s51, 0
	s_cmp_gt_u32 s52, 29
	s_cbranch_scc0 .LBB0_722
	s_and_b64 vcc, exec, s[84:85]
	s_cbranch_vccz .LBB0_725
	s_barrier

; #define PG8_WAIT_V(n) asm volatile("s_waitcnt vmcnt(" #n ")" ::: "memory")
; #define PG8_BAR __builtin_amdgcn_s_barrier()
; template <class Epi, bool ALIGN_EPI>
; __device__ __forceinline__ void gemm_phase(LAS unsigned char* lds, const Gemm g, const StaticOrder& S, const Epi& E, const int wid) {
;     ...
;     for (int i = 0; i < 2; ++i) { int R, C; stage_rc(tid * 16 + i * 8192, R, C); const int Rb = 64 * (R >> 5) + perm32(R & 31);
;         voffA[i] = (unsigned)(R * K + C) * 2u; voffB[i] = (unsigned)(Rb * K + C) * 2u; }
;     const size_t kstep = (size_t)(BK * 2);
;     const size_t hstep = (size_t)HALF * K * 2;
;     const size_t hstepB = (size_t)32 * K * 2;
;     const size_t tstep = 2 * hstep;
;     const unsigned ldsw = (unsigned)wid * 1024u;
;     const int aoff = lds_byte(wr * 64 + fr, fq * 8), boff = lds_byte(wc * 32 + fr, fq * 8);
;     ...
;     Unit cur, nxt; int ui = 0;
;     if (!S.next(0, cur)) return;
;     f32x4 acc[2][2][4][2];
; #pragma unroll
;     for (int a = 0; a < 2; ++a)
; #pragma unroll
;         for (int b = 0; b < 2; ++b)
; #pragma unroll
;             for (int m = 0; m < 4; ++m)
; #pragma unroll
;                 for (int n = 0; n < 2; ++n) acc[a][b][m][n] = (f32x4){0.f, 0.f, 0.f, 0.f};
;     bf16x8 At[4][2], B0[2][2], B1[2][2];
;     const char* cA = (const char*)g.A + (size_t)cur.pm * tstep; const char* cB = (const char*)g.Bt + (size_t)cur.pn * tstep;
;     PG8_STAGE(PG8_SB(0, 0), cB, voffB); PG8_STAGE(PG8_SB(0, 1), cB + hstepB, voffB); PG8_STAGE(PG8_SA(0, 0), cA, voffA); PG8_STAGE(PG8_SA(0, 1), cA + hstep, voffA);
;     if (wr == 1) PG8_BAR;
;     PG8_WAIT_V(2); PG8_BAR;
;     PG8_STAGE(PG8_SB(1, 0), cB + kstep, voffB); PG8_STAGE(PG8_SA(1, 0), cA + kstep, voffA); PG8_STAGE(PG8_SB(1, 1), cB + hstepB + kstep, voffB);
;     PG8_WAIT_V(6); PG8_BAR;
; __global__ void __launch_bounds__(NWAVES * 64, 2) fwd(Args args) {
;     ...
;         unsigned char* wsp = ws; asm volatile("" : "+s"(wsp)); const unsigned char* tbl = wsp + WS_PTRS;
;         float* out = (float*)ld_uptr(tbl, 16);
;         bf16_t* HB = (bf16_t*)(wsp + WS_HB); bf16_t* WgT = (bf16_t*)(wsp + WS_WG); bf16_t* PP = (bf16_t*)(wsp + WS_PP); float* rowss = (float*)(wsp + WS_ROWSS);
;         pg8::Gemm g{HB, WgT, M, DM, DM}; pg8::StaticOrder S; S.init(M, DM, G, bx);
.LBB0_797:
	s_cmp_lt_i32 s82, 5
	s_cselect_b64 s[2:3], -1, 0
	s_and_b64 s[0:1], s[2:3], s[0:1]
	s_andn2_b64 vcc, exec, s[0:1]
	s_cbranch_vccnz .LBB0_818
	v_mov_b32_e32 v0, 0x20000
	global_load_dwordx2 v[250:251], v0, s[80:81] offset:128
	v_mbcnt_lo_u32_b32 v0, -1, 0
	v_mbcnt_hi_u32_b32 v200, -1, v0
	s_cmpk_gt_u32 s77, 0xff
	v_mov_b32_e32 v0, v200
	s_cbranch_scc1 .LBB0_818
	v_lshlrev_b32_e32 v1, 4, v0
	v_add_u32_e32 v2, s33, v1
	v_add_u32_e32 v3, 0x2000, v2
	v_ashrrev_i32_e32 v4, 31, v3
	v_lshrrev_b32_e32 v4, 22, v4
	v_add_u32_e32 v4, v3, v4
	v_ashrrev_i32_e32 v4, 10, v4
	v_mul_i32_i24_e32 v5, 0x400, v4
	v_sub_u32_e32 v3, v3, v5
	v_lshrrev_b32_e32 v5, 4, v3
	v_bitop3_b32 v3, v5, v3, 32 bitop3:0x6c
	v_ashrrev_i32_e32 v5, 31, v3
	v_lshrrev_b32_e32 v5, 26, v5
	v_add_u32_e32 v5, v3, v5
	v_ashrrev_i32_e32 v6, 6, v5
	v_and_b32_e32 v5, 0xffc0, v5
	v_sub_u32_e32 v3, v3, v5
	v_lshlrev_b32_e32 v7, 3, v4
	v_lshrrev_b16_e32 v5, 7, v3
	v_and_b32_e32 v7, -16, v7
	v_and_b32_e32 v5, 1, v5
	v_add_u32_e32 v7, v6, v7
	v_add_u16_e32 v3, v3, v5
	v_mov_b32_e32 v5, 1
	v_lshrrev_b32_e32 v8, 2, v7
	v_lshlrev_b32_e32 v9, 1, v7
	v_lshlrev_b32_e32 v4, 5, v4
	v_ashrrev_i16_sdwa v3, v5, sext(v3) dst_sel:DWORD dst_unused:UNUSED_PAD src0_sel:DWORD src1_sel:BYTE_0
	v_and_b32_e32 v8, 4, v8
	v_and_b32_e32 v6, 3, v6
	v_and_b32_e32 v9, 0xfffd8, v9
	v_and_b32_e32 v4, 32, v4
	v_bfe_i32 v3, v3, 0, 16
	v_or3_b32 v6, v6, v8, v9
	v_add_lshl_u32 v3, v4, v3, 1
	v_lshl_add_u32 v176, v6, 12, v3
	v_lshl_add_u32 v178, v7, 12, v3
	v_ashrrev_i32_e32 v3, 31, v2
	v_lshrrev_b32_e32 v3, 22, v3
	v_add_u32_e32 v3, v2, v3
	v_ashrrev_i32_e32 v3, 10, v3
	v_mul_i32_i24_e32 v4, 0x400, v3
	v_sub_u32_e32 v2, v2, v4
	s_add_u32 s6, s80, 0x5300000
	v_lshrrev_b32_e32 v4, 4, v2
	s_addc_u32 s7, s81, 0
	v_bitop3_b32 v2, v4, v2, 32 bitop3:0x6c
	s_add_u32 s26, s80, 0x2600000
	v_ashrrev_i32_e32 v4, 31, v2
	s_addc_u32 s27, s81, 0
	v_lshrrev_b32_e32 v4, 26, v4
	s_lshl_b32 s1, s77, 5
	v_add_u32_e32 v4, v2, v4
	v_lshlrev_b32_e32 v7, 3, v3
	s_lshr_b32 s0, s77, 3
	s_lshl_b32 s4, s77, 2
	s_and_b32 s1, s1, 32
	v_ashrrev_i32_e32 v6, 6, v4
	v_and_b32_e32 v7, -16, v7
	v_and_b32_e32 v4, 0xc0, v4
	s_and_b32 s4, s4, 24
	s_or_b32 s0, s1, s0
	s_bfe_u32 s1, s77, 0x30003
	v_add_u32_e32 v7, v6, v7
	v_sub_u32_e32 v2, v2, v4
	s_or_b32 s41, s4, s1
	s_bfe_u32 s4, s0, 0x50003
	v_lshrrev_b32_e32 v8, 2, v7
	v_lshlrev_b32_e32 v9, 1, v7
	v_lshlrev_b32_e32 v3, 5, v3
	v_ashrrev_i16_sdwa v2, v5, sext(v2) dst_sel:DWORD dst_unused:UNUSED_PAD src0_sel:DWORD src1_sel:BYTE_0
	s_lshl_b32 s5, s41, 20
	s_lshl_b32 s0, s4, 20
	v_and_b32_e32 v8, 4, v8
	v_and_b32_e32 v6, 3, v6
	v_and_b32_e32 v9, 0xfffd8, v9
	v_and_b32_e32 v3, 32, v3
	v_bfe_i32 v2, v2, 0, 16
	s_add_u32 s18, s26, s0
	v_or3_b32 v6, v6, v8, v9
	v_add_lshl_u32 v2, v3, v2, 1
	s_addc_u32 s19, s27, 0
	s_add_i32 s28, s33, 0
	v_lshl_add_u32 v180, v6, 12, v2
	s_mov_b64 s[0:1], s[18:19]
	s_add_i32 m0, s28, 0x10000
	v_lshl_add_u32 v182, v7, 12, v2
	global_load_lds_dwordx4 v180, s[0:1]
	s_add_i32 m0, s28, 0x12000
	v_mov_b32_e32 v181, 0
	global_load_lds_dwordx4 v176, s[0:1]
	s_add_u32 s0, s18, 0x20000
	s_addc_u32 s1, s19, 0
	s_add_i32 m0, s28, 0x14000
	v_cndmask_b32_e64 v2, 0, 1, s[96:97]
	global_load_lds_dwordx4 v180, s[0:1]
	s_add_i32 m0, s28, 0x16000
	s_add_u32 s20, s6, s5
	s_addc_u32 s21, s7, 0
	global_load_lds_dwordx4 v176, s[0:1]
	s_mov_b64 s[0:1], s[20:21]
	s_mov_b32 m0, s28
	s_add_i32 s29, s28, 0x2000
	v_mov_b32_e32 v177, v181
	global_load_lds_dwordx4 v182, s[0:1]
	s_mov_b32 m0, s29
	v_mov_b32_e32 v183, v181
	global_load_lds_dwordx4 v178, s[0:1]
	s_add_u32 s0, s20, 0x80000
	s_addc_u32 s1, s21, 0
	s_add_i32 s30, s28, 0x4000
	s_mov_b32 m0, s30
	s_add_i32 s31, s28, 0x6000
	s_andn2_b64 vcc, exec, s[96:97]
	global_load_lds_dwordx4 v182, s[0:1]
	s_mov_b32 m0, s31
	v_mov_b32_e32 v179, v181
	global_load_lds_dwordx4 v178, s[0:1]
	v_cmp_ne_u32_e64 s[0:1], 1, v2
	s_cbranch_vccnz .LBB0_801
	s_barrier
.LBB0_801:
	s_and_b32 s42, 0xffff, s4
	s_add_u32 s8, s80, 0xc300000
	s_addc_u32 s9, s81, 0
	s_add_u32 s4, s18, 0x80
	s_addc_u32 s5, s19, 0
	s_waitcnt vmcnt(2)
	v_readfirstlane_b32 s3, v251
	v_readfirstlane_b32 s2, v250
	s_barrier
	s_add_i32 m0, s28, 0x18000
	v_lshl_add_u64 v[2:3], s[4:5], 0, v[180:181]
	global_load_lds_dwordx4 v[2:3], off
	s_add_i32 m0, s28, 0x1a000
	v_lshl_add_u64 v[2:3], s[4:5], 0, v[176:177]
	s_add_u32 s4, s20, 0x80
	s_addc_u32 s5, s21, 0
	s_add_i32 s34, s28, 0x8000
	global_load_lds_dwordx4 v[2:3], off
	s_mov_b32 m0, s34
	v_lshl_add_u64 v[2:3], s[4:5], 0, v[182:183]
	s_add_i32 s35, s28, 0xa000
	global_load_lds_dwordx4 v[2:3], off
	v_lshl_add_u64 v[2:3], s[4:5], 0, v[178:179]
	s_add_u32 s4, s18, 0x20080
	s_mov_b32 m0, s35
	s_addc_u32 s5, s19, 0
	global_load_lds_dwordx4 v[2:3], off
	s_add_i32 m0, s28, 0x1c000
	v_lshl_add_u64 v[2:3], s[4:5], 0, v[180:181]
	global_load_lds_dwordx4 v[2:3], off
	v_lshl_add_u64 v[2:3], s[4:5], 0, v[176:177]
	s_add_i32 m0, s28, 0x1e000
	v_and_b32_e32 v5, 48, v0
	global_load_lds_dwordx4 v[2:3], off
	v_and_b32_e32 v2, 15, v0
	v_or_b32_e32 v3, s79, v2
	v_lshlrev_b32_e32 v4, 6, v3
	s_movk_i32 s4, 0x3c0
	v_and_b32_e32 v1, 0xfffffc00, v1
	v_lshlrev_b32_e32 v3, 2, v3
	v_lshlrev_b32_e32 v0, 2, v0
	v_and_or_b32 v4, v4, s4, v5
	v_add_u32_e32 v6, s94, v1
	v_and_b32_e32 v3, 32, v3
	v_lshl_or_b32 v2, v2, 6, v5
	v_add_u32_e32 v1, s93, v1
	v_and_b32_e32 v0, 32, v0
	s_waitcnt vmcnt(6)
	v_bitop3_b32 v3, v4, v6, v3 bitop3:0xde
	v_bitop3_b32 v201, v2, v1, v0 bitop3:0xde
	s_add_i32 s38, 0, 0x10000
	s_add_i32 s39, 0, 0x14000
	s_mov_b32 s36, 0
	s_ashr_i32 s37, s78, 31
	v_mov_b64_e32 v[184:185], 0x100
	v_mov_b64_e32 v[186:187], 0xff
	v_add_u32_e32 v202, s38, v201
	v_add_u32_e32 v203, s39, v201
	v_add_u32_e32 v204, 0, v3
	v_mov_b32_e32 v205, 0x358637bd
	s_mov_b32 s40, 0x800000
	s_barrier
	s_branch .LBB0_804

; #define PG8_STAGE(bufoff, gbase, voff) do { unsigned long long _gb = (unsigned long long)(gbase); asm volatile("" : "+s"(_gb)); _Pragma("unroll") for (int _i = 0; _i < 2; ++_i) \
;         __builtin_amdgcn_global_load_lds((const GAS unsigned*)((const GAS char*)_gb + (voff)[_i]), (LAS unsigned*)(lds + (bufoff) + ldsw + _i * 8192), 16, 0, 0); } while (0)
; #define PG8_LDA(dst, b, h) do { _Pragma("unroll") for (int m = 0; m < 4; ++m) _Pragma("unroll") for (int k = 0; k < 2; ++k) dst[m][k] = *(const LAS bf16x8*)(lds + PG8_SA(b, h) + aoff + m * 2048 + k * 1024); } while (0)
; #define PG8_LDB(dst, b, h) do { _Pragma("unroll") for (int n = 0; n < 2; ++n) _Pragma("unroll") for (int k = 0; k < 2; ++k) dst[n][k] = *(const LAS bf16x8*)(lds + PG8_SB(b, h) + boff + n * 2048 + k * 1024); } while (0)
; #define PG8_WAIT_V(n) asm volatile("s_waitcnt vmcnt(" #n ")" ::: "memory")
; #define PG8_WAIT_L(n) asm volatile("s_waitcnt lgkmcnt(" #n ")" ::: "memory")
; #define PG8_BAR __builtin_amdgcn_s_barrier()
; #define PG8_SCHED __builtin_amdgcn_sched_barrier(0)
; template <class Epi, bool ALIGN_EPI>
; __device__ __forceinline__ void gemm_phase(LAS unsigned char* lds, const Gemm g, const StaticOrder& S, const Epi& E, const int wid) {
;     ...
;         for (int t = 0; t < nt; t += 2) {
;             const bool last = (t == nt - 2);
;             const char* a1 = cA + (size_t)(t + 1) * kstep;
;             const char* a2 = last ? nA : cA + (size_t)(t + 2) * kstep; const char* b2 = last ? nB : cB + (size_t)(t + 2) * kstep;
;             const char* a3 = a2 + kstep; const char* b3 = b2 + kstep;
;             PG8_LDB(B0, 0, 0); PG8_LDB(B1, 0, 1); PG8_SCHED; PG8_LDA(At, 0, 0); PG8_STAGE(PG8_SA(1, 1), a1 + hstep, voffA);
;             PG8_WAIT_V(8); PG8_WAIT_L(0); PG8_BAR; PG8_MMA(0, 0, At, B0); PG8_MMA(0, 1, At, B1); PG8_BAR; PG8_SCHED;
;             PG8_LDA(At, 0, 1); PG8_STAGE(PG8_SB(0, 0), b2, voffB); PG8_STAGE(PG8_SB(0, 1), b2 + hstepB, voffB); PG8_STAGE(PG8_SA(0, 0), a2, voffA);
;             PG8_WAIT_V(8); PG8_WAIT_L(0); PG8_BAR; PG8_MMA(1, 0, At, B0); PG8_MMA(1, 1, At, B1); PG8_BAR; PG8_SCHED;
;             PG8_LDB(B0, 1, 0); PG8_LDB(B1, 1, 1); PG8_SCHED; PG8_LDA(At, 1, 0); PG8_STAGE(PG8_SA(0, 1), a2 + hstep, voffA);
;             PG8_WAIT_V(8); PG8_WAIT_L(0); PG8_BAR; PG8_MMA(0, 0, At, B0); PG8_MMA(0, 1, At, B1); PG8_BAR; PG8_SCHED;
.LBB0_811:
	ds_read_b128 v[128:131], v202
	ds_read_b128 v[132:135], v202 offset:1024
	ds_read_b128 v[136:139], v202 offset:2048
	ds_read_b128 v[140:143], v202 offset:3072
	ds_read_b128 v[144:147], v203
	ds_read_b128 v[148:151], v203 offset:1024
	ds_read_b128 v[152:155], v203 offset:2048
	ds_read_b128 v[156:159], v203 offset:3072
	s_cmp_eq_u32 s49, 28
	s_cselect_b32 s24, s43, s47
	s_cselect_b32 s25, s13, s48
	s_cselect_b32 s22, s44, s45
	s_cselect_b32 s23, s11, s46
	s_add_u32 s20, s24, 0x80
	s_addc_u32 s21, s25, 0
	s_mov_b64 s[50:51], s[18:19]
	ds_read_b128 v[160:163], v204
	ds_read_b128 v[164:167], v204 offset:1024
	ds_read_b128 v[168:171], v204 offset:2048
	ds_read_b128 v[172:175], v204 offset:3072
	ds_read_b128 v[188:191], v204 offset:4096
	ds_read_b128 v[192:195], v204 offset:5120
	ds_read_b128 v[196:199], v204 offset:6144
	ds_read_b128 v[206:209], v204 offset:7168
	s_add_i32 m0, s28, 0xc000
	v_lshl_add_u64 v[210:211], s[50:51], 0, v[182:183]
	global_load_lds_dwordx4 v[210:211], off
	v_lshl_add_u64 v[210:211], s[50:51], 0, v[178:179]
	s_add_i32 m0, s28, 0xe000
	s_nop 0
	global_load_lds_dwordx4 v[210:211], off
	s_waitcnt vmcnt(8)
	s_waitcnt lgkmcnt(0)
	s_barrier
	s_setprio 1
	v_mfma_f32_16x16x32_bf16 v[124:127], v[128:131], v[160:163], v[124:127]
	v_mfma_f32_16x16x32_bf16 v[120:123], v[136:139], v[160:163], v[120:123]
	v_mfma_f32_16x16x32_bf16 v[108:111], v[128:131], v[168:171], v[108:111]
	v_mfma_f32_16x16x32_bf16 v[104:107], v[136:139], v[168:171], v[104:107]
	v_mfma_f32_16x16x32_bf16 v[92:95], v[128:131], v[188:191], v[92:95]
	v_mfma_f32_16x16x32_bf16 v[88:91], v[136:139], v[188:191], v[88:91]
	v_mfma_f32_16x16x32_bf16 v[76:79], v[128:131], v[196:199], v[76:79]
	v_mfma_f32_16x16x32_bf16 v[72:75], v[136:139], v[196:199], v[72:75]
	v_mfma_f32_16x16x32_bf16 v[124:127], v[132:135], v[164:167], v[124:127]
	v_mfma_f32_16x16x32_bf16 v[120:123], v[140:143], v[164:167], v[120:123]
	v_mfma_f32_16x16x32_bf16 v[108:111], v[132:135], v[172:175], v[108:111]
	v_mfma_f32_16x16x32_bf16 v[104:107], v[140:143], v[172:175], v[104:107]
	v_mfma_f32_16x16x32_bf16 v[92:95], v[132:135], v[192:195], v[92:95]
	v_mfma_f32_16x16x32_bf16 v[88:91], v[140:143], v[192:195], v[88:91]
	v_mfma_f32_16x16x32_bf16 v[76:79], v[132:135], v[206:209], v[76:79]
	v_mfma_f32_16x16x32_bf16 v[72:75], v[140:143], v[206:209], v[72:75]
	v_mfma_f32_16x16x32_bf16 v[116:119], v[144:147], v[160:163], v[116:119]
	v_mfma_f32_16x16x32_bf16 v[112:115], v[152:155], v[160:163], v[112:115]
	v_mfma_f32_16x16x32_bf16 v[100:103], v[144:147], v[168:171], v[100:103]
	v_mfma_f32_16x16x32_bf16 v[96:99], v[152:155], v[168:171], v[96:99]
	v_mfma_f32_16x16x32_bf16 v[84:87], v[144:147], v[188:191], v[84:87]
	v_mfma_f32_16x16x32_bf16 v[80:83], v[152:155], v[188:191], v[80:83]
	v_mfma_f32_16x16x32_bf16 v[68:71], v[144:147], v[196:199], v[68:71]
	v_mfma_f32_16x16x32_bf16 v[64:67], v[152:155], v[196:199], v[64:67]
	v_mfma_f32_16x16x32_bf16 v[116:119], v[148:151], v[164:167], v[116:119]
	v_mfma_f32_16x16x32_bf16 v[112:115], v[156:159], v[164:167], v[112:115]
	v_mfma_f32_16x16x32_bf16 v[100:103], v[148:151], v[172:175], v[100:103]
	v_mfma_f32_16x16x32_bf16 v[96:99], v[156:159], v[172:175], v[96:99]
	v_mfma_f32_16x16x32_bf16 v[84:87], v[148:151], v[192:195], v[84:87]
	v_mfma_f32_16x16x32_bf16 v[80:83], v[156:159], v[192:195], v[80:83]
	v_mfma_f32_16x16x32_bf16 v[68:71], v[148:151], v[206:209], v[68:71]
	v_mfma_f32_16x16x32_bf16 v[64:67], v[156:159], v[206:209], v[64:67]
	s_setprio 0
	s_barrier
	s_mov_b64 s[50:51], s[22:23]
	s_add_i32 s52, s38, s33
	ds_read_b128 v[160:163], v204 offset:16384
	ds_read_b128 v[164:167], v204 offset:17408
	ds_read_b128 v[168:171], v204 offset:18432
	ds_read_b128 v[172:175], v204 offset:19456
	ds_read_b128 v[188:191], v204 offset:20480
	ds_read_b128 v[192:195], v204 offset:21504
	ds_read_b128 v[196:199], v204 offset:22528
	ds_read_b128 v[206:209], v204 offset:23552
	s_mov_b32 m0, s52
	v_lshl_add_u64 v[210:211], s[50:51], 0, v[180:181]
	global_load_lds_dwordx4 v[210:211], off
	s_add_i32 m0, s52, 0x2000
	v_lshl_add_u64 v[210:211], s[50:51], 0, v[176:177]
	s_add_u32 s50, s22, 0x20000
	s_addc_u32 s51, s23, 0
	s_add_i32 s52, s39, s33
	global_load_lds_dwordx4 v[210:211], off
	s_mov_b32 m0, s52
	v_lshl_add_u64 v[210:211], s[50:51], 0, v[180:181]
	global_load_lds_dwordx4 v[210:211], off
	v_lshl_add_u64 v[210:211], s[50:51], 0, v[176:177]
	s_add_i32 m0, s52, 0x2000
	s_mov_b64 s[50:51], s[24:25]
	global_load_lds_dwordx4 v[210:211], off
	s_mov_b32 m0, s28
	v_lshl_add_u64 v[210:211], s[50:51], 0, v[182:183]
	global_load_lds_dwordx4 v[210:211], off
	v_lshl_add_u64 v[210:211], s[50:51], 0, v[178:179]
	s_mov_b32 m0, s29
	s_nop 0
	global_load_lds_dwordx4 v[210:211], off
	s_waitcnt vmcnt(8)
	s_waitcnt lgkmcnt(0)
	s_barrier
; #define PG8_STAGE(bufoff, gbase, voff) do { unsigned long long _gb = (unsigned long long)(gbase); asm volatile("" : "+s"(_gb)); _Pragma("unroll") for (int _i = 0; _i < 2; ++_i) \
;         __builtin_amdgcn_global_load_lds((const GAS unsigned*)((const GAS char*)_gb + (voff)[_i]), (LAS unsigned*)(lds + (bufoff) + ldsw + _i * 8192), 16, 0, 0); } while (0)
; #define PG8_LDA(dst, b, h) do { _Pragma("unroll") for (int m = 0; m < 4; ++m) _Pragma("unroll") for (int k = 0; k < 2; ++k) dst[m][k] = *(const LAS bf16x8*)(lds + PG8_SA(b, h) + aoff + m * 2048 + k * 1024); } while (0)
; #define PG8_LDB(dst, b, h) do { _Pragma("unroll") for (int n = 0; n < 2; ++n) _Pragma("unroll") for (int k = 0; k < 2; ++k) dst[n][k] = *(const LAS bf16x8*)(lds + PG8_SB(b, h) + boff + n * 2048 + k * 1024); } while (0)
; #define PG8_MMA(ai, bj, At, Bt) do { __builtin_amdgcn_s_setprio(1); _Pragma("unroll") for (int m = 0; m < 4; ++m) _Pragma("unroll") for (int n = 0; n < 2; ++n) _Pragma("unroll") for (int k = 0; k < 2; ++k) \
;         acc[ai][bj][m][n] = __builtin_amdgcn_mfma_f32_16x16x32_bf16(Bt[n][k], At[m][k], acc[ai][bj][m][n], 0, 0, 0); __builtin_amdgcn_s_setprio(0); } while (0)
; #define PG8_WAIT_V(n) asm volatile("s_waitcnt vmcnt(" #n ")" ::: "memory")
; #define PG8_WAIT_L(n) asm volatile("s_waitcnt lgkmcnt(" #n ")" ::: "memory")
; #define PG8_BAR __builtin_amdgcn_s_barrier()
; #define PG8_SCHED __builtin_amdgcn_sched_barrier(0)
; template <class Epi, bool ALIGN_EPI>
; __device__ __forceinline__ void gemm_phase(LAS unsigned char* lds, const Gemm g, const StaticOrder& S, const Epi& E, const int wid) {
;     ...
;             PG8_WAIT_V(8); PG8_WAIT_L(0); PG8_BAR; PG8_MMA(1, 0, At, B0); PG8_MMA(1, 1, At, B1); PG8_BAR; PG8_SCHED;
;             PG8_LDB(B0, 1, 0); PG8_LDB(B1, 1, 1); PG8_SCHED; PG8_LDA(At, 1, 0); PG8_STAGE(PG8_SA(0, 1), a2 + hstep, voffA);
;             PG8_WAIT_V(8); PG8_WAIT_L(0); PG8_BAR; PG8_MMA(0, 0, At, B0); PG8_MMA(0, 1, At, B1); PG8_BAR; PG8_SCHED;
;             PG8_LDA(At, 1, 1); PG8_STAGE(PG8_SB(1, 0), b3, voffB); PG8_STAGE(PG8_SB(1, 1), b3 + hstepB, voffB); PG8_STAGE(PG8_SA(1, 0), a3, voffA);
	s_setprio 1
	v_mfma_f32_16x16x32_bf16 v[60:63], v[128:131], v[160:163], v[60:63]
	v_mfma_f32_16x16x32_bf16 v[56:59], v[136:139], v[160:163], v[56:59]
	v_mfma_f32_16x16x32_bf16 v[44:47], v[128:131], v[168:171], v[44:47]
	v_mfma_f32_16x16x32_bf16 v[40:43], v[136:139], v[168:171], v[40:43]
	v_mfma_f32_16x16x32_bf16 v[28:31], v[128:131], v[188:191], v[28:31]
	v_mfma_f32_16x16x32_bf16 v[24:27], v[136:139], v[188:191], v[24:27]
	v_mfma_f32_16x16x32_bf16 v[12:15], v[128:131], v[196:199], v[12:15]
	v_mfma_f32_16x16x32_bf16 v[8:11], v[136:139], v[196:199], v[8:11]
	v_mfma_f32_16x16x32_bf16 v[60:63], v[132:135], v[164:167], v[60:63]
	v_mfma_f32_16x16x32_bf16 v[56:59], v[140:143], v[164:167], v[56:59]
	v_mfma_f32_16x16x32_bf16 v[44:47], v[132:135], v[172:175], v[44:47]
	v_mfma_f32_16x16x32_bf16 v[40:43], v[140:143], v[172:175], v[40:43]
	v_mfma_f32_16x16x32_bf16 v[28:31], v[132:135], v[192:195], v[28:31]
	v_mfma_f32_16x16x32_bf16 v[24:27], v[140:143], v[192:195], v[24:27]
	v_mfma_f32_16x16x32_bf16 v[12:15], v[132:135], v[206:209], v[12:15]
	v_mfma_f32_16x16x32_bf16 v[8:11], v[140:143], v[206:209], v[8:11]
	v_mfma_f32_16x16x32_bf16 v[52:55], v[144:147], v[160:163], v[52:55]
	v_mfma_f32_16x16x32_bf16 v[48:51], v[152:155], v[160:163], v[48:51]
	v_mfma_f32_16x16x32_bf16 v[36:39], v[144:147], v[168:171], v[36:39]
	v_mfma_f32_16x16x32_bf16 v[32:35], v[152:155], v[168:171], v[32:35]
	v_mfma_f32_16x16x32_bf16 v[20:23], v[144:147], v[188:191], v[20:23]
	v_mfma_f32_16x16x32_bf16 v[16:19], v[152:155], v[188:191], v[16:19]
	v_mfma_f32_16x16x32_bf16 v[4:7], v[144:147], v[196:199], v[4:7]
	v_mfma_f32_16x16x32_bf16 v[0:3], v[152:155], v[196:199], v[0:3]
	v_mfma_f32_16x16x32_bf16 v[52:55], v[148:151], v[164:167], v[52:55]
	v_mfma_f32_16x16x32_bf16 v[48:51], v[156:159], v[164:167], v[48:51]
	v_mfma_f32_16x16x32_bf16 v[36:39], v[148:151], v[172:175], v[36:39]
	v_mfma_f32_16x16x32_bf16 v[32:35], v[156:159], v[172:175], v[32:35]
	v_mfma_f32_16x16x32_bf16 v[20:23], v[148:151], v[192:195], v[20:23]
	v_mfma_f32_16x16x32_bf16 v[16:19], v[156:159], v[192:195], v[16:19]
	v_mfma_f32_16x16x32_bf16 v[4:7], v[148:151], v[206:209], v[4:7]
	v_mfma_f32_16x16x32_bf16 v[0:3], v[156:159], v[206:209], v[0:3]
	s_setprio 0
	s_barrier
	s_add_i32 s50, 0, 0x18000
	s_add_i32 s51, 0, 0x1c000
	v_add_u32_e32 v140, s50, v201
	v_add_u32_e32 v156, s51, v201
	ds_read_b128 v[128:131], v140
	ds_read_b128 v[132:135], v140 offset:1024
	ds_read_b128 v[136:139], v140 offset:2048
	ds_read_b128 v[140:143], v140 offset:3072
	ds_read_b128 v[144:147], v156
	ds_read_b128 v[148:151], v156 offset:1024
	ds_read_b128 v[152:155], v156 offset:2048
	ds_read_b128 v[156:159], v156 offset:3072
	s_add_u32 s24, s24, 0x80000
	s_addc_u32 s25, s25, 0
	s_mov_b32 m0, s30
	ds_read_b128 v[160:163], v204 offset:32768
	ds_read_b128 v[164:167], v204 offset:33792
	ds_read_b128 v[168:171], v204 offset:34816
	ds_read_b128 v[172:175], v204 offset:35840
	ds_read_b128 v[188:191], v204 offset:36864
	ds_read_b128 v[192:195], v204 offset:37888
	ds_read_b128 v[196:199], v204 offset:38912
	ds_read_b128 v[206:209], v204 offset:39936
	s_nop 0
	v_lshl_add_u64 v[210:211], s[24:25], 0, v[182:183]
	global_load_lds_dwordx4 v[210:211], off
	v_lshl_add_u64 v[210:211], s[24:25], 0, v[178:179]
	s_mov_b32 m0, s31
	s_nop 0
	global_load_lds_dwordx4 v[210:211], off
	s_waitcnt vmcnt(8)
	s_waitcnt lgkmcnt(0)
	s_barrier
	s_setprio 1
	v_mfma_f32_16x16x32_bf16 v[124:127], v[128:131], v[160:163], v[124:127]
	v_mfma_f32_16x16x32_bf16 v[120:123], v[136:139], v[160:163], v[120:123]
	v_mfma_f32_16x16x32_bf16 v[108:111], v[128:131], v[168:171], v[108:111]
	v_mfma_f32_16x16x32_bf16 v[104:107], v[136:139], v[168:171], v[104:107]
	v_mfma_f32_16x16x32_bf16 v[92:95], v[128:131], v[188:191], v[92:95]
	v_mfma_f32_16x16x32_bf16 v[88:91], v[136:139], v[188:191], v[88:91]
	v_mfma_f32_16x16x32_bf16 v[76:79], v[128:131], v[196:199], v[76:79]
	v_mfma_f32_16x16x32_bf16 v[72:75], v[136:139], v[196:199], v[72:75]
	v_mfma_f32_16x16x32_bf16 v[124:127], v[132:135], v[164:167], v[124:127]
	v_mfma_f32_16x16x32_bf16 v[120:123], v[140:143], v[164:167], v[120:123]
	v_mfma_f32_16x16x32_bf16 v[108:111], v[132:135], v[172:175], v[108:111]
	v_mfma_f32_16x16x32_bf16 v[104:107], v[140:143], v[172:175], v[104:107]
	v_mfma_f32_16x16x32_bf16 v[92:95], v[132:135], v[192:195], v[92:95]
	v_mfma_f32_16x16x32_bf16 v[88:91], v[140:143], v[192:195], v[88:91]
	v_mfma_f32_16x16x32_bf16 v[76:79], v[132:135], v[206:209], v[76:79]
	v_mfma_f32_16x16x32_bf16 v[72:75], v[140:143], v[206:209], v[72:75]
	v_mfma_f32_16x16x32_bf16 v[116:119], v[144:147], v[160:163], v[116:119]
	v_mfma_f32_16x16x32_bf16 v[112:115], v[152:155], v[160:163], v[112:115]
	v_mfma_f32_16x16x32_bf16 v[100:103], v[144:147], v[168:171], v[100:103]
	v_mfma_f32_16x16x32_bf16 v[96:99], v[152:155], v[168:171], v[96:99]
	v_mfma_f32_16x16x32_bf16 v[84:87], v[144:147], v[188:191], v[84:87]
	v_mfma_f32_16x16x32_bf16 v[80:83], v[152:155], v[188:191], v[80:83]
	v_mfma_f32_16x16x32_bf16 v[68:71], v[144:147], v[196:199], v[68:71]
	v_mfma_f32_16x16x32_bf16 v[64:67], v[152:155], v[196:199], v[64:67]
	v_mfma_f32_16x16x32_bf16 v[116:119], v[148:151], v[164:167], v[116:119]
	v_mfma_f32_16x16x32_bf16 v[112:115], v[156:159], v[164:167], v[112:115]
	v_mfma_f32_16x16x32_bf16 v[100:103], v[148:151], v[172:175], v[100:103]
	v_mfma_f32_16x16x32_bf16 v[96:99], v[156:159], v[172:175], v[96:99]
	v_mfma_f32_16x16x32_bf16 v[84:87], v[148:151], v[192:195], v[84:87]
	v_mfma_f32_16x16x32_bf16 v[80:83], v[156:159], v[192:195], v[80:83]
	v_mfma_f32_16x16x32_bf16 v[68:71], v[148:151], v[206:209], v[68:71]
	v_mfma_f32_16x16x32_bf16 v[64:67], v[156:159], v[206:209], v[64:67]
	s_setprio 0
	s_barrier
; #define PG8_STAGE(bufoff, gbase, voff) do { unsigned long long _gb = (unsigned long long)(gbase); asm volatile("" : "+s"(_gb)); _Pragma("unroll") for (int _i = 0; _i < 2; ++_i) \
;         __builtin_amdgcn_global_load_lds((const GAS unsigned*)((const GAS char*)_gb + (voff)[_i]), (LAS unsigned*)(lds + (bufoff) + ldsw + _i * 8192), 16, 0, 0); } while (0)
; #define PG8_LDA(dst, b, h) do { _Pragma("unroll") for (int m = 0; m < 4; ++m) _Pragma("unroll") for (int k = 0; k < 2; ++k) dst[m][k] = *(const LAS bf16x8*)(lds + PG8_SA(b, h) + aoff + m * 2048 + k * 1024); } while (0)
; #define PG8_MMA(ai, bj, At, Bt) do { __builtin_amdgcn_s_setprio(1); _Pragma("unroll") for (int m = 0; m < 4; ++m) _Pragma("unroll") for (int n = 0; n < 2; ++n) _Pragma("unroll") for (int k = 0; k < 2; ++k) \
;         acc[ai][bj][m][n] = __builtin_amdgcn_mfma_f32_16x16x32_bf16(Bt[n][k], At[m][k], acc[ai][bj][m][n], 0, 0, 0); __builtin_amdgcn_s_setprio(0); } while (0)
; #define PG8_WAIT_V(n) asm volatile("s_waitcnt vmcnt(" #n ")" ::: "memory")
; #define PG8_WAIT_L(n) asm volatile("s_waitcnt lgkmcnt(" #n ")" ::: "memory")
; #define PG8_BAR __builtin_amdgcn_s_barrier()
; #define PG8_SCHED __builtin_amdgcn_sched_barrier(0)
; template <class Epi, bool ALIGN_EPI>
; __device__ __forceinline__ void gemm_phase(LAS unsigned char* lds, const Gemm g, const StaticOrder& S, const Epi& E, const int wid) {
;     ...
;             PG8_LDA(At, 1, 1); PG8_STAGE(PG8_SB(1, 0), b3, voffB); PG8_STAGE(PG8_SB(1, 1), b3 + hstepB, voffB); PG8_STAGE(PG8_SA(1, 0), a3, voffA);
;             PG8_WAIT_V(8); PG8_WAIT_L(0); PG8_BAR; PG8_MMA(1, 0, At, B0); PG8_MMA(1, 1, At, B1); PG8_BAR; PG8_SCHED;
;         }
	s_add_u32 s24, s22, 0x80
	s_addc_u32 s25, s23, 0
	s_add_i32 s50, s50, s33
	ds_read_b128 v[160:163], v204 offset:49152
	ds_read_b128 v[164:167], v204 offset:50176
	ds_read_b128 v[168:171], v204 offset:51200
	ds_read_b128 v[172:175], v204 offset:52224
	ds_read_b128 v[188:191], v204 offset:53248
	ds_read_b128 v[192:195], v204 offset:54272
	ds_read_b128 v[196:199], v204 offset:55296
	ds_read_b128 v[206:209], v204 offset:56320
	s_mov_b32 m0, s50
	v_lshl_add_u64 v[210:211], s[24:25], 0, v[180:181]
	global_load_lds_dwordx4 v[210:211], off
	s_add_i32 m0, s50, 0x2000
	s_add_u32 s22, s22, 0x20080
	v_lshl_add_u64 v[210:211], s[24:25], 0, v[176:177]
	s_addc_u32 s23, s23, 0
	s_add_i32 s24, s51, s33
	global_load_lds_dwordx4 v[210:211], off
	s_mov_b32 m0, s24
	v_lshl_add_u64 v[210:211], s[22:23], 0, v[180:181]
	global_load_lds_dwordx4 v[210:211], off
	v_lshl_add_u64 v[210:211], s[22:23], 0, v[176:177]
	s_add_i32 m0, s24, 0x2000
	s_nop 0
	global_load_lds_dwordx4 v[210:211], off
	s_mov_b32 m0, s34
	v_lshl_add_u64 v[210:211], s[20:21], 0, v[182:183]
	global_load_lds_dwordx4 v[210:211], off
	v_lshl_add_u64 v[210:211], s[20:21], 0, v[178:179]
	s_mov_b32 m0, s35
	s_nop 0
	global_load_lds_dwordx4 v[210:211], off
	s_waitcnt vmcnt(8)
	s_waitcnt lgkmcnt(0)
	s_barrier
	s_setprio 1
	v_mfma_f32_16x16x32_bf16 v[60:63], v[128:131], v[160:163], v[60:63]
	v_mfma_f32_16x16x32_bf16 v[56:59], v[136:139], v[160:163], v[56:59]
	v_mfma_f32_16x16x32_bf16 v[44:47], v[128:131], v[168:171], v[44:47]
	v_mfma_f32_16x16x32_bf16 v[40:43], v[136:139], v[168:171], v[40:43]
	v_mfma_f32_16x16x32_bf16 v[28:31], v[128:131], v[188:191], v[28:31]
	v_mfma_f32_16x16x32_bf16 v[24:27], v[136:139], v[188:191], v[24:27]
	v_mfma_f32_16x16x32_bf16 v[12:15], v[128:131], v[196:199], v[12:15]
	v_mfma_f32_16x16x32_bf16 v[8:11], v[136:139], v[196:199], v[8:11]
	v_mfma_f32_16x16x32_bf16 v[60:63], v[132:135], v[164:167], v[60:63]
	v_mfma_f32_16x16x32_bf16 v[56:59], v[140:143], v[164:167], v[56:59]
	v_mfma_f32_16x16x32_bf16 v[44:47], v[132:135], v[172:175], v[44:47]
	v_mfma_f32_16x16x32_bf16 v[40:43], v[140:143], v[172:175], v[40:43]
	v_mfma_f32_16x16x32_bf16 v[28:31], v[132:135], v[192:195], v[28:31]
	v_mfma_f32_16x16x32_bf16 v[24:27], v[140:143], v[192:195], v[24:27]
	v_mfma_f32_16x16x32_bf16 v[12:15], v[132:135], v[206:209], v[12:15]
	v_mfma_f32_16x16x32_bf16 v[8:11], v[140:143], v[206:209], v[8:11]
	v_mfma_f32_16x16x32_bf16 v[52:55], v[144:147], v[160:163], v[52:55]
	v_mfma_f32_16x16x32_bf16 v[48:51], v[152:155], v[160:163], v[48:51]
	v_mfma_f32_16x16x32_bf16 v[36:39], v[144:147], v[168:171], v[36:39]
	v_mfma_f32_16x16x32_bf16 v[32:35], v[152:155], v[168:171], v[32:35]
	v_mfma_f32_16x16x32_bf16 v[20:23], v[144:147], v[188:191], v[20:23]
	v_mfma_f32_16x16x32_bf16 v[16:19], v[152:155], v[188:191], v[16:19]
	v_mfma_f32_16x16x32_bf16 v[4:7], v[144:147], v[196:199], v[4:7]
	v_mfma_f32_16x16x32_bf16 v[0:3], v[152:155], v[196:199], v[0:3]
	v_mfma_f32_16x16x32_bf16 v[52:55], v[148:151], v[164:167], v[52:55]
	v_mfma_f32_16x16x32_bf16 v[48:51], v[156:159], v[164:167], v[48:51]
	v_mfma_f32_16x16x32_bf16 v[36:39], v[148:151], v[172:175], v[36:39]
	v_mfma_f32_16x16x32_bf16 v[32:35], v[156:159], v[172:175], v[32:35]
	v_mfma_f32_16x16x32_bf16 v[20:23], v[148:151], v[192:195], v[20:23]
	v_mfma_f32_16x16x32_bf16 v[16:19], v[156:159], v[192:195], v[16:19]
	v_mfma_f32_16x16x32_bf16 v[4:7], v[148:151], v[206:209], v[4:7]
	v_mfma_f32_16x16x32_bf16 v[0:3], v[156:159], v[206:209], v[0:3]
	s_setprio 0
	s_barrier
	s_add_i32 s49, s49, 2
	s_add_u32 s45, s45, 0x100
	s_addc_u32 s46, s46, 0
	s_add_u32 s18, s18, 0x100
	s_addc_u32 s19, s19, 0
	s_add_u32 s47, s47, 0x100
	s_addc_u32 s48, s48, 0
	s_cmp_gt_u32 s49, 29
	s_cbranch_scc0 .LBB0_811
	s_and_b64 vcc, exec, s[84:85]
	s_cbranch_vccz .LBB0_814
	s_barrier

; #define LAS __attribute__((address_space(3)))
; __global__ void __launch_bounds__(NWAVES * 64, 2) fwd(Args args) {
;     extern __shared__ __attribute__((aligned(16))) unsigned char lds_raw[];
;     LAS unsigned char* lds = (LAS unsigned char*)lds_raw;
;     const int wid = __builtin_amdgcn_readfirstlane((int)threadIdx.x >> 6);
	.amdhsa_kernel _Z3fwd4Args
		.amdhsa_group_segment_fixed_size 0
		.amdhsa_private_segment_fixed_size 0
		.amdhsa_kernarg_size 408
		.amdhsa_user_sgpr_count 2
		.amdhsa_user_sgpr_dispatch_ptr 0
		.amdhsa_user_sgpr_queue_ptr 0
		.amdhsa_user_sgpr_kernarg_segment_ptr 1
		.amdhsa_user_sgpr_dispatch_id 0
		.amdhsa_user_sgpr_kernarg_preload_length 0
		.amdhsa_user_sgpr_kernarg_preload_offset 0
		.amdhsa_user_sgpr_private_segment_size 0
		.amdhsa_uses_dynamic_stack 0
		.amdhsa_enable_private_segment 0
		.amdhsa_system_sgpr_workgroup_id_x 1
		.amdhsa_system_sgpr_workgroup_id_y 0
		.amdhsa_system_sgpr_workgroup_id_z 0
		.amdhsa_system_sgpr_workgroup_info 0
		.amdhsa_system_vgpr_workitem_id 0
		.amdhsa_next_free_vgpr 256
		.amdhsa_next_free_sgpr 102
		.amdhsa_accum_offset 256
		.amdhsa_reserve_vcc 1
		.amdhsa_float_round_mode_32 0
		.amdhsa_float_round_mode_16_64 0
		.amdhsa_float_denorm_mode_32 3
		.amdhsa_float_denorm_mode_16_64 3
		.amdhsa_dx10_clamp 1
		.amdhsa_ieee_mode 1
		.amdhsa_fp16_overflow 0
		.amdhsa_tg_split 0
		.amdhsa_exception_fp_ieee_invalid_op 0
		.amdhsa_exception_fp_denorm_src 0
		.amdhsa_exception_fp_ieee_div_zero 0
		.amdhsa_exception_fp_ieee_overflow 0
		.amdhsa_exception_fp_ieee_underflow 0
		.amdhsa_exception_fp_ieee_inexact 0
		.amdhsa_exception_int_div_zero 0
	.end_amdhsa_kernel

; __global__ void __launch_bounds__(NWAVES * 64, 2) fwd(Args args) {
amdhsa.kernels:
  - .agpr_count:     0
    .args:
      - .offset:         0
        .size:           152
        .value_kind:     by_value
      - .offset:         152
        .size:           4
        .value_kind:     hidden_block_count_x
      - .offset:         156
        .size:           4
        .value_kind:     hidden_block_count_y
      - .offset:         160
        .size:           4
        .value_kind:     hidden_block_count_z
      - .offset:         164
        .size:           2
        .value_kind:     hidden_group_size_x
      - .offset:         166
        .size:           2
        .value_kind:     hidden_group_size_y
      - .offset:         168
        .size:           2
        .value_kind:     hidden_group_size_z
      - .offset:         170
        .size:           2
        .value_kind:     hidden_remainder_x
      - .offset:         172
        .size:           2
        .value_kind:     hidden_remainder_y
      - .offset:         174
        .size:           2
        .value_kind:     hidden_remainder_z
      - .offset:         192
        .size:           8
        .value_kind:     hidden_global_offset_x
      - .offset:         200
        .size:           8
        .value_kind:     hidden_global_offset_y
      - .offset:         208
        .size:           8
        .value_kind:     hidden_global_offset_z
      - .offset:         216
        .size:           2
        .value_kind:     hidden_grid_dims
      - .offset:         272
        .size:           4
        .value_kind:     hidden_dynamic_lds_size
    .group_segment_fixed_size: 0
    .kernarg_segment_align: 8
    .kernarg_segment_size: 408
    .language:       OpenCL C
    .language_version:
      - 2
      - 0
    .max_flat_workgroup_size: 512
    .name:           _Z3fwd4Args
    .private_segment_fixed_size: 0
    .sgpr_count:     108
    .sgpr_spill_count: 73
    .symbol:         _Z3fwd4Args.kd
    .uniform_work_group_size: 1
    .uses_dynamic_stack: false
    .vgpr_count:     256
    .vgpr_spill_count: 0
    .wavefront_size: 64
